# hyena FFT head/tail: radix-4 pass pairs fused into radix-16 passes (half the LDS round trips), packed-f32 butterflies
# speedup vs baseline: 1.0903x; 1.0246x over previous
; HD float2 cmul(float2 a, float2 b){ return make_float2(a.x*b.x - a.y*b.y, a.x*b.y + a.y*b.x); }
; HD float2 cmulc(float2 a, float2 b){ return make_float2(a.x*b.x + a.y*b.y, a.y*b.x - a.x*b.y); }
; template<bool INV, bool NOTW>
; HD void bf4c(float2* Z, int i0, int i1, int i2, int i3, float2 w1, float2 w2, float2 w3){
;   float2 a0=Z[i0], a1=Z[i1], a2=Z[i2], a3=Z[i3];
;   if (INV && !NOTW){ a1=cmulc(a1,w1); a2=cmulc(a2,w2); a3=cmulc(a3,w3); }
;   float2 s02=make_float2(a0.x+a2.x,a0.y+a2.y), d02=make_float2(a0.x-a2.x,a0.y-a2.y);
;   float2 s13=make_float2(a1.x+a3.x,a1.y+a3.y), d13=make_float2(a1.x-a3.x,a1.y-a3.y);
;   float2 y0=make_float2(s02.x+s13.x,s02.y+s13.y), y2=make_float2(s02.x-s13.x,s02.y-s13.y);
;   float2 ym=make_float2(d02.x+d13.y,d02.y-d13.x);
;   float2 yp=make_float2(d02.x-d13.y,d02.y+d13.x);
;   float2 y1, y3;
;   if (INV){ y1=yp; y3=ym; } else if (NOTW){ y1=ym; y3=yp; } else { y1=cmul(ym,w1); y2=cmul(y2,w2); y3=cmul(yp,w3); }
;   Z[i0]=y0; Z[i1]=y1; Z[i2]=y2; Z[i3]=y3;
; template<bool INV, int LQ, bool BARRIER=true>
; HD void fft_pass(float2* Z, const float2* twA, const float2* twB, int tid){
;     ...
;     _Pragma("unroll") for (int e=0;e<2;++e){ int j=tid+512*e; int k=j*tws;
;       float2 w1=cmul(twA[k>>6],twB[k&63]), w2=cmul(w1,w1), w3=cmul(w2,w1);
;       _Pragma("unroll") for (int ip=0;ip<4;++ip){ int base=ip*4096+j; bf4c<INV,false>(Z,base,base+q,base+2*q,base+3*q,w1,w2,w3); } }
;   } else {
;     int j=tid&(q-1); int base0=((tid>>LQ)<<(LQ+2))+j;
;     float2 w1=make_float2(1.f,0.f), w2=w1, w3=w1;
;     if (LQ>0){ int k=j*tws; w1=cmul(twA[k>>6],twB[k&63]); w2=cmul(w1,w1); w3=cmul(w2,w1); }
;     _Pragma("unroll") for (int i=0;i<8;++i){ int base=base0+i*2048; bf4c<INV,(LQ==0)>(Z,base,base+q,base+2*q,base+3*q,w1,w2,w3); }
.Lmy_pf_skipb:
	v_mov_b32_e32 v222, 0x3f6c835e
	v_mov_b32_e32 v223, 0x3ec3ef15
	v_mov_b32_e32 v224, 0x3f3504f3
	v_mov_b32_e32 v225, 0x3f3504f3
	v_and_b32_e32 v8, 255, v154
	v_lshrrev_b32_e32 v9, 4, v8
	v_lshlrev_b32_e32 v9, 3, v9
	v_add_u32_e32 v9, 0x20800, v9
	v_and_b32_e32 v10, 15, v8
	v_lshlrev_b32_e32 v10, 5, v10
	v_add_u32_e32 v10, 0x20a00, v10
	ds_read_b64 v[0:1], v9
	ds_read_b64 v[2:3], v10
	s_waitcnt lgkmcnt(0)
	v_pk_mul_f32 v[250:251], v[0:1], v[2:3] op_sel:[1,1] op_sel_hi:[1,0]
	v_pk_fma_f32 v[80:81], v[0:1], v[2:3], v[250:251] op_sel:[0,0,0] op_sel_hi:[0,1,1] neg_lo:[0,0,1]
	v_pk_mul_f32 v[250:251], v[80:81], v[80:81] op_sel:[1,1] op_sel_hi:[1,0]
	v_pk_fma_f32 v[82:83], v[80:81], v[80:81], v[250:251] op_sel:[0,0,0] op_sel_hi:[0,1,1] neg_lo:[0,0,1]
	v_pk_mul_f32 v[250:251], v[82:83], v[80:81] op_sel:[1,1] op_sel_hi:[1,0]
	v_pk_fma_f32 v[84:85], v[82:83], v[80:81], v[250:251] op_sel:[0,0,0] op_sel_hi:[0,1,1] neg_lo:[0,0,1]
	v_lshrrev_b32_e32 v9, 2, v8
	v_lshlrev_b32_e32 v9, 3, v9
	v_add_u32_e32 v9, 0x20800, v9
	v_and_b32_e32 v10, 3, v8
	v_lshlrev_b32_e32 v10, 7, v10
	v_add_u32_e32 v10, 0x20a00, v10
	ds_read_b64 v[0:1], v9
	ds_read_b64 v[2:3], v10
	s_waitcnt lgkmcnt(0)
	v_pk_mul_f32 v[250:251], v[0:1], v[2:3] op_sel:[1,1] op_sel_hi:[1,0]
	v_pk_fma_f32 v[236:237], v[0:1], v[2:3], v[250:251] op_sel:[0,0,0] op_sel_hi:[0,1,1] neg_lo:[0,0,1]
	v_pk_mul_f32 v[250:251], v[236:237], v[236:237] op_sel:[1,1] op_sel_hi:[1,0]
	v_pk_fma_f32 v[238:239], v[236:237], v[236:237], v[250:251] op_sel:[0,0,0] op_sel_hi:[0,1,1] neg_lo:[0,0,1]
	v_pk_mul_f32 v[250:251], v[238:239], v[236:237] op_sel:[1,1] op_sel_hi:[1,0]
	v_pk_fma_f32 v[240:241], v[238:239], v[236:237], v[250:251] op_sel:[0,0,0] op_sel_hi:[0,1,1] neg_lo:[0,0,1]
	v_lshrrev_b32_e32 v226, 8, v154
	v_lshlrev_b32_e32 v226, 12, v226
	v_and_b32_e32 v227, 255, v154
	v_add_u32_e32 v226, v226, v227
	v_lshlrev_b32_e32 v226, 3, v226
	v_add_u32_e32 v227, 0x10000, v226
	ds_read_b64 v[0:1], v226 offset:0
	ds_read_b64 v[8:9], v226 offset:8192
	ds_read_b64 v[16:17], v226 offset:16384
	ds_read_b64 v[24:25], v226 offset:24576
	ds_read_b64 v[2:3], v226 offset:2048
	ds_read_b64 v[10:11], v226 offset:10240
	ds_read_b64 v[18:19], v226 offset:18432
	ds_read_b64 v[26:27], v226 offset:26624
	ds_read_b64 v[4:5], v226 offset:4096
	ds_read_b64 v[12:13], v226 offset:12288
	ds_read_b64 v[20:21], v226 offset:20480
	ds_read_b64 v[28:29], v226 offset:28672
	ds_read_b64 v[6:7], v226 offset:6144
	ds_read_b64 v[14:15], v226 offset:14336
	ds_read_b64 v[22:23], v226 offset:22528
	ds_read_b64 v[30:31], v226 offset:30720
	s_waitcnt lgkmcnt(12)
	v_pk_add_f32 v[242:243], v[0:1], v[16:17]
	v_pk_add_f32 v[244:245], v[0:1], v[16:17] neg_lo:[0,1] neg_hi:[0,1]
	v_pk_add_f32 v[246:247], v[8:9], v[24:25]
	v_pk_add_f32 v[248:249], v[8:9], v[24:25] neg_lo:[0,1] neg_hi:[0,1]
	v_pk_add_f32 v[0:1], v[242:243], v[246:247]
	v_pk_add_f32 v[8:9], v[244:245], v[248:249] op_sel:[0,1] op_sel_hi:[1,0] neg_hi:[0,1]
	v_pk_mul_f32 v[250:251], v[8:9], v[80:81] op_sel:[1,1] op_sel_hi:[1,0]
	v_pk_fma_f32 v[8:9], v[8:9], v[80:81], v[250:251] op_sel:[0,0,0] op_sel_hi:[0,1,1] neg_lo:[0,0,1]
	v_pk_add_f32 v[16:17], v[242:243], v[246:247] neg_lo:[0,1] neg_hi:[0,1]
	v_pk_mul_f32 v[250:251], v[16:17], v[82:83] op_sel:[1,1] op_sel_hi:[1,0]
	v_pk_fma_f32 v[16:17], v[16:17], v[82:83], v[250:251] op_sel:[0,0,0] op_sel_hi:[0,1,1] neg_lo:[0,0,1]
	v_pk_add_f32 v[24:25], v[244:245], v[248:249] op_sel:[0,1] op_sel_hi:[1,0] neg_lo:[0,1]
	v_pk_mul_f32 v[250:251], v[24:25], v[84:85] op_sel:[1,1] op_sel_hi:[1,0]
	v_pk_fma_f32 v[24:25], v[24:25], v[84:85], v[250:251] op_sel:[0,0,0] op_sel_hi:[0,1,1] neg_lo:[0,0,1]
	s_waitcnt lgkmcnt(8)
	v_pk_add_f32 v[242:243], v[2:3], v[18:19]
	v_pk_add_f32 v[244:245], v[2:3], v[18:19] neg_lo:[0,1] neg_hi:[0,1]
	v_pk_add_f32 v[246:247], v[10:11], v[26:27]
	v_pk_add_f32 v[248:249], v[10:11], v[26:27] neg_lo:[0,1] neg_hi:[0,1]
	v_pk_add_f32 v[2:3], v[242:243], v[246:247]
	v_pk_add_f32 v[10:11], v[244:245], v[248:249] op_sel:[0,1] op_sel_hi:[1,0] neg_hi:[0,1]
	v_pk_mul_f32 v[250:251], v[10:11], v[80:81] op_sel:[1,1] op_sel_hi:[1,0]
	v_pk_fma_f32 v[10:11], v[10:11], v[80:81], v[250:251] op_sel:[0,0,0] op_sel_hi:[0,1,1] neg_lo:[0,0,1]
	v_pk_mul_f32 v[250:251], v[10:11], v[222:223] op_sel:[1,1] op_sel_hi:[1,0] neg_lo:[0,1] neg_hi:[0,0]
	v_pk_fma_f32 v[10:11], v[10:11], v[222:223], v[250:251] op_sel:[0,0,0] op_sel_hi:[0,1,1] neg_lo:[0,0,1] neg_hi:[0,1,0]
	v_pk_add_f32 v[18:19], v[242:243], v[246:247] neg_lo:[0,1] neg_hi:[0,1]
	v_pk_mul_f32 v[250:251], v[18:19], v[82:83] op_sel:[1,1] op_sel_hi:[1,0]
	v_pk_fma_f32 v[18:19], v[18:19], v[82:83], v[250:251] op_sel:[0,0,0] op_sel_hi:[0,1,1] neg_lo:[0,0,1]
	v_pk_mul_f32 v[250:251], v[18:19], v[224:225] op_sel:[1,1] op_sel_hi:[1,0] neg_lo:[0,1] neg_hi:[0,0]
	v_pk_fma_f32 v[18:19], v[18:19], v[224:225], v[250:251] op_sel:[0,0,0] op_sel_hi:[0,1,1] neg_lo:[0,0,1] neg_hi:[0,1,0]
	v_pk_add_f32 v[26:27], v[244:245], v[248:249] op_sel:[0,1] op_sel_hi:[1,0] neg_lo:[0,1]
	v_pk_mul_f32 v[250:251], v[26:27], v[84:85] op_sel:[1,1] op_sel_hi:[1,0]
	v_pk_fma_f32 v[26:27], v[26:27], v[84:85], v[250:251] op_sel:[0,0,0] op_sel_hi:[0,1,1] neg_lo:[0,0,1]
	v_pk_mul_f32 v[250:251], v[26:27], v[222:223] op_sel:[1,0] op_sel_hi:[1,1] neg_lo:[0,1] neg_hi:[0,0]
	v_pk_fma_f32 v[26:27], v[26:27], v[222:223], v[250:251] op_sel:[0,1,0] op_sel_hi:[0,0,1] neg_lo:[0,0,1] neg_hi:[0,1,0]
	s_waitcnt lgkmcnt(4)
; HD float2 cmul(float2 a, float2 b){ return make_float2(a.x*b.x - a.y*b.y, a.x*b.y + a.y*b.x); }
; HD float2 cmulc(float2 a, float2 b){ return make_float2(a.x*b.x + a.y*b.y, a.y*b.x - a.x*b.y); }
; template<bool INV, bool NOTW>
; HD void bf4c(float2* Z, int i0, int i1, int i2, int i3, float2 w1, float2 w2, float2 w3){
;   float2 a0=Z[i0], a1=Z[i1], a2=Z[i2], a3=Z[i3];
;   if (INV && !NOTW){ a1=cmulc(a1,w1); a2=cmulc(a2,w2); a3=cmulc(a3,w3); }
;   float2 s02=make_float2(a0.x+a2.x,a0.y+a2.y), d02=make_float2(a0.x-a2.x,a0.y-a2.y);
;   float2 s13=make_float2(a1.x+a3.x,a1.y+a3.y), d13=make_float2(a1.x-a3.x,a1.y-a3.y);
;   float2 y0=make_float2(s02.x+s13.x,s02.y+s13.y), y2=make_float2(s02.x-s13.x,s02.y-s13.y);
;   float2 ym=make_float2(d02.x+d13.y,d02.y-d13.x);
;   float2 yp=make_float2(d02.x-d13.y,d02.y+d13.x);
;   float2 y1, y3;
;   if (INV){ y1=yp; y3=ym; } else if (NOTW){ y1=ym; y3=yp; } else { y1=cmul(ym,w1); y2=cmul(y2,w2); y3=cmul(yp,w3); }
;   Z[i0]=y0; Z[i1]=y1; Z[i2]=y2; Z[i3]=y3;
; template<bool INV, int LQ, bool BARRIER=true>
; HD void fft_pass(float2* Z, const float2* twA, const float2* twB, int tid){
;     ...
;     _Pragma("unroll") for (int e=0;e<2;++e){ int j=tid+512*e; int k=j*tws;
;       float2 w1=cmul(twA[k>>6],twB[k&63]), w2=cmul(w1,w1), w3=cmul(w2,w1);
;       _Pragma("unroll") for (int ip=0;ip<4;++ip){ int base=ip*4096+j; bf4c<INV,false>(Z,base,base+q,base+2*q,base+3*q,w1,w2,w3); } }
;   } else {
;     int j=tid&(q-1); int base0=((tid>>LQ)<<(LQ+2))+j;
;     float2 w1=make_float2(1.f,0.f), w2=w1, w3=w1;
;     if (LQ>0){ int k=j*tws; w1=cmul(twA[k>>6],twB[k&63]); w2=cmul(w1,w1); w3=cmul(w2,w1); }
;     _Pragma("unroll") for (int i=0;i<8;++i){ int base=base0+i*2048; bf4c<INV,(LQ==0)>(Z,base,base+q,base+2*q,base+3*q,w1,w2,w3); }
	v_pk_add_f32 v[242:243], v[4:5], v[20:21]
	v_pk_add_f32 v[244:245], v[4:5], v[20:21] neg_lo:[0,1] neg_hi:[0,1]
	v_pk_add_f32 v[246:247], v[12:13], v[28:29]
	v_pk_add_f32 v[248:249], v[12:13], v[28:29] neg_lo:[0,1] neg_hi:[0,1]
	v_pk_add_f32 v[4:5], v[242:243], v[246:247]
	v_pk_add_f32 v[12:13], v[244:245], v[248:249] op_sel:[0,1] op_sel_hi:[1,0] neg_hi:[0,1]
	v_pk_mul_f32 v[250:251], v[12:13], v[80:81] op_sel:[1,1] op_sel_hi:[1,0]
	v_pk_fma_f32 v[12:13], v[12:13], v[80:81], v[250:251] op_sel:[0,0,0] op_sel_hi:[0,1,1] neg_lo:[0,0,1]
	v_pk_mul_f32 v[250:251], v[12:13], v[224:225] op_sel:[1,1] op_sel_hi:[1,0] neg_lo:[0,1] neg_hi:[0,0]
	v_pk_fma_f32 v[12:13], v[12:13], v[224:225], v[250:251] op_sel:[0,0,0] op_sel_hi:[0,1,1] neg_lo:[0,0,1] neg_hi:[0,1,0]
	v_pk_add_f32 v[20:21], v[242:243], v[246:247] neg_lo:[0,1] neg_hi:[0,1]
	v_pk_mul_f32 v[250:251], v[20:21], v[82:83] op_sel:[1,1] op_sel_hi:[1,0]
	v_pk_fma_f32 v[20:21], v[20:21], v[82:83], v[250:251] op_sel:[0,0,0] op_sel_hi:[0,1,1] neg_lo:[0,0,1]
	v_pk_add_f32 v[20:21], v[20:21], 0 op_sel:[1,0] op_sel_hi:[0,0] neg_hi:[1,0]
	v_pk_add_f32 v[28:29], v[244:245], v[248:249] op_sel:[0,1] op_sel_hi:[1,0] neg_lo:[0,1]
	v_pk_mul_f32 v[250:251], v[28:29], v[84:85] op_sel:[1,1] op_sel_hi:[1,0]
	v_pk_fma_f32 v[28:29], v[28:29], v[84:85], v[250:251] op_sel:[0,0,0] op_sel_hi:[0,1,1] neg_lo:[0,0,1]
	v_pk_mul_f32 v[250:251], v[28:29], v[224:225] op_sel:[1,1] op_sel_hi:[1,0] neg_lo:[0,1] neg_hi:[0,1]
	v_pk_fma_f32 v[28:29], v[28:29], v[224:225], v[250:251] op_sel:[0,0,0] op_sel_hi:[0,1,1] neg_lo:[0,1,1] neg_hi:[0,1,0]
	s_waitcnt lgkmcnt(0)
	v_pk_add_f32 v[242:243], v[6:7], v[22:23]
	v_pk_add_f32 v[244:245], v[6:7], v[22:23] neg_lo:[0,1] neg_hi:[0,1]
	v_pk_add_f32 v[246:247], v[14:15], v[30:31]
	v_pk_add_f32 v[248:249], v[14:15], v[30:31] neg_lo:[0,1] neg_hi:[0,1]
	v_pk_add_f32 v[6:7], v[242:243], v[246:247]
	v_pk_add_f32 v[14:15], v[244:245], v[248:249] op_sel:[0,1] op_sel_hi:[1,0] neg_hi:[0,1]
	v_pk_mul_f32 v[250:251], v[14:15], v[80:81] op_sel:[1,1] op_sel_hi:[1,0]
	v_pk_fma_f32 v[14:15], v[14:15], v[80:81], v[250:251] op_sel:[0,0,0] op_sel_hi:[0,1,1] neg_lo:[0,0,1]
	v_pk_mul_f32 v[250:251], v[14:15], v[222:223] op_sel:[1,0] op_sel_hi:[1,1] neg_lo:[0,1] neg_hi:[0,0]
	v_pk_fma_f32 v[14:15], v[14:15], v[222:223], v[250:251] op_sel:[0,1,0] op_sel_hi:[0,0,1] neg_lo:[0,0,1] neg_hi:[0,1,0]
	v_pk_add_f32 v[22:23], v[242:243], v[246:247] neg_lo:[0,1] neg_hi:[0,1]
	v_pk_mul_f32 v[250:251], v[22:23], v[82:83] op_sel:[1,1] op_sel_hi:[1,0]
	v_pk_fma_f32 v[22:23], v[22:23], v[82:83], v[250:251] op_sel:[0,0,0] op_sel_hi:[0,1,1] neg_lo:[0,0,1]
	v_pk_mul_f32 v[250:251], v[22:23], v[224:225] op_sel:[1,1] op_sel_hi:[1,0] neg_lo:[0,1] neg_hi:[0,1]
	v_pk_fma_f32 v[22:23], v[22:23], v[224:225], v[250:251] op_sel:[0,0,0] op_sel_hi:[0,1,1] neg_lo:[0,1,1] neg_hi:[0,1,0]
	v_pk_add_f32 v[30:31], v[244:245], v[248:249] op_sel:[0,1] op_sel_hi:[1,0] neg_lo:[0,1]
	v_pk_mul_f32 v[250:251], v[30:31], v[84:85] op_sel:[1,1] op_sel_hi:[1,0]
	v_pk_fma_f32 v[30:31], v[30:31], v[84:85], v[250:251] op_sel:[0,0,0] op_sel_hi:[0,1,1] neg_lo:[0,0,1]
	v_pk_mul_f32 v[250:251], v[30:31], v[222:223] op_sel:[1,1] op_sel_hi:[1,0] neg_lo:[0,0] neg_hi:[0,1]
	v_pk_fma_f32 v[30:31], v[30:31], v[222:223], v[250:251] op_sel:[0,0,0] op_sel_hi:[0,1,1] neg_lo:[0,1,1] neg_hi:[0,0,0]
	v_pk_add_f32 v[242:243], v[0:1], v[4:5]
	v_pk_add_f32 v[244:245], v[0:1], v[4:5] neg_lo:[0,1] neg_hi:[0,1]
	v_pk_add_f32 v[246:247], v[2:3], v[6:7]
	v_pk_add_f32 v[248:249], v[2:3], v[6:7] neg_lo:[0,1] neg_hi:[0,1]
	v_pk_add_f32 v[0:1], v[242:243], v[246:247]
	ds_write_b64 v226, v[0:1] offset:0
	v_pk_add_f32 v[2:3], v[244:245], v[248:249] op_sel:[0,1] op_sel_hi:[1,0] neg_hi:[0,1]
	v_pk_mul_f32 v[250:251], v[2:3], v[236:237] op_sel:[1,1] op_sel_hi:[1,0]
	v_pk_fma_f32 v[2:3], v[2:3], v[236:237], v[250:251] op_sel:[0,0,0] op_sel_hi:[0,1,1] neg_lo:[0,0,1]
	ds_write_b64 v226, v[2:3] offset:2048
	v_pk_add_f32 v[4:5], v[242:243], v[246:247] neg_lo:[0,1] neg_hi:[0,1]
	v_pk_mul_f32 v[250:251], v[4:5], v[238:239] op_sel:[1,1] op_sel_hi:[1,0]
	v_pk_fma_f32 v[4:5], v[4:5], v[238:239], v[250:251] op_sel:[0,0,0] op_sel_hi:[0,1,1] neg_lo:[0,0,1]
	ds_write_b64 v226, v[4:5] offset:4096
	v_pk_add_f32 v[6:7], v[244:245], v[248:249] op_sel:[0,1] op_sel_hi:[1,0] neg_lo:[0,1]
	v_pk_mul_f32 v[250:251], v[6:7], v[240:241] op_sel:[1,1] op_sel_hi:[1,0]
	v_pk_fma_f32 v[6:7], v[6:7], v[240:241], v[250:251] op_sel:[0,0,0] op_sel_hi:[0,1,1] neg_lo:[0,0,1]
	ds_write_b64 v226, v[6:7] offset:6144
	v_pk_add_f32 v[242:243], v[8:9], v[12:13]
	v_pk_add_f32 v[244:245], v[8:9], v[12:13] neg_lo:[0,1] neg_hi:[0,1]
	v_pk_add_f32 v[246:247], v[10:11], v[14:15]
	v_pk_add_f32 v[248:249], v[10:11], v[14:15] neg_lo:[0,1] neg_hi:[0,1]
	v_pk_add_f32 v[8:9], v[242:243], v[246:247]
	ds_write_b64 v226, v[8:9] offset:8192
	v_pk_add_f32 v[10:11], v[244:245], v[248:249] op_sel:[0,1] op_sel_hi:[1,0] neg_hi:[0,1]
	v_pk_mul_f32 v[250:251], v[10:11], v[236:237] op_sel:[1,1] op_sel_hi:[1,0]
	v_pk_fma_f32 v[10:11], v[10:11], v[236:237], v[250:251] op_sel:[0,0,0] op_sel_hi:[0,1,1] neg_lo:[0,0,1]
	ds_write_b64 v226, v[10:11] offset:10240
	v_pk_add_f32 v[12:13], v[242:243], v[246:247] neg_lo:[0,1] neg_hi:[0,1]
	v_pk_mul_f32 v[250:251], v[12:13], v[238:239] op_sel:[1,1] op_sel_hi:[1,0]
	v_pk_fma_f32 v[12:13], v[12:13], v[238:239], v[250:251] op_sel:[0,0,0] op_sel_hi:[0,1,1] neg_lo:[0,0,1]
	ds_write_b64 v226, v[12:13] offset:12288
	v_pk_add_f32 v[14:15], v[244:245], v[248:249] op_sel:[0,1] op_sel_hi:[1,0] neg_lo:[0,1]
	v_pk_mul_f32 v[250:251], v[14:15], v[240:241] op_sel:[1,1] op_sel_hi:[1,0]
; HD float2 cmul(float2 a, float2 b){ return make_float2(a.x*b.x - a.y*b.y, a.x*b.y + a.y*b.x); }
; HD float2 cmulc(float2 a, float2 b){ return make_float2(a.x*b.x + a.y*b.y, a.y*b.x - a.x*b.y); }
; template<bool INV, bool NOTW>
; HD void bf4c(float2* Z, int i0, int i1, int i2, int i3, float2 w1, float2 w2, float2 w3){
;   float2 a0=Z[i0], a1=Z[i1], a2=Z[i2], a3=Z[i3];
;   if (INV && !NOTW){ a1=cmulc(a1,w1); a2=cmulc(a2,w2); a3=cmulc(a3,w3); }
;   float2 s02=make_float2(a0.x+a2.x,a0.y+a2.y), d02=make_float2(a0.x-a2.x,a0.y-a2.y);
;   float2 s13=make_float2(a1.x+a3.x,a1.y+a3.y), d13=make_float2(a1.x-a3.x,a1.y-a3.y);
;   float2 y0=make_float2(s02.x+s13.x,s02.y+s13.y), y2=make_float2(s02.x-s13.x,s02.y-s13.y);
;   float2 ym=make_float2(d02.x+d13.y,d02.y-d13.x);
;   float2 yp=make_float2(d02.x-d13.y,d02.y+d13.x);
;   float2 y1, y3;
;   if (INV){ y1=yp; y3=ym; } else if (NOTW){ y1=ym; y3=yp; } else { y1=cmul(ym,w1); y2=cmul(y2,w2); y3=cmul(yp,w3); }
;   Z[i0]=y0; Z[i1]=y1; Z[i2]=y2; Z[i3]=y3;
; template<bool INV, int LQ, bool BARRIER=true>
; HD void fft_pass(float2* Z, const float2* twA, const float2* twB, int tid){
;     ...
;     _Pragma("unroll") for (int e=0;e<2;++e){ int j=tid+512*e; int k=j*tws;
;       float2 w1=cmul(twA[k>>6],twB[k&63]), w2=cmul(w1,w1), w3=cmul(w2,w1);
;       _Pragma("unroll") for (int ip=0;ip<4;++ip){ int base=ip*4096+j; bf4c<INV,false>(Z,base,base+q,base+2*q,base+3*q,w1,w2,w3); } }
;   } else {
;     int j=tid&(q-1); int base0=((tid>>LQ)<<(LQ+2))+j;
;     float2 w1=make_float2(1.f,0.f), w2=w1, w3=w1;
;     if (LQ>0){ int k=j*tws; w1=cmul(twA[k>>6],twB[k&63]); w2=cmul(w1,w1); w3=cmul(w2,w1); }
;     _Pragma("unroll") for (int i=0;i<8;++i){ int base=base0+i*2048; bf4c<INV,(LQ==0)>(Z,base,base+q,base+2*q,base+3*q,w1,w2,w3); }
	v_pk_fma_f32 v[14:15], v[14:15], v[240:241], v[250:251] op_sel:[0,0,0] op_sel_hi:[0,1,1] neg_lo:[0,0,1]
	ds_write_b64 v226, v[14:15] offset:14336
	v_pk_add_f32 v[242:243], v[16:17], v[20:21]
	v_pk_add_f32 v[244:245], v[16:17], v[20:21] neg_lo:[0,1] neg_hi:[0,1]
	v_pk_add_f32 v[246:247], v[18:19], v[22:23]
	v_pk_add_f32 v[248:249], v[18:19], v[22:23] neg_lo:[0,1] neg_hi:[0,1]
	v_pk_add_f32 v[16:17], v[242:243], v[246:247]
	ds_write_b64 v226, v[16:17] offset:16384
	v_pk_add_f32 v[18:19], v[244:245], v[248:249] op_sel:[0,1] op_sel_hi:[1,0] neg_hi:[0,1]
	v_pk_mul_f32 v[250:251], v[18:19], v[236:237] op_sel:[1,1] op_sel_hi:[1,0]
	v_pk_fma_f32 v[18:19], v[18:19], v[236:237], v[250:251] op_sel:[0,0,0] op_sel_hi:[0,1,1] neg_lo:[0,0,1]
	ds_write_b64 v226, v[18:19] offset:18432
	v_pk_add_f32 v[20:21], v[242:243], v[246:247] neg_lo:[0,1] neg_hi:[0,1]
	v_pk_mul_f32 v[250:251], v[20:21], v[238:239] op_sel:[1,1] op_sel_hi:[1,0]
	v_pk_fma_f32 v[20:21], v[20:21], v[238:239], v[250:251] op_sel:[0,0,0] op_sel_hi:[0,1,1] neg_lo:[0,0,1]
	ds_write_b64 v226, v[20:21] offset:20480
	v_pk_add_f32 v[22:23], v[244:245], v[248:249] op_sel:[0,1] op_sel_hi:[1,0] neg_lo:[0,1]
	v_pk_mul_f32 v[250:251], v[22:23], v[240:241] op_sel:[1,1] op_sel_hi:[1,0]
	v_pk_fma_f32 v[22:23], v[22:23], v[240:241], v[250:251] op_sel:[0,0,0] op_sel_hi:[0,1,1] neg_lo:[0,0,1]
	ds_write_b64 v226, v[22:23] offset:22528
	v_pk_add_f32 v[242:243], v[24:25], v[28:29]
	v_pk_add_f32 v[244:245], v[24:25], v[28:29] neg_lo:[0,1] neg_hi:[0,1]
	v_pk_add_f32 v[246:247], v[26:27], v[30:31]
	v_pk_add_f32 v[248:249], v[26:27], v[30:31] neg_lo:[0,1] neg_hi:[0,1]
	v_pk_add_f32 v[24:25], v[242:243], v[246:247]
	ds_write_b64 v226, v[24:25] offset:24576
	v_pk_add_f32 v[26:27], v[244:245], v[248:249] op_sel:[0,1] op_sel_hi:[1,0] neg_hi:[0,1]
	v_pk_mul_f32 v[250:251], v[26:27], v[236:237] op_sel:[1,1] op_sel_hi:[1,0]
	v_pk_fma_f32 v[26:27], v[26:27], v[236:237], v[250:251] op_sel:[0,0,0] op_sel_hi:[0,1,1] neg_lo:[0,0,1]
	ds_write_b64 v226, v[26:27] offset:26624
	v_pk_add_f32 v[28:29], v[242:243], v[246:247] neg_lo:[0,1] neg_hi:[0,1]
	v_pk_mul_f32 v[250:251], v[28:29], v[238:239] op_sel:[1,1] op_sel_hi:[1,0]
	v_pk_fma_f32 v[28:29], v[28:29], v[238:239], v[250:251] op_sel:[0,0,0] op_sel_hi:[0,1,1] neg_lo:[0,0,1]
	ds_write_b64 v226, v[28:29] offset:28672
	v_pk_add_f32 v[30:31], v[244:245], v[248:249] op_sel:[0,1] op_sel_hi:[1,0] neg_lo:[0,1]
	v_pk_mul_f32 v[250:251], v[30:31], v[240:241] op_sel:[1,1] op_sel_hi:[1,0]
	v_pk_fma_f32 v[30:31], v[30:31], v[240:241], v[250:251] op_sel:[0,0,0] op_sel_hi:[0,1,1] neg_lo:[0,0,1]
	ds_write_b64 v226, v[30:31] offset:30720
	ds_read_b64 v[0:1], v227 offset:0
	ds_read_b64 v[8:9], v227 offset:8192
	ds_read_b64 v[16:17], v227 offset:16384
	ds_read_b64 v[24:25], v227 offset:24576
	ds_read_b64 v[2:3], v227 offset:2048
	ds_read_b64 v[10:11], v227 offset:10240
	ds_read_b64 v[18:19], v227 offset:18432
	ds_read_b64 v[26:27], v227 offset:26624
	ds_read_b64 v[4:5], v227 offset:4096
	ds_read_b64 v[12:13], v227 offset:12288
	ds_read_b64 v[20:21], v227 offset:20480
	ds_read_b64 v[28:29], v227 offset:28672
	ds_read_b64 v[6:7], v227 offset:6144
	ds_read_b64 v[14:15], v227 offset:14336
	ds_read_b64 v[22:23], v227 offset:22528
	ds_read_b64 v[30:31], v227 offset:30720
	s_waitcnt lgkmcnt(12)
	v_pk_add_f32 v[242:243], v[0:1], v[16:17]
	v_pk_add_f32 v[244:245], v[0:1], v[16:17] neg_lo:[0,1] neg_hi:[0,1]
	v_pk_add_f32 v[246:247], v[8:9], v[24:25]
	v_pk_add_f32 v[248:249], v[8:9], v[24:25] neg_lo:[0,1] neg_hi:[0,1]
	v_pk_add_f32 v[0:1], v[242:243], v[246:247]
	v_pk_add_f32 v[8:9], v[244:245], v[248:249] op_sel:[0,1] op_sel_hi:[1,0] neg_hi:[0,1]
	v_pk_mul_f32 v[250:251], v[8:9], v[80:81] op_sel:[1,1] op_sel_hi:[1,0]
	v_pk_fma_f32 v[8:9], v[8:9], v[80:81], v[250:251] op_sel:[0,0,0] op_sel_hi:[0,1,1] neg_lo:[0,0,1]
	v_pk_add_f32 v[16:17], v[242:243], v[246:247] neg_lo:[0,1] neg_hi:[0,1]
	v_pk_mul_f32 v[250:251], v[16:17], v[82:83] op_sel:[1,1] op_sel_hi:[1,0]
	v_pk_fma_f32 v[16:17], v[16:17], v[82:83], v[250:251] op_sel:[0,0,0] op_sel_hi:[0,1,1] neg_lo:[0,0,1]
	v_pk_add_f32 v[24:25], v[244:245], v[248:249] op_sel:[0,1] op_sel_hi:[1,0] neg_lo:[0,1]
	v_pk_mul_f32 v[250:251], v[24:25], v[84:85] op_sel:[1,1] op_sel_hi:[1,0]
	v_pk_fma_f32 v[24:25], v[24:25], v[84:85], v[250:251] op_sel:[0,0,0] op_sel_hi:[0,1,1] neg_lo:[0,0,1]
	s_waitcnt lgkmcnt(8)
	v_pk_add_f32 v[242:243], v[2:3], v[18:19]
	v_pk_add_f32 v[244:245], v[2:3], v[18:19] neg_lo:[0,1] neg_hi:[0,1]
	v_pk_add_f32 v[246:247], v[10:11], v[26:27]
	v_pk_add_f32 v[248:249], v[10:11], v[26:27] neg_lo:[0,1] neg_hi:[0,1]
	v_pk_add_f32 v[2:3], v[242:243], v[246:247]
	v_pk_add_f32 v[10:11], v[244:245], v[248:249] op_sel:[0,1] op_sel_hi:[1,0] neg_hi:[0,1]
	v_pk_mul_f32 v[250:251], v[10:11], v[80:81] op_sel:[1,1] op_sel_hi:[1,0]
	v_pk_fma_f32 v[10:11], v[10:11], v[80:81], v[250:251] op_sel:[0,0,0] op_sel_hi:[0,1,1] neg_lo:[0,0,1]
	v_pk_mul_f32 v[250:251], v[10:11], v[222:223] op_sel:[1,1] op_sel_hi:[1,0] neg_lo:[0,1] neg_hi:[0,0]
	v_pk_fma_f32 v[10:11], v[10:11], v[222:223], v[250:251] op_sel:[0,0,0] op_sel_hi:[0,1,1] neg_lo:[0,0,1] neg_hi:[0,1,0]
	v_pk_add_f32 v[18:19], v[242:243], v[246:247] neg_lo:[0,1] neg_hi:[0,1]
	v_pk_mul_f32 v[250:251], v[18:19], v[82:83] op_sel:[1,1] op_sel_hi:[1,0]
	v_pk_fma_f32 v[18:19], v[18:19], v[82:83], v[250:251] op_sel:[0,0,0] op_sel_hi:[0,1,1] neg_lo:[0,0,1]
	v_pk_mul_f32 v[250:251], v[18:19], v[224:225] op_sel:[1,1] op_sel_hi:[1,0] neg_lo:[0,1] neg_hi:[0,0]
	v_pk_fma_f32 v[18:19], v[18:19], v[224:225], v[250:251] op_sel:[0,0,0] op_sel_hi:[0,1,1] neg_lo:[0,0,1] neg_hi:[0,1,0]
	v_pk_add_f32 v[26:27], v[244:245], v[248:249] op_sel:[0,1] op_sel_hi:[1,0] neg_lo:[0,1]
	v_pk_mul_f32 v[250:251], v[26:27], v[84:85] op_sel:[1,1] op_sel_hi:[1,0]
	v_pk_fma_f32 v[26:27], v[26:27], v[84:85], v[250:251] op_sel:[0,0,0] op_sel_hi:[0,1,1] neg_lo:[0,0,1]
	v_pk_mul_f32 v[250:251], v[26:27], v[222:223] op_sel:[1,0] op_sel_hi:[1,1] neg_lo:[0,1] neg_hi:[0,0]
	v_pk_fma_f32 v[26:27], v[26:27], v[222:223], v[250:251] op_sel:[0,1,0] op_sel_hi:[0,0,1] neg_lo:[0,0,1] neg_hi:[0,1,0]
	s_waitcnt lgkmcnt(4)
; HD float2 cmul(float2 a, float2 b){ return make_float2(a.x*b.x - a.y*b.y, a.x*b.y + a.y*b.x); }
; HD float2 cmulc(float2 a, float2 b){ return make_float2(a.x*b.x + a.y*b.y, a.y*b.x - a.x*b.y); }
; template<bool INV, bool NOTW>
; HD void bf4c(float2* Z, int i0, int i1, int i2, int i3, float2 w1, float2 w2, float2 w3){
;   float2 a0=Z[i0], a1=Z[i1], a2=Z[i2], a3=Z[i3];
;   if (INV && !NOTW){ a1=cmulc(a1,w1); a2=cmulc(a2,w2); a3=cmulc(a3,w3); }
;   float2 s02=make_float2(a0.x+a2.x,a0.y+a2.y), d02=make_float2(a0.x-a2.x,a0.y-a2.y);
;   float2 s13=make_float2(a1.x+a3.x,a1.y+a3.y), d13=make_float2(a1.x-a3.x,a1.y-a3.y);
;   float2 y0=make_float2(s02.x+s13.x,s02.y+s13.y), y2=make_float2(s02.x-s13.x,s02.y-s13.y);
;   float2 ym=make_float2(d02.x+d13.y,d02.y-d13.x);
;   float2 yp=make_float2(d02.x-d13.y,d02.y+d13.x);
;   float2 y1, y3;
;   if (INV){ y1=yp; y3=ym; } else if (NOTW){ y1=ym; y3=yp; } else { y1=cmul(ym,w1); y2=cmul(y2,w2); y3=cmul(yp,w3); }
;   Z[i0]=y0; Z[i1]=y1; Z[i2]=y2; Z[i3]=y3;
; template<bool INV, int LQ, bool BARRIER=true>
; HD void fft_pass(float2* Z, const float2* twA, const float2* twB, int tid){
;     ...
;     _Pragma("unroll") for (int e=0;e<2;++e){ int j=tid+512*e; int k=j*tws;
;       float2 w1=cmul(twA[k>>6],twB[k&63]), w2=cmul(w1,w1), w3=cmul(w2,w1);
;       _Pragma("unroll") for (int ip=0;ip<4;++ip){ int base=ip*4096+j; bf4c<INV,false>(Z,base,base+q,base+2*q,base+3*q,w1,w2,w3); } }
;   } else {
;     int j=tid&(q-1); int base0=((tid>>LQ)<<(LQ+2))+j;
;     float2 w1=make_float2(1.f,0.f), w2=w1, w3=w1;
;     if (LQ>0){ int k=j*tws; w1=cmul(twA[k>>6],twB[k&63]); w2=cmul(w1,w1); w3=cmul(w2,w1); }
;     _Pragma("unroll") for (int i=0;i<8;++i){ int base=base0+i*2048; bf4c<INV,(LQ==0)>(Z,base,base+q,base+2*q,base+3*q,w1,w2,w3); }
	v_pk_add_f32 v[242:243], v[4:5], v[20:21]
	v_pk_add_f32 v[244:245], v[4:5], v[20:21] neg_lo:[0,1] neg_hi:[0,1]
	v_pk_add_f32 v[246:247], v[12:13], v[28:29]
	v_pk_add_f32 v[248:249], v[12:13], v[28:29] neg_lo:[0,1] neg_hi:[0,1]
	v_pk_add_f32 v[4:5], v[242:243], v[246:247]
	v_pk_add_f32 v[12:13], v[244:245], v[248:249] op_sel:[0,1] op_sel_hi:[1,0] neg_hi:[0,1]
	v_pk_mul_f32 v[250:251], v[12:13], v[80:81] op_sel:[1,1] op_sel_hi:[1,0]
	v_pk_fma_f32 v[12:13], v[12:13], v[80:81], v[250:251] op_sel:[0,0,0] op_sel_hi:[0,1,1] neg_lo:[0,0,1]
	v_pk_mul_f32 v[250:251], v[12:13], v[224:225] op_sel:[1,1] op_sel_hi:[1,0] neg_lo:[0,1] neg_hi:[0,0]
	v_pk_fma_f32 v[12:13], v[12:13], v[224:225], v[250:251] op_sel:[0,0,0] op_sel_hi:[0,1,1] neg_lo:[0,0,1] neg_hi:[0,1,0]
	v_pk_add_f32 v[20:21], v[242:243], v[246:247] neg_lo:[0,1] neg_hi:[0,1]
	v_pk_mul_f32 v[250:251], v[20:21], v[82:83] op_sel:[1,1] op_sel_hi:[1,0]
	v_pk_fma_f32 v[20:21], v[20:21], v[82:83], v[250:251] op_sel:[0,0,0] op_sel_hi:[0,1,1] neg_lo:[0,0,1]
	v_pk_add_f32 v[20:21], v[20:21], 0 op_sel:[1,0] op_sel_hi:[0,0] neg_hi:[1,0]
	v_pk_add_f32 v[28:29], v[244:245], v[248:249] op_sel:[0,1] op_sel_hi:[1,0] neg_lo:[0,1]
	v_pk_mul_f32 v[250:251], v[28:29], v[84:85] op_sel:[1,1] op_sel_hi:[1,0]
	v_pk_fma_f32 v[28:29], v[28:29], v[84:85], v[250:251] op_sel:[0,0,0] op_sel_hi:[0,1,1] neg_lo:[0,0,1]
	v_pk_mul_f32 v[250:251], v[28:29], v[224:225] op_sel:[1,1] op_sel_hi:[1,0] neg_lo:[0,1] neg_hi:[0,1]
	v_pk_fma_f32 v[28:29], v[28:29], v[224:225], v[250:251] op_sel:[0,0,0] op_sel_hi:[0,1,1] neg_lo:[0,1,1] neg_hi:[0,1,0]
	s_waitcnt lgkmcnt(0)
	v_pk_add_f32 v[242:243], v[6:7], v[22:23]
	v_pk_add_f32 v[244:245], v[6:7], v[22:23] neg_lo:[0,1] neg_hi:[0,1]
	v_pk_add_f32 v[246:247], v[14:15], v[30:31]
	v_pk_add_f32 v[248:249], v[14:15], v[30:31] neg_lo:[0,1] neg_hi:[0,1]
	v_pk_add_f32 v[6:7], v[242:243], v[246:247]
	v_pk_add_f32 v[14:15], v[244:245], v[248:249] op_sel:[0,1] op_sel_hi:[1,0] neg_hi:[0,1]
	v_pk_mul_f32 v[250:251], v[14:15], v[80:81] op_sel:[1,1] op_sel_hi:[1,0]
	v_pk_fma_f32 v[14:15], v[14:15], v[80:81], v[250:251] op_sel:[0,0,0] op_sel_hi:[0,1,1] neg_lo:[0,0,1]
	v_pk_mul_f32 v[250:251], v[14:15], v[222:223] op_sel:[1,0] op_sel_hi:[1,1] neg_lo:[0,1] neg_hi:[0,0]
	v_pk_fma_f32 v[14:15], v[14:15], v[222:223], v[250:251] op_sel:[0,1,0] op_sel_hi:[0,0,1] neg_lo:[0,0,1] neg_hi:[0,1,0]
	v_pk_add_f32 v[22:23], v[242:243], v[246:247] neg_lo:[0,1] neg_hi:[0,1]
	v_pk_mul_f32 v[250:251], v[22:23], v[82:83] op_sel:[1,1] op_sel_hi:[1,0]
	v_pk_fma_f32 v[22:23], v[22:23], v[82:83], v[250:251] op_sel:[0,0,0] op_sel_hi:[0,1,1] neg_lo:[0,0,1]
	v_pk_mul_f32 v[250:251], v[22:23], v[224:225] op_sel:[1,1] op_sel_hi:[1,0] neg_lo:[0,1] neg_hi:[0,1]
	v_pk_fma_f32 v[22:23], v[22:23], v[224:225], v[250:251] op_sel:[0,0,0] op_sel_hi:[0,1,1] neg_lo:[0,1,1] neg_hi:[0,1,0]
	v_pk_add_f32 v[30:31], v[244:245], v[248:249] op_sel:[0,1] op_sel_hi:[1,0] neg_lo:[0,1]
	v_pk_mul_f32 v[250:251], v[30:31], v[84:85] op_sel:[1,1] op_sel_hi:[1,0]
	v_pk_fma_f32 v[30:31], v[30:31], v[84:85], v[250:251] op_sel:[0,0,0] op_sel_hi:[0,1,1] neg_lo:[0,0,1]
	v_pk_mul_f32 v[250:251], v[30:31], v[222:223] op_sel:[1,1] op_sel_hi:[1,0] neg_lo:[0,0] neg_hi:[0,1]
	v_pk_fma_f32 v[30:31], v[30:31], v[222:223], v[250:251] op_sel:[0,0,0] op_sel_hi:[0,1,1] neg_lo:[0,1,1] neg_hi:[0,0,0]
	v_pk_add_f32 v[242:243], v[0:1], v[4:5]
	v_pk_add_f32 v[244:245], v[0:1], v[4:5] neg_lo:[0,1] neg_hi:[0,1]
	v_pk_add_f32 v[246:247], v[2:3], v[6:7]
	v_pk_add_f32 v[248:249], v[2:3], v[6:7] neg_lo:[0,1] neg_hi:[0,1]
	v_pk_add_f32 v[0:1], v[242:243], v[246:247]
	ds_write_b64 v227, v[0:1] offset:0
	v_pk_add_f32 v[2:3], v[244:245], v[248:249] op_sel:[0,1] op_sel_hi:[1,0] neg_hi:[0,1]
	v_pk_mul_f32 v[250:251], v[2:3], v[236:237] op_sel:[1,1] op_sel_hi:[1,0]
	v_pk_fma_f32 v[2:3], v[2:3], v[236:237], v[250:251] op_sel:[0,0,0] op_sel_hi:[0,1,1] neg_lo:[0,0,1]
	ds_write_b64 v227, v[2:3] offset:2048
	v_pk_add_f32 v[4:5], v[242:243], v[246:247] neg_lo:[0,1] neg_hi:[0,1]
	v_pk_mul_f32 v[250:251], v[4:5], v[238:239] op_sel:[1,1] op_sel_hi:[1,0]
	v_pk_fma_f32 v[4:5], v[4:5], v[238:239], v[250:251] op_sel:[0,0,0] op_sel_hi:[0,1,1] neg_lo:[0,0,1]
	ds_write_b64 v227, v[4:5] offset:4096
	v_pk_add_f32 v[6:7], v[244:245], v[248:249] op_sel:[0,1] op_sel_hi:[1,0] neg_lo:[0,1]
	v_pk_mul_f32 v[250:251], v[6:7], v[240:241] op_sel:[1,1] op_sel_hi:[1,0]
	v_pk_fma_f32 v[6:7], v[6:7], v[240:241], v[250:251] op_sel:[0,0,0] op_sel_hi:[0,1,1] neg_lo:[0,0,1]
	ds_write_b64 v227, v[6:7] offset:6144
	v_pk_add_f32 v[242:243], v[8:9], v[12:13]
	v_pk_add_f32 v[244:245], v[8:9], v[12:13] neg_lo:[0,1] neg_hi:[0,1]
	v_pk_add_f32 v[246:247], v[10:11], v[14:15]
	v_pk_add_f32 v[248:249], v[10:11], v[14:15] neg_lo:[0,1] neg_hi:[0,1]
	v_pk_add_f32 v[8:9], v[242:243], v[246:247]
	ds_write_b64 v227, v[8:9] offset:8192
	v_pk_add_f32 v[10:11], v[244:245], v[248:249] op_sel:[0,1] op_sel_hi:[1,0] neg_hi:[0,1]
	v_pk_mul_f32 v[250:251], v[10:11], v[236:237] op_sel:[1,1] op_sel_hi:[1,0]
	v_pk_fma_f32 v[10:11], v[10:11], v[236:237], v[250:251] op_sel:[0,0,0] op_sel_hi:[0,1,1] neg_lo:[0,0,1]
	ds_write_b64 v227, v[10:11] offset:10240
	v_pk_add_f32 v[12:13], v[242:243], v[246:247] neg_lo:[0,1] neg_hi:[0,1]
	v_pk_mul_f32 v[250:251], v[12:13], v[238:239] op_sel:[1,1] op_sel_hi:[1,0]
	v_pk_fma_f32 v[12:13], v[12:13], v[238:239], v[250:251] op_sel:[0,0,0] op_sel_hi:[0,1,1] neg_lo:[0,0,1]
	ds_write_b64 v227, v[12:13] offset:12288
	v_pk_add_f32 v[14:15], v[244:245], v[248:249] op_sel:[0,1] op_sel_hi:[1,0] neg_lo:[0,1]
	v_pk_mul_f32 v[250:251], v[14:15], v[240:241] op_sel:[1,1] op_sel_hi:[1,0]
; HD float2 cmul(float2 a, float2 b){ return make_float2(a.x*b.x - a.y*b.y, a.x*b.y + a.y*b.x); }
; template<bool INV, int LQ, bool BARRIER=true>
; HD void fft_pass(float2* Z, const float2* twA, const float2* twB, int tid){
;     ...
;     int j=tid&(q-1); int base0=((tid>>LQ)<<(LQ+2))+j;
;     float2 w1=make_float2(1.f,0.f), w2=w1, w3=w1;
;     if (LQ>0){ int k=j*tws; w1=cmul(twA[k>>6],twB[k&63]); w2=cmul(w1,w1); w3=cmul(w2,w1); }
;     _Pragma("unroll") for (int i=0;i<8;++i){ int base=base0+i*2048; bf4c<INV,(LQ==0)>(Z,base,base+q,base+2*q,base+3*q,w1,w2,w3); }
;   }
;   if (BARRIER) __syncthreads(); else asm volatile("s_waitcnt lgkmcnt(0)" ::: "memory");
; }
; __device__ __forceinline__ void fft_fwd_head(float2* Z, const float2* twA, const float2* twB, int tid){
;   fft_pass<false,10>(Z,twA,twB,tid); fft_pass<false,8>(Z,twA,twB,tid); fft_pass<false,6,false>(Z,twA,twB,tid);
;   fft_pass<false,4,false>(Z,twA,twB,tid); fft_pass<false,2,false>(Z,twA,twB,tid);
	v_pk_fma_f32 v[14:15], v[14:15], v[240:241], v[250:251] op_sel:[0,0,0] op_sel_hi:[0,1,1] neg_lo:[0,0,1]
	ds_write_b64 v227, v[14:15] offset:14336
	v_pk_add_f32 v[242:243], v[16:17], v[20:21]
	v_pk_add_f32 v[244:245], v[16:17], v[20:21] neg_lo:[0,1] neg_hi:[0,1]
	v_pk_add_f32 v[246:247], v[18:19], v[22:23]
	v_pk_add_f32 v[248:249], v[18:19], v[22:23] neg_lo:[0,1] neg_hi:[0,1]
	v_pk_add_f32 v[16:17], v[242:243], v[246:247]
	ds_write_b64 v227, v[16:17] offset:16384
	v_pk_add_f32 v[18:19], v[244:245], v[248:249] op_sel:[0,1] op_sel_hi:[1,0] neg_hi:[0,1]
	v_pk_mul_f32 v[250:251], v[18:19], v[236:237] op_sel:[1,1] op_sel_hi:[1,0]
	v_pk_fma_f32 v[18:19], v[18:19], v[236:237], v[250:251] op_sel:[0,0,0] op_sel_hi:[0,1,1] neg_lo:[0,0,1]
	ds_write_b64 v227, v[18:19] offset:18432
	v_pk_add_f32 v[20:21], v[242:243], v[246:247] neg_lo:[0,1] neg_hi:[0,1]
	v_pk_mul_f32 v[250:251], v[20:21], v[238:239] op_sel:[1,1] op_sel_hi:[1,0]
	v_pk_fma_f32 v[20:21], v[20:21], v[238:239], v[250:251] op_sel:[0,0,0] op_sel_hi:[0,1,1] neg_lo:[0,0,1]
	ds_write_b64 v227, v[20:21] offset:20480
	v_pk_add_f32 v[22:23], v[244:245], v[248:249] op_sel:[0,1] op_sel_hi:[1,0] neg_lo:[0,1]
	v_pk_mul_f32 v[250:251], v[22:23], v[240:241] op_sel:[1,1] op_sel_hi:[1,0]
	v_pk_fma_f32 v[22:23], v[22:23], v[240:241], v[250:251] op_sel:[0,0,0] op_sel_hi:[0,1,1] neg_lo:[0,0,1]
	ds_write_b64 v227, v[22:23] offset:22528
	v_pk_add_f32 v[242:243], v[24:25], v[28:29]
	v_pk_add_f32 v[244:245], v[24:25], v[28:29] neg_lo:[0,1] neg_hi:[0,1]
	v_pk_add_f32 v[246:247], v[26:27], v[30:31]
	v_pk_add_f32 v[248:249], v[26:27], v[30:31] neg_lo:[0,1] neg_hi:[0,1]
	v_pk_add_f32 v[24:25], v[242:243], v[246:247]
	ds_write_b64 v227, v[24:25] offset:24576
	v_pk_add_f32 v[26:27], v[244:245], v[248:249] op_sel:[0,1] op_sel_hi:[1,0] neg_hi:[0,1]
	v_pk_mul_f32 v[250:251], v[26:27], v[236:237] op_sel:[1,1] op_sel_hi:[1,0]
	v_pk_fma_f32 v[26:27], v[26:27], v[236:237], v[250:251] op_sel:[0,0,0] op_sel_hi:[0,1,1] neg_lo:[0,0,1]
	ds_write_b64 v227, v[26:27] offset:26624
	v_pk_add_f32 v[28:29], v[242:243], v[246:247] neg_lo:[0,1] neg_hi:[0,1]
	v_pk_mul_f32 v[250:251], v[28:29], v[238:239] op_sel:[1,1] op_sel_hi:[1,0]
	v_pk_fma_f32 v[28:29], v[28:29], v[238:239], v[250:251] op_sel:[0,0,0] op_sel_hi:[0,1,1] neg_lo:[0,0,1]
	ds_write_b64 v227, v[28:29] offset:28672
	v_pk_add_f32 v[30:31], v[244:245], v[248:249] op_sel:[0,1] op_sel_hi:[1,0] neg_lo:[0,1]
	v_pk_mul_f32 v[250:251], v[30:31], v[240:241] op_sel:[1,1] op_sel_hi:[1,0]
	v_pk_fma_f32 v[30:31], v[30:31], v[240:241], v[250:251] op_sel:[0,0,0] op_sel_hi:[0,1,1] neg_lo:[0,0,1]
	ds_write_b64 v227, v[30:31] offset:30720
	s_waitcnt lgkmcnt(0)
	s_barrier
	v_and_b32_e32 v8, 15, v154
	v_lshlrev_b32_e32 v9, 3, v8
	v_add_u32_e32 v9, 0x20800, v9
	v_mov_b32_e32 v10, 0x20a00
	ds_read_b64 v[0:1], v9
	ds_read_b64 v[2:3], v10
	s_waitcnt lgkmcnt(0)
	v_pk_mul_f32 v[250:251], v[0:1], v[2:3] op_sel:[1,1] op_sel_hi:[1,0]
	v_pk_fma_f32 v[80:81], v[0:1], v[2:3], v[250:251] op_sel:[0,0,0] op_sel_hi:[0,1,1] neg_lo:[0,0,1]
	v_pk_mul_f32 v[250:251], v[80:81], v[80:81] op_sel:[1,1] op_sel_hi:[1,0]
	v_pk_fma_f32 v[82:83], v[80:81], v[80:81], v[250:251] op_sel:[0,0,0] op_sel_hi:[0,1,1] neg_lo:[0,0,1]
	v_pk_mul_f32 v[250:251], v[82:83], v[80:81] op_sel:[1,1] op_sel_hi:[1,0]
	v_pk_fma_f32 v[84:85], v[82:83], v[80:81], v[250:251] op_sel:[0,0,0] op_sel_hi:[0,1,1] neg_lo:[0,0,1]
	v_lshlrev_b32_e32 v9, 5, v8
	v_add_u32_e32 v9, 0x20800, v9
	v_mov_b32_e32 v10, 0x20a00
	ds_read_b64 v[0:1], v9
	ds_read_b64 v[2:3], v10
	s_waitcnt lgkmcnt(0)
	v_pk_mul_f32 v[250:251], v[0:1], v[2:3] op_sel:[1,1] op_sel_hi:[1,0]
	v_pk_fma_f32 v[236:237], v[0:1], v[2:3], v[250:251] op_sel:[0,0,0] op_sel_hi:[0,1,1] neg_lo:[0,0,1]
	v_pk_mul_f32 v[250:251], v[236:237], v[236:237] op_sel:[1,1] op_sel_hi:[1,0]
	v_pk_fma_f32 v[238:239], v[236:237], v[236:237], v[250:251] op_sel:[0,0,0] op_sel_hi:[0,1,1] neg_lo:[0,0,1]
	v_pk_mul_f32 v[250:251], v[238:239], v[236:237] op_sel:[1,1] op_sel_hi:[1,0]
	v_pk_fma_f32 v[240:241], v[238:239], v[236:237], v[250:251] op_sel:[0,0,0] op_sel_hi:[0,1,1] neg_lo:[0,0,1]
	v_lshrrev_b32_e32 v226, 6, v154
	v_bfe_u32 v227, v154, 4, 2
	v_lshl_add_u32 v226, v227, 3, v226
	v_lshlrev_b32_e32 v226, 8, v226
	v_and_b32_e32 v227, 15, v154
	v_add_u32_e32 v226, v226, v227
	v_lshlrev_b32_e32 v226, 3, v226
	v_add_u32_e32 v227, 0x10000, v226
	ds_read_b64 v[0:1], v226 offset:0
	ds_read_b64 v[8:9], v226 offset:512
	ds_read_b64 v[16:17], v226 offset:1024
	ds_read_b64 v[24:25], v226 offset:1536
	ds_read_b64 v[2:3], v226 offset:128
	ds_read_b64 v[10:11], v226 offset:640
	ds_read_b64 v[18:19], v226 offset:1152
	ds_read_b64 v[26:27], v226 offset:1664
	ds_read_b64 v[4:5], v226 offset:256
	ds_read_b64 v[12:13], v226 offset:768
	ds_read_b64 v[20:21], v226 offset:1280
	ds_read_b64 v[28:29], v226 offset:1792
	ds_read_b64 v[6:7], v226 offset:384
	ds_read_b64 v[14:15], v226 offset:896
	ds_read_b64 v[22:23], v226 offset:1408
	ds_read_b64 v[30:31], v226 offset:1920
	s_waitcnt lgkmcnt(12)
	v_pk_add_f32 v[242:243], v[0:1], v[16:17]
	v_pk_add_f32 v[244:245], v[0:1], v[16:17] neg_lo:[0,1] neg_hi:[0,1]
	v_pk_add_f32 v[246:247], v[8:9], v[24:25]
	v_pk_add_f32 v[248:249], v[8:9], v[24:25] neg_lo:[0,1] neg_hi:[0,1]
	v_pk_add_f32 v[0:1], v[242:243], v[246:247]
	v_pk_add_f32 v[8:9], v[244:245], v[248:249] op_sel:[0,1] op_sel_hi:[1,0] neg_hi:[0,1]
	v_pk_mul_f32 v[250:251], v[8:9], v[80:81] op_sel:[1,1] op_sel_hi:[1,0]
	v_pk_fma_f32 v[8:9], v[8:9], v[80:81], v[250:251] op_sel:[0,0,0] op_sel_hi:[0,1,1] neg_lo:[0,0,1]
	v_pk_add_f32 v[16:17], v[242:243], v[246:247] neg_lo:[0,1] neg_hi:[0,1]
	v_pk_mul_f32 v[250:251], v[16:17], v[82:83] op_sel:[1,1] op_sel_hi:[1,0]
	v_pk_fma_f32 v[16:17], v[16:17], v[82:83], v[250:251] op_sel:[0,0,0] op_sel_hi:[0,1,1] neg_lo:[0,0,1]
	v_pk_add_f32 v[24:25], v[244:245], v[248:249] op_sel:[0,1] op_sel_hi:[1,0] neg_lo:[0,1]
	v_pk_mul_f32 v[250:251], v[24:25], v[84:85] op_sel:[1,1] op_sel_hi:[1,0]
	v_pk_fma_f32 v[24:25], v[24:25], v[84:85], v[250:251] op_sel:[0,0,0] op_sel_hi:[0,1,1] neg_lo:[0,0,1]
	s_waitcnt lgkmcnt(8)
; HD float2 cmul(float2 a, float2 b){ return make_float2(a.x*b.x - a.y*b.y, a.x*b.y + a.y*b.x); }
; HD float2 cmulc(float2 a, float2 b){ return make_float2(a.x*b.x + a.y*b.y, a.y*b.x - a.x*b.y); }
; template<bool INV, bool NOTW>
; HD void bf4c(float2* Z, int i0, int i1, int i2, int i3, float2 w1, float2 w2, float2 w3){
;   float2 a0=Z[i0], a1=Z[i1], a2=Z[i2], a3=Z[i3];
;   if (INV && !NOTW){ a1=cmulc(a1,w1); a2=cmulc(a2,w2); a3=cmulc(a3,w3); }
;   float2 s02=make_float2(a0.x+a2.x,a0.y+a2.y), d02=make_float2(a0.x-a2.x,a0.y-a2.y);
;   float2 s13=make_float2(a1.x+a3.x,a1.y+a3.y), d13=make_float2(a1.x-a3.x,a1.y-a3.y);
;   float2 y0=make_float2(s02.x+s13.x,s02.y+s13.y), y2=make_float2(s02.x-s13.x,s02.y-s13.y);
;   float2 ym=make_float2(d02.x+d13.y,d02.y-d13.x);
;   float2 yp=make_float2(d02.x-d13.y,d02.y+d13.x);
;   float2 y1, y3;
;   if (INV){ y1=yp; y3=ym; } else if (NOTW){ y1=ym; y3=yp; } else { y1=cmul(ym,w1); y2=cmul(y2,w2); y3=cmul(yp,w3); }
;   Z[i0]=y0; Z[i1]=y1; Z[i2]=y2; Z[i3]=y3;
; template<bool INV, int LQ, bool BARRIER=true>
; HD void fft_pass(float2* Z, const float2* twA, const float2* twB, int tid){
;     ...
;     int j=tid&(q-1); int base0=((tid>>LQ)<<(LQ+2))+j;
;     float2 w1=make_float2(1.f,0.f), w2=w1, w3=w1;
;     if (LQ>0){ int k=j*tws; w1=cmul(twA[k>>6],twB[k&63]); w2=cmul(w1,w1); w3=cmul(w2,w1); }
;     _Pragma("unroll") for (int i=0;i<8;++i){ int base=base0+i*2048; bf4c<INV,(LQ==0)>(Z,base,base+q,base+2*q,base+3*q,w1,w2,w3); }
;   }
;   if (BARRIER) __syncthreads(); else asm volatile("s_waitcnt lgkmcnt(0)" ::: "memory");
; }
; __device__ __forceinline__ void fft_fwd_head(float2* Z, const float2* twA, const float2* twB, int tid){
;   fft_pass<false,10>(Z,twA,twB,tid); fft_pass<false,8>(Z,twA,twB,tid); fft_pass<false,6,false>(Z,twA,twB,tid);
;   fft_pass<false,4,false>(Z,twA,twB,tid); fft_pass<false,2,false>(Z,twA,twB,tid);
	v_pk_add_f32 v[242:243], v[2:3], v[18:19]
	v_pk_add_f32 v[244:245], v[2:3], v[18:19] neg_lo:[0,1] neg_hi:[0,1]
	v_pk_add_f32 v[246:247], v[10:11], v[26:27]
	v_pk_add_f32 v[248:249], v[10:11], v[26:27] neg_lo:[0,1] neg_hi:[0,1]
	v_pk_add_f32 v[2:3], v[242:243], v[246:247]
	v_pk_add_f32 v[10:11], v[244:245], v[248:249] op_sel:[0,1] op_sel_hi:[1,0] neg_hi:[0,1]
	v_pk_mul_f32 v[250:251], v[10:11], v[80:81] op_sel:[1,1] op_sel_hi:[1,0]
	v_pk_fma_f32 v[10:11], v[10:11], v[80:81], v[250:251] op_sel:[0,0,0] op_sel_hi:[0,1,1] neg_lo:[0,0,1]
	v_pk_mul_f32 v[250:251], v[10:11], v[222:223] op_sel:[1,1] op_sel_hi:[1,0] neg_lo:[0,1] neg_hi:[0,0]
	v_pk_fma_f32 v[10:11], v[10:11], v[222:223], v[250:251] op_sel:[0,0,0] op_sel_hi:[0,1,1] neg_lo:[0,0,1] neg_hi:[0,1,0]
	v_pk_add_f32 v[18:19], v[242:243], v[246:247] neg_lo:[0,1] neg_hi:[0,1]
	v_pk_mul_f32 v[250:251], v[18:19], v[82:83] op_sel:[1,1] op_sel_hi:[1,0]
	v_pk_fma_f32 v[18:19], v[18:19], v[82:83], v[250:251] op_sel:[0,0,0] op_sel_hi:[0,1,1] neg_lo:[0,0,1]
	v_pk_mul_f32 v[250:251], v[18:19], v[224:225] op_sel:[1,1] op_sel_hi:[1,0] neg_lo:[0,1] neg_hi:[0,0]
	v_pk_fma_f32 v[18:19], v[18:19], v[224:225], v[250:251] op_sel:[0,0,0] op_sel_hi:[0,1,1] neg_lo:[0,0,1] neg_hi:[0,1,0]
	v_pk_add_f32 v[26:27], v[244:245], v[248:249] op_sel:[0,1] op_sel_hi:[1,0] neg_lo:[0,1]
	v_pk_mul_f32 v[250:251], v[26:27], v[84:85] op_sel:[1,1] op_sel_hi:[1,0]
	v_pk_fma_f32 v[26:27], v[26:27], v[84:85], v[250:251] op_sel:[0,0,0] op_sel_hi:[0,1,1] neg_lo:[0,0,1]
	v_pk_mul_f32 v[250:251], v[26:27], v[222:223] op_sel:[1,0] op_sel_hi:[1,1] neg_lo:[0,1] neg_hi:[0,0]
	v_pk_fma_f32 v[26:27], v[26:27], v[222:223], v[250:251] op_sel:[0,1,0] op_sel_hi:[0,0,1] neg_lo:[0,0,1] neg_hi:[0,1,0]
	s_waitcnt lgkmcnt(4)
	v_pk_add_f32 v[242:243], v[4:5], v[20:21]
	v_pk_add_f32 v[244:245], v[4:5], v[20:21] neg_lo:[0,1] neg_hi:[0,1]
	v_pk_add_f32 v[246:247], v[12:13], v[28:29]
	v_pk_add_f32 v[248:249], v[12:13], v[28:29] neg_lo:[0,1] neg_hi:[0,1]
	v_pk_add_f32 v[4:5], v[242:243], v[246:247]
	v_pk_add_f32 v[12:13], v[244:245], v[248:249] op_sel:[0,1] op_sel_hi:[1,0] neg_hi:[0,1]
	v_pk_mul_f32 v[250:251], v[12:13], v[80:81] op_sel:[1,1] op_sel_hi:[1,0]
	v_pk_fma_f32 v[12:13], v[12:13], v[80:81], v[250:251] op_sel:[0,0,0] op_sel_hi:[0,1,1] neg_lo:[0,0,1]
	v_pk_mul_f32 v[250:251], v[12:13], v[224:225] op_sel:[1,1] op_sel_hi:[1,0] neg_lo:[0,1] neg_hi:[0,0]
	v_pk_fma_f32 v[12:13], v[12:13], v[224:225], v[250:251] op_sel:[0,0,0] op_sel_hi:[0,1,1] neg_lo:[0,0,1] neg_hi:[0,1,0]
	v_pk_add_f32 v[20:21], v[242:243], v[246:247] neg_lo:[0,1] neg_hi:[0,1]
	v_pk_mul_f32 v[250:251], v[20:21], v[82:83] op_sel:[1,1] op_sel_hi:[1,0]
	v_pk_fma_f32 v[20:21], v[20:21], v[82:83], v[250:251] op_sel:[0,0,0] op_sel_hi:[0,1,1] neg_lo:[0,0,1]
	v_pk_add_f32 v[20:21], v[20:21], 0 op_sel:[1,0] op_sel_hi:[0,0] neg_hi:[1,0]
	v_pk_add_f32 v[28:29], v[244:245], v[248:249] op_sel:[0,1] op_sel_hi:[1,0] neg_lo:[0,1]
	v_pk_mul_f32 v[250:251], v[28:29], v[84:85] op_sel:[1,1] op_sel_hi:[1,0]
	v_pk_fma_f32 v[28:29], v[28:29], v[84:85], v[250:251] op_sel:[0,0,0] op_sel_hi:[0,1,1] neg_lo:[0,0,1]
	v_pk_mul_f32 v[250:251], v[28:29], v[224:225] op_sel:[1,1] op_sel_hi:[1,0] neg_lo:[0,1] neg_hi:[0,1]
	v_pk_fma_f32 v[28:29], v[28:29], v[224:225], v[250:251] op_sel:[0,0,0] op_sel_hi:[0,1,1] neg_lo:[0,1,1] neg_hi:[0,1,0]
	s_waitcnt lgkmcnt(0)
	v_pk_add_f32 v[242:243], v[6:7], v[22:23]
	v_pk_add_f32 v[244:245], v[6:7], v[22:23] neg_lo:[0,1] neg_hi:[0,1]
	v_pk_add_f32 v[246:247], v[14:15], v[30:31]
	v_pk_add_f32 v[248:249], v[14:15], v[30:31] neg_lo:[0,1] neg_hi:[0,1]
	v_pk_add_f32 v[6:7], v[242:243], v[246:247]
	v_pk_add_f32 v[14:15], v[244:245], v[248:249] op_sel:[0,1] op_sel_hi:[1,0] neg_hi:[0,1]
	v_pk_mul_f32 v[250:251], v[14:15], v[80:81] op_sel:[1,1] op_sel_hi:[1,0]
	v_pk_fma_f32 v[14:15], v[14:15], v[80:81], v[250:251] op_sel:[0,0,0] op_sel_hi:[0,1,1] neg_lo:[0,0,1]
	v_pk_mul_f32 v[250:251], v[14:15], v[222:223] op_sel:[1,0] op_sel_hi:[1,1] neg_lo:[0,1] neg_hi:[0,0]
	v_pk_fma_f32 v[14:15], v[14:15], v[222:223], v[250:251] op_sel:[0,1,0] op_sel_hi:[0,0,1] neg_lo:[0,0,1] neg_hi:[0,1,0]
	v_pk_add_f32 v[22:23], v[242:243], v[246:247] neg_lo:[0,1] neg_hi:[0,1]
	v_pk_mul_f32 v[250:251], v[22:23], v[82:83] op_sel:[1,1] op_sel_hi:[1,0]
	v_pk_fma_f32 v[22:23], v[22:23], v[82:83], v[250:251] op_sel:[0,0,0] op_sel_hi:[0,1,1] neg_lo:[0,0,1]
	v_pk_mul_f32 v[250:251], v[22:23], v[224:225] op_sel:[1,1] op_sel_hi:[1,0] neg_lo:[0,1] neg_hi:[0,1]
	v_pk_fma_f32 v[22:23], v[22:23], v[224:225], v[250:251] op_sel:[0,0,0] op_sel_hi:[0,1,1] neg_lo:[0,1,1] neg_hi:[0,1,0]
	v_pk_add_f32 v[30:31], v[244:245], v[248:249] op_sel:[0,1] op_sel_hi:[1,0] neg_lo:[0,1]
	v_pk_mul_f32 v[250:251], v[30:31], v[84:85] op_sel:[1,1] op_sel_hi:[1,0]
	v_pk_fma_f32 v[30:31], v[30:31], v[84:85], v[250:251] op_sel:[0,0,0] op_sel_hi:[0,1,1] neg_lo:[0,0,1]
	v_pk_mul_f32 v[250:251], v[30:31], v[222:223] op_sel:[1,1] op_sel_hi:[1,0] neg_lo:[0,0] neg_hi:[0,1]
	v_pk_fma_f32 v[30:31], v[30:31], v[222:223], v[250:251] op_sel:[0,0,0] op_sel_hi:[0,1,1] neg_lo:[0,1,1] neg_hi:[0,0,0]
	v_pk_add_f32 v[242:243], v[0:1], v[4:5]
	v_pk_add_f32 v[244:245], v[0:1], v[4:5] neg_lo:[0,1] neg_hi:[0,1]
	v_pk_add_f32 v[246:247], v[2:3], v[6:7]
	v_pk_add_f32 v[248:249], v[2:3], v[6:7] neg_lo:[0,1] neg_hi:[0,1]
	v_pk_add_f32 v[0:1], v[242:243], v[246:247]
	ds_write_b64 v226, v[0:1] offset:0
	v_pk_add_f32 v[2:3], v[244:245], v[248:249] op_sel:[0,1] op_sel_hi:[1,0] neg_hi:[0,1]
	v_pk_mul_f32 v[250:251], v[2:3], v[236:237] op_sel:[1,1] op_sel_hi:[1,0]
	v_pk_fma_f32 v[2:3], v[2:3], v[236:237], v[250:251] op_sel:[0,0,0] op_sel_hi:[0,1,1] neg_lo:[0,0,1]
; HD float2 cmul(float2 a, float2 b){ return make_float2(a.x*b.x - a.y*b.y, a.x*b.y + a.y*b.x); }
; HD float2 cmulc(float2 a, float2 b){ return make_float2(a.x*b.x + a.y*b.y, a.y*b.x - a.x*b.y); }
; template<bool INV, bool NOTW>
; HD void bf4c(float2* Z, int i0, int i1, int i2, int i3, float2 w1, float2 w2, float2 w3){
;   float2 a0=Z[i0], a1=Z[i1], a2=Z[i2], a3=Z[i3];
;   if (INV && !NOTW){ a1=cmulc(a1,w1); a2=cmulc(a2,w2); a3=cmulc(a3,w3); }
;   float2 s02=make_float2(a0.x+a2.x,a0.y+a2.y), d02=make_float2(a0.x-a2.x,a0.y-a2.y);
;   float2 s13=make_float2(a1.x+a3.x,a1.y+a3.y), d13=make_float2(a1.x-a3.x,a1.y-a3.y);
;   float2 y0=make_float2(s02.x+s13.x,s02.y+s13.y), y2=make_float2(s02.x-s13.x,s02.y-s13.y);
;   float2 ym=make_float2(d02.x+d13.y,d02.y-d13.x);
;   float2 yp=make_float2(d02.x-d13.y,d02.y+d13.x);
;   float2 y1, y3;
;   if (INV){ y1=yp; y3=ym; } else if (NOTW){ y1=ym; y3=yp; } else { y1=cmul(ym,w1); y2=cmul(y2,w2); y3=cmul(yp,w3); }
;   Z[i0]=y0; Z[i1]=y1; Z[i2]=y2; Z[i3]=y3;
; template<bool INV, int LQ, bool BARRIER=true>
; HD void fft_pass(float2* Z, const float2* twA, const float2* twB, int tid){
;     ...
;     int j=tid&(q-1); int base0=((tid>>LQ)<<(LQ+2))+j;
;     float2 w1=make_float2(1.f,0.f), w2=w1, w3=w1;
;     if (LQ>0){ int k=j*tws; w1=cmul(twA[k>>6],twB[k&63]); w2=cmul(w1,w1); w3=cmul(w2,w1); }
;     _Pragma("unroll") for (int i=0;i<8;++i){ int base=base0+i*2048; bf4c<INV,(LQ==0)>(Z,base,base+q,base+2*q,base+3*q,w1,w2,w3); }
;   }
;   if (BARRIER) __syncthreads(); else asm volatile("s_waitcnt lgkmcnt(0)" ::: "memory");
; }
; __device__ __forceinline__ void fft_fwd_head(float2* Z, const float2* twA, const float2* twB, int tid){
;   fft_pass<false,10>(Z,twA,twB,tid); fft_pass<false,8>(Z,twA,twB,tid); fft_pass<false,6,false>(Z,twA,twB,tid);
;   fft_pass<false,4,false>(Z,twA,twB,tid); fft_pass<false,2,false>(Z,twA,twB,tid);
	ds_write_b64 v226, v[2:3] offset:128
	v_pk_add_f32 v[4:5], v[242:243], v[246:247] neg_lo:[0,1] neg_hi:[0,1]
	v_pk_mul_f32 v[250:251], v[4:5], v[238:239] op_sel:[1,1] op_sel_hi:[1,0]
	v_pk_fma_f32 v[4:5], v[4:5], v[238:239], v[250:251] op_sel:[0,0,0] op_sel_hi:[0,1,1] neg_lo:[0,0,1]
	ds_write_b64 v226, v[4:5] offset:256
	v_pk_add_f32 v[6:7], v[244:245], v[248:249] op_sel:[0,1] op_sel_hi:[1,0] neg_lo:[0,1]
	v_pk_mul_f32 v[250:251], v[6:7], v[240:241] op_sel:[1,1] op_sel_hi:[1,0]
	v_pk_fma_f32 v[6:7], v[6:7], v[240:241], v[250:251] op_sel:[0,0,0] op_sel_hi:[0,1,1] neg_lo:[0,0,1]
	ds_write_b64 v226, v[6:7] offset:384
	v_pk_add_f32 v[242:243], v[8:9], v[12:13]
	v_pk_add_f32 v[244:245], v[8:9], v[12:13] neg_lo:[0,1] neg_hi:[0,1]
	v_pk_add_f32 v[246:247], v[10:11], v[14:15]
	v_pk_add_f32 v[248:249], v[10:11], v[14:15] neg_lo:[0,1] neg_hi:[0,1]
	v_pk_add_f32 v[8:9], v[242:243], v[246:247]
	ds_write_b64 v226, v[8:9] offset:512
	v_pk_add_f32 v[10:11], v[244:245], v[248:249] op_sel:[0,1] op_sel_hi:[1,0] neg_hi:[0,1]
	v_pk_mul_f32 v[250:251], v[10:11], v[236:237] op_sel:[1,1] op_sel_hi:[1,0]
	v_pk_fma_f32 v[10:11], v[10:11], v[236:237], v[250:251] op_sel:[0,0,0] op_sel_hi:[0,1,1] neg_lo:[0,0,1]
	ds_write_b64 v226, v[10:11] offset:640
	v_pk_add_f32 v[12:13], v[242:243], v[246:247] neg_lo:[0,1] neg_hi:[0,1]
	v_pk_mul_f32 v[250:251], v[12:13], v[238:239] op_sel:[1,1] op_sel_hi:[1,0]
	v_pk_fma_f32 v[12:13], v[12:13], v[238:239], v[250:251] op_sel:[0,0,0] op_sel_hi:[0,1,1] neg_lo:[0,0,1]
	ds_write_b64 v226, v[12:13] offset:768
	v_pk_add_f32 v[14:15], v[244:245], v[248:249] op_sel:[0,1] op_sel_hi:[1,0] neg_lo:[0,1]
	v_pk_mul_f32 v[250:251], v[14:15], v[240:241] op_sel:[1,1] op_sel_hi:[1,0]
	v_pk_fma_f32 v[14:15], v[14:15], v[240:241], v[250:251] op_sel:[0,0,0] op_sel_hi:[0,1,1] neg_lo:[0,0,1]
	ds_write_b64 v226, v[14:15] offset:896
	v_pk_add_f32 v[242:243], v[16:17], v[20:21]
	v_pk_add_f32 v[244:245], v[16:17], v[20:21] neg_lo:[0,1] neg_hi:[0,1]
	v_pk_add_f32 v[246:247], v[18:19], v[22:23]
	v_pk_add_f32 v[248:249], v[18:19], v[22:23] neg_lo:[0,1] neg_hi:[0,1]
	v_pk_add_f32 v[16:17], v[242:243], v[246:247]
	ds_write_b64 v226, v[16:17] offset:1024
	v_pk_add_f32 v[18:19], v[244:245], v[248:249] op_sel:[0,1] op_sel_hi:[1,0] neg_hi:[0,1]
	v_pk_mul_f32 v[250:251], v[18:19], v[236:237] op_sel:[1,1] op_sel_hi:[1,0]
	v_pk_fma_f32 v[18:19], v[18:19], v[236:237], v[250:251] op_sel:[0,0,0] op_sel_hi:[0,1,1] neg_lo:[0,0,1]
	ds_write_b64 v226, v[18:19] offset:1152
	v_pk_add_f32 v[20:21], v[242:243], v[246:247] neg_lo:[0,1] neg_hi:[0,1]
	v_pk_mul_f32 v[250:251], v[20:21], v[238:239] op_sel:[1,1] op_sel_hi:[1,0]
	v_pk_fma_f32 v[20:21], v[20:21], v[238:239], v[250:251] op_sel:[0,0,0] op_sel_hi:[0,1,1] neg_lo:[0,0,1]
	ds_write_b64 v226, v[20:21] offset:1280
	v_pk_add_f32 v[22:23], v[244:245], v[248:249] op_sel:[0,1] op_sel_hi:[1,0] neg_lo:[0,1]
	v_pk_mul_f32 v[250:251], v[22:23], v[240:241] op_sel:[1,1] op_sel_hi:[1,0]
	v_pk_fma_f32 v[22:23], v[22:23], v[240:241], v[250:251] op_sel:[0,0,0] op_sel_hi:[0,1,1] neg_lo:[0,0,1]
	ds_write_b64 v226, v[22:23] offset:1408
	v_pk_add_f32 v[242:243], v[24:25], v[28:29]
	v_pk_add_f32 v[244:245], v[24:25], v[28:29] neg_lo:[0,1] neg_hi:[0,1]
	v_pk_add_f32 v[246:247], v[26:27], v[30:31]
	v_pk_add_f32 v[248:249], v[26:27], v[30:31] neg_lo:[0,1] neg_hi:[0,1]
	v_pk_add_f32 v[24:25], v[242:243], v[246:247]
	ds_write_b64 v226, v[24:25] offset:1536
	v_pk_add_f32 v[26:27], v[244:245], v[248:249] op_sel:[0,1] op_sel_hi:[1,0] neg_hi:[0,1]
	v_pk_mul_f32 v[250:251], v[26:27], v[236:237] op_sel:[1,1] op_sel_hi:[1,0]
	v_pk_fma_f32 v[26:27], v[26:27], v[236:237], v[250:251] op_sel:[0,0,0] op_sel_hi:[0,1,1] neg_lo:[0,0,1]
	ds_write_b64 v226, v[26:27] offset:1664
	v_pk_add_f32 v[28:29], v[242:243], v[246:247] neg_lo:[0,1] neg_hi:[0,1]
	v_pk_mul_f32 v[250:251], v[28:29], v[238:239] op_sel:[1,1] op_sel_hi:[1,0]
	v_pk_fma_f32 v[28:29], v[28:29], v[238:239], v[250:251] op_sel:[0,0,0] op_sel_hi:[0,1,1] neg_lo:[0,0,1]
	ds_write_b64 v226, v[28:29] offset:1792
	v_pk_add_f32 v[30:31], v[244:245], v[248:249] op_sel:[0,1] op_sel_hi:[1,0] neg_lo:[0,1]
	v_pk_mul_f32 v[250:251], v[30:31], v[240:241] op_sel:[1,1] op_sel_hi:[1,0]
	v_pk_fma_f32 v[30:31], v[30:31], v[240:241], v[250:251] op_sel:[0,0,0] op_sel_hi:[0,1,1] neg_lo:[0,0,1]
	ds_write_b64 v226, v[30:31] offset:1920
	ds_read_b64 v[0:1], v227 offset:0
	ds_read_b64 v[8:9], v227 offset:512
	ds_read_b64 v[16:17], v227 offset:1024
	ds_read_b64 v[24:25], v227 offset:1536
	ds_read_b64 v[2:3], v227 offset:128
	ds_read_b64 v[10:11], v227 offset:640
	ds_read_b64 v[18:19], v227 offset:1152
	ds_read_b64 v[26:27], v227 offset:1664
	ds_read_b64 v[4:5], v227 offset:256
	ds_read_b64 v[12:13], v227 offset:768
	ds_read_b64 v[20:21], v227 offset:1280
	ds_read_b64 v[28:29], v227 offset:1792
	ds_read_b64 v[6:7], v227 offset:384
	ds_read_b64 v[14:15], v227 offset:896
	ds_read_b64 v[22:23], v227 offset:1408
	ds_read_b64 v[30:31], v227 offset:1920
	s_waitcnt lgkmcnt(12)
	v_pk_add_f32 v[242:243], v[0:1], v[16:17]
	v_pk_add_f32 v[244:245], v[0:1], v[16:17] neg_lo:[0,1] neg_hi:[0,1]
	v_pk_add_f32 v[246:247], v[8:9], v[24:25]
	v_pk_add_f32 v[248:249], v[8:9], v[24:25] neg_lo:[0,1] neg_hi:[0,1]
	v_pk_add_f32 v[0:1], v[242:243], v[246:247]
	v_pk_add_f32 v[8:9], v[244:245], v[248:249] op_sel:[0,1] op_sel_hi:[1,0] neg_hi:[0,1]
	v_pk_mul_f32 v[250:251], v[8:9], v[80:81] op_sel:[1,1] op_sel_hi:[1,0]
	v_pk_fma_f32 v[8:9], v[8:9], v[80:81], v[250:251] op_sel:[0,0,0] op_sel_hi:[0,1,1] neg_lo:[0,0,1]
	v_pk_add_f32 v[16:17], v[242:243], v[246:247] neg_lo:[0,1] neg_hi:[0,1]
	v_pk_mul_f32 v[250:251], v[16:17], v[82:83] op_sel:[1,1] op_sel_hi:[1,0]
	v_pk_fma_f32 v[16:17], v[16:17], v[82:83], v[250:251] op_sel:[0,0,0] op_sel_hi:[0,1,1] neg_lo:[0,0,1]
	v_pk_add_f32 v[24:25], v[244:245], v[248:249] op_sel:[0,1] op_sel_hi:[1,0] neg_lo:[0,1]
	v_pk_mul_f32 v[250:251], v[24:25], v[84:85] op_sel:[1,1] op_sel_hi:[1,0]
	v_pk_fma_f32 v[24:25], v[24:25], v[84:85], v[250:251] op_sel:[0,0,0] op_sel_hi:[0,1,1] neg_lo:[0,0,1]
	s_waitcnt lgkmcnt(8)
; HD float2 cmul(float2 a, float2 b){ return make_float2(a.x*b.x - a.y*b.y, a.x*b.y + a.y*b.x); }
; HD float2 cmulc(float2 a, float2 b){ return make_float2(a.x*b.x + a.y*b.y, a.y*b.x - a.x*b.y); }
; template<bool INV, bool NOTW>
; HD void bf4c(float2* Z, int i0, int i1, int i2, int i3, float2 w1, float2 w2, float2 w3){
;   float2 a0=Z[i0], a1=Z[i1], a2=Z[i2], a3=Z[i3];
;   if (INV && !NOTW){ a1=cmulc(a1,w1); a2=cmulc(a2,w2); a3=cmulc(a3,w3); }
;   float2 s02=make_float2(a0.x+a2.x,a0.y+a2.y), d02=make_float2(a0.x-a2.x,a0.y-a2.y);
;   float2 s13=make_float2(a1.x+a3.x,a1.y+a3.y), d13=make_float2(a1.x-a3.x,a1.y-a3.y);
;   float2 y0=make_float2(s02.x+s13.x,s02.y+s13.y), y2=make_float2(s02.x-s13.x,s02.y-s13.y);
;   float2 ym=make_float2(d02.x+d13.y,d02.y-d13.x);
;   float2 yp=make_float2(d02.x-d13.y,d02.y+d13.x);
;   float2 y1, y3;
;   if (INV){ y1=yp; y3=ym; } else if (NOTW){ y1=ym; y3=yp; } else { y1=cmul(ym,w1); y2=cmul(y2,w2); y3=cmul(yp,w3); }
;   Z[i0]=y0; Z[i1]=y1; Z[i2]=y2; Z[i3]=y3;
; template<bool INV, int LQ, bool BARRIER=true>
; HD void fft_pass(float2* Z, const float2* twA, const float2* twB, int tid){
;     ...
;     int j=tid&(q-1); int base0=((tid>>LQ)<<(LQ+2))+j;
;     float2 w1=make_float2(1.f,0.f), w2=w1, w3=w1;
;     if (LQ>0){ int k=j*tws; w1=cmul(twA[k>>6],twB[k&63]); w2=cmul(w1,w1); w3=cmul(w2,w1); }
;     _Pragma("unroll") for (int i=0;i<8;++i){ int base=base0+i*2048; bf4c<INV,(LQ==0)>(Z,base,base+q,base+2*q,base+3*q,w1,w2,w3); }
;   }
;   if (BARRIER) __syncthreads(); else asm volatile("s_waitcnt lgkmcnt(0)" ::: "memory");
; }
; __device__ __forceinline__ void fft_fwd_head(float2* Z, const float2* twA, const float2* twB, int tid){
;   fft_pass<false,10>(Z,twA,twB,tid); fft_pass<false,8>(Z,twA,twB,tid); fft_pass<false,6,false>(Z,twA,twB,tid);
;   fft_pass<false,4,false>(Z,twA,twB,tid); fft_pass<false,2,false>(Z,twA,twB,tid);
	v_pk_add_f32 v[242:243], v[2:3], v[18:19]
	v_pk_add_f32 v[244:245], v[2:3], v[18:19] neg_lo:[0,1] neg_hi:[0,1]
	v_pk_add_f32 v[246:247], v[10:11], v[26:27]
	v_pk_add_f32 v[248:249], v[10:11], v[26:27] neg_lo:[0,1] neg_hi:[0,1]
	v_pk_add_f32 v[2:3], v[242:243], v[246:247]
	v_pk_add_f32 v[10:11], v[244:245], v[248:249] op_sel:[0,1] op_sel_hi:[1,0] neg_hi:[0,1]
	v_pk_mul_f32 v[250:251], v[10:11], v[80:81] op_sel:[1,1] op_sel_hi:[1,0]
	v_pk_fma_f32 v[10:11], v[10:11], v[80:81], v[250:251] op_sel:[0,0,0] op_sel_hi:[0,1,1] neg_lo:[0,0,1]
	v_pk_mul_f32 v[250:251], v[10:11], v[222:223] op_sel:[1,1] op_sel_hi:[1,0] neg_lo:[0,1] neg_hi:[0,0]
	v_pk_fma_f32 v[10:11], v[10:11], v[222:223], v[250:251] op_sel:[0,0,0] op_sel_hi:[0,1,1] neg_lo:[0,0,1] neg_hi:[0,1,0]
	v_pk_add_f32 v[18:19], v[242:243], v[246:247] neg_lo:[0,1] neg_hi:[0,1]
	v_pk_mul_f32 v[250:251], v[18:19], v[82:83] op_sel:[1,1] op_sel_hi:[1,0]
	v_pk_fma_f32 v[18:19], v[18:19], v[82:83], v[250:251] op_sel:[0,0,0] op_sel_hi:[0,1,1] neg_lo:[0,0,1]
	v_pk_mul_f32 v[250:251], v[18:19], v[224:225] op_sel:[1,1] op_sel_hi:[1,0] neg_lo:[0,1] neg_hi:[0,0]
	v_pk_fma_f32 v[18:19], v[18:19], v[224:225], v[250:251] op_sel:[0,0,0] op_sel_hi:[0,1,1] neg_lo:[0,0,1] neg_hi:[0,1,0]
	v_pk_add_f32 v[26:27], v[244:245], v[248:249] op_sel:[0,1] op_sel_hi:[1,0] neg_lo:[0,1]
	v_pk_mul_f32 v[250:251], v[26:27], v[84:85] op_sel:[1,1] op_sel_hi:[1,0]
	v_pk_fma_f32 v[26:27], v[26:27], v[84:85], v[250:251] op_sel:[0,0,0] op_sel_hi:[0,1,1] neg_lo:[0,0,1]
	v_pk_mul_f32 v[250:251], v[26:27], v[222:223] op_sel:[1,0] op_sel_hi:[1,1] neg_lo:[0,1] neg_hi:[0,0]
	v_pk_fma_f32 v[26:27], v[26:27], v[222:223], v[250:251] op_sel:[0,1,0] op_sel_hi:[0,0,1] neg_lo:[0,0,1] neg_hi:[0,1,0]
	s_waitcnt lgkmcnt(4)
	v_pk_add_f32 v[242:243], v[4:5], v[20:21]
	v_pk_add_f32 v[244:245], v[4:5], v[20:21] neg_lo:[0,1] neg_hi:[0,1]
	v_pk_add_f32 v[246:247], v[12:13], v[28:29]
	v_pk_add_f32 v[248:249], v[12:13], v[28:29] neg_lo:[0,1] neg_hi:[0,1]
	v_pk_add_f32 v[4:5], v[242:243], v[246:247]
	v_pk_add_f32 v[12:13], v[244:245], v[248:249] op_sel:[0,1] op_sel_hi:[1,0] neg_hi:[0,1]
	v_pk_mul_f32 v[250:251], v[12:13], v[80:81] op_sel:[1,1] op_sel_hi:[1,0]
	v_pk_fma_f32 v[12:13], v[12:13], v[80:81], v[250:251] op_sel:[0,0,0] op_sel_hi:[0,1,1] neg_lo:[0,0,1]
	v_pk_mul_f32 v[250:251], v[12:13], v[224:225] op_sel:[1,1] op_sel_hi:[1,0] neg_lo:[0,1] neg_hi:[0,0]
	v_pk_fma_f32 v[12:13], v[12:13], v[224:225], v[250:251] op_sel:[0,0,0] op_sel_hi:[0,1,1] neg_lo:[0,0,1] neg_hi:[0,1,0]
	v_pk_add_f32 v[20:21], v[242:243], v[246:247] neg_lo:[0,1] neg_hi:[0,1]
	v_pk_mul_f32 v[250:251], v[20:21], v[82:83] op_sel:[1,1] op_sel_hi:[1,0]
	v_pk_fma_f32 v[20:21], v[20:21], v[82:83], v[250:251] op_sel:[0,0,0] op_sel_hi:[0,1,1] neg_lo:[0,0,1]
	v_pk_add_f32 v[20:21], v[20:21], 0 op_sel:[1,0] op_sel_hi:[0,0] neg_hi:[1,0]
	v_pk_add_f32 v[28:29], v[244:245], v[248:249] op_sel:[0,1] op_sel_hi:[1,0] neg_lo:[0,1]
	v_pk_mul_f32 v[250:251], v[28:29], v[84:85] op_sel:[1,1] op_sel_hi:[1,0]
	v_pk_fma_f32 v[28:29], v[28:29], v[84:85], v[250:251] op_sel:[0,0,0] op_sel_hi:[0,1,1] neg_lo:[0,0,1]
	v_pk_mul_f32 v[250:251], v[28:29], v[224:225] op_sel:[1,1] op_sel_hi:[1,0] neg_lo:[0,1] neg_hi:[0,1]
	v_pk_fma_f32 v[28:29], v[28:29], v[224:225], v[250:251] op_sel:[0,0,0] op_sel_hi:[0,1,1] neg_lo:[0,1,1] neg_hi:[0,1,0]
	s_waitcnt lgkmcnt(0)
	v_pk_add_f32 v[242:243], v[6:7], v[22:23]
	v_pk_add_f32 v[244:245], v[6:7], v[22:23] neg_lo:[0,1] neg_hi:[0,1]
	v_pk_add_f32 v[246:247], v[14:15], v[30:31]
	v_pk_add_f32 v[248:249], v[14:15], v[30:31] neg_lo:[0,1] neg_hi:[0,1]
	v_pk_add_f32 v[6:7], v[242:243], v[246:247]
	v_pk_add_f32 v[14:15], v[244:245], v[248:249] op_sel:[0,1] op_sel_hi:[1,0] neg_hi:[0,1]
	v_pk_mul_f32 v[250:251], v[14:15], v[80:81] op_sel:[1,1] op_sel_hi:[1,0]
	v_pk_fma_f32 v[14:15], v[14:15], v[80:81], v[250:251] op_sel:[0,0,0] op_sel_hi:[0,1,1] neg_lo:[0,0,1]
	v_pk_mul_f32 v[250:251], v[14:15], v[222:223] op_sel:[1,0] op_sel_hi:[1,1] neg_lo:[0,1] neg_hi:[0,0]
	v_pk_fma_f32 v[14:15], v[14:15], v[222:223], v[250:251] op_sel:[0,1,0] op_sel_hi:[0,0,1] neg_lo:[0,0,1] neg_hi:[0,1,0]
	v_pk_add_f32 v[22:23], v[242:243], v[246:247] neg_lo:[0,1] neg_hi:[0,1]
	v_pk_mul_f32 v[250:251], v[22:23], v[82:83] op_sel:[1,1] op_sel_hi:[1,0]
	v_pk_fma_f32 v[22:23], v[22:23], v[82:83], v[250:251] op_sel:[0,0,0] op_sel_hi:[0,1,1] neg_lo:[0,0,1]
	v_pk_mul_f32 v[250:251], v[22:23], v[224:225] op_sel:[1,1] op_sel_hi:[1,0] neg_lo:[0,1] neg_hi:[0,1]
	v_pk_fma_f32 v[22:23], v[22:23], v[224:225], v[250:251] op_sel:[0,0,0] op_sel_hi:[0,1,1] neg_lo:[0,1,1] neg_hi:[0,1,0]
	v_pk_add_f32 v[30:31], v[244:245], v[248:249] op_sel:[0,1] op_sel_hi:[1,0] neg_lo:[0,1]
	v_pk_mul_f32 v[250:251], v[30:31], v[84:85] op_sel:[1,1] op_sel_hi:[1,0]
	v_pk_fma_f32 v[30:31], v[30:31], v[84:85], v[250:251] op_sel:[0,0,0] op_sel_hi:[0,1,1] neg_lo:[0,0,1]
	v_pk_mul_f32 v[250:251], v[30:31], v[222:223] op_sel:[1,1] op_sel_hi:[1,0] neg_lo:[0,0] neg_hi:[0,1]
	v_pk_fma_f32 v[30:31], v[30:31], v[222:223], v[250:251] op_sel:[0,0,0] op_sel_hi:[0,1,1] neg_lo:[0,1,1] neg_hi:[0,0,0]
	v_pk_add_f32 v[242:243], v[0:1], v[4:5]
	v_pk_add_f32 v[244:245], v[0:1], v[4:5] neg_lo:[0,1] neg_hi:[0,1]
	v_pk_add_f32 v[246:247], v[2:3], v[6:7]
	v_pk_add_f32 v[248:249], v[2:3], v[6:7] neg_lo:[0,1] neg_hi:[0,1]
	v_pk_add_f32 v[0:1], v[242:243], v[246:247]
	ds_write_b64 v227, v[0:1] offset:0
	v_pk_add_f32 v[2:3], v[244:245], v[248:249] op_sel:[0,1] op_sel_hi:[1,0] neg_hi:[0,1]
	v_pk_mul_f32 v[250:251], v[2:3], v[236:237] op_sel:[1,1] op_sel_hi:[1,0]
	v_pk_fma_f32 v[2:3], v[2:3], v[236:237], v[250:251] op_sel:[0,0,0] op_sel_hi:[0,1,1] neg_lo:[0,0,1]
; HD float2 cmul(float2 a, float2 b){ return make_float2(a.x*b.x - a.y*b.y, a.x*b.y + a.y*b.x); }
; HD float2 cmulc(float2 a, float2 b){ return make_float2(a.x*b.x + a.y*b.y, a.y*b.x - a.x*b.y); }
; template<bool INV, bool NOTW>
; HD void bf4c(float2* Z, int i0, int i1, int i2, int i3, float2 w1, float2 w2, float2 w3){
;   float2 a0=Z[i0], a1=Z[i1], a2=Z[i2], a3=Z[i3];
;   if (INV && !NOTW){ a1=cmulc(a1,w1); a2=cmulc(a2,w2); a3=cmulc(a3,w3); }
;   float2 s02=make_float2(a0.x+a2.x,a0.y+a2.y), d02=make_float2(a0.x-a2.x,a0.y-a2.y);
;   float2 s13=make_float2(a1.x+a3.x,a1.y+a3.y), d13=make_float2(a1.x-a3.x,a1.y-a3.y);
;   float2 y0=make_float2(s02.x+s13.x,s02.y+s13.y), y2=make_float2(s02.x-s13.x,s02.y-s13.y);
;   float2 ym=make_float2(d02.x+d13.y,d02.y-d13.x);
;   float2 yp=make_float2(d02.x-d13.y,d02.y+d13.x);
;   float2 y1, y3;
;   if (INV){ y1=yp; y3=ym; } else if (NOTW){ y1=ym; y3=yp; } else { y1=cmul(ym,w1); y2=cmul(y2,w2); y3=cmul(yp,w3); }
;   Z[i0]=y0; Z[i1]=y1; Z[i2]=y2; Z[i3]=y3;
; template<bool INV, int LQ, bool BARRIER=true>
; HD void fft_pass(float2* Z, const float2* twA, const float2* twB, int tid){
;     ...
;     int j=tid&(q-1); int base0=((tid>>LQ)<<(LQ+2))+j;
;     float2 w1=make_float2(1.f,0.f), w2=w1, w3=w1;
;     if (LQ>0){ int k=j*tws; w1=cmul(twA[k>>6],twB[k&63]); w2=cmul(w1,w1); w3=cmul(w2,w1); }
;     _Pragma("unroll") for (int i=0;i<8;++i){ int base=base0+i*2048; bf4c<INV,(LQ==0)>(Z,base,base+q,base+2*q,base+3*q,w1,w2,w3); }
;   }
;   if (BARRIER) __syncthreads(); else asm volatile("s_waitcnt lgkmcnt(0)" ::: "memory");
	ds_write_b64 v227, v[2:3] offset:128
	v_pk_add_f32 v[4:5], v[242:243], v[246:247] neg_lo:[0,1] neg_hi:[0,1]
	v_pk_mul_f32 v[250:251], v[4:5], v[238:239] op_sel:[1,1] op_sel_hi:[1,0]
	v_pk_fma_f32 v[4:5], v[4:5], v[238:239], v[250:251] op_sel:[0,0,0] op_sel_hi:[0,1,1] neg_lo:[0,0,1]
	ds_write_b64 v227, v[4:5] offset:256
	v_pk_add_f32 v[6:7], v[244:245], v[248:249] op_sel:[0,1] op_sel_hi:[1,0] neg_lo:[0,1]
	v_pk_mul_f32 v[250:251], v[6:7], v[240:241] op_sel:[1,1] op_sel_hi:[1,0]
	v_pk_fma_f32 v[6:7], v[6:7], v[240:241], v[250:251] op_sel:[0,0,0] op_sel_hi:[0,1,1] neg_lo:[0,0,1]
	ds_write_b64 v227, v[6:7] offset:384
	v_pk_add_f32 v[242:243], v[8:9], v[12:13]
	v_pk_add_f32 v[244:245], v[8:9], v[12:13] neg_lo:[0,1] neg_hi:[0,1]
	v_pk_add_f32 v[246:247], v[10:11], v[14:15]
	v_pk_add_f32 v[248:249], v[10:11], v[14:15] neg_lo:[0,1] neg_hi:[0,1]
	v_pk_add_f32 v[8:9], v[242:243], v[246:247]
	ds_write_b64 v227, v[8:9] offset:512
	v_pk_add_f32 v[10:11], v[244:245], v[248:249] op_sel:[0,1] op_sel_hi:[1,0] neg_hi:[0,1]
	v_pk_mul_f32 v[250:251], v[10:11], v[236:237] op_sel:[1,1] op_sel_hi:[1,0]
	v_pk_fma_f32 v[10:11], v[10:11], v[236:237], v[250:251] op_sel:[0,0,0] op_sel_hi:[0,1,1] neg_lo:[0,0,1]
	ds_write_b64 v227, v[10:11] offset:640
	v_pk_add_f32 v[12:13], v[242:243], v[246:247] neg_lo:[0,1] neg_hi:[0,1]
	v_pk_mul_f32 v[250:251], v[12:13], v[238:239] op_sel:[1,1] op_sel_hi:[1,0]
	v_pk_fma_f32 v[12:13], v[12:13], v[238:239], v[250:251] op_sel:[0,0,0] op_sel_hi:[0,1,1] neg_lo:[0,0,1]
	ds_write_b64 v227, v[12:13] offset:768
	v_pk_add_f32 v[14:15], v[244:245], v[248:249] op_sel:[0,1] op_sel_hi:[1,0] neg_lo:[0,1]
	v_pk_mul_f32 v[250:251], v[14:15], v[240:241] op_sel:[1,1] op_sel_hi:[1,0]
	v_pk_fma_f32 v[14:15], v[14:15], v[240:241], v[250:251] op_sel:[0,0,0] op_sel_hi:[0,1,1] neg_lo:[0,0,1]
	ds_write_b64 v227, v[14:15] offset:896
	v_pk_add_f32 v[242:243], v[16:17], v[20:21]
	v_pk_add_f32 v[244:245], v[16:17], v[20:21] neg_lo:[0,1] neg_hi:[0,1]
	v_pk_add_f32 v[246:247], v[18:19], v[22:23]
	v_pk_add_f32 v[248:249], v[18:19], v[22:23] neg_lo:[0,1] neg_hi:[0,1]
	v_pk_add_f32 v[16:17], v[242:243], v[246:247]
	ds_write_b64 v227, v[16:17] offset:1024
	v_pk_add_f32 v[18:19], v[244:245], v[248:249] op_sel:[0,1] op_sel_hi:[1,0] neg_hi:[0,1]
	v_pk_mul_f32 v[250:251], v[18:19], v[236:237] op_sel:[1,1] op_sel_hi:[1,0]
	v_pk_fma_f32 v[18:19], v[18:19], v[236:237], v[250:251] op_sel:[0,0,0] op_sel_hi:[0,1,1] neg_lo:[0,0,1]
	ds_write_b64 v227, v[18:19] offset:1152
	v_pk_add_f32 v[20:21], v[242:243], v[246:247] neg_lo:[0,1] neg_hi:[0,1]
	v_pk_mul_f32 v[250:251], v[20:21], v[238:239] op_sel:[1,1] op_sel_hi:[1,0]
	v_pk_fma_f32 v[20:21], v[20:21], v[238:239], v[250:251] op_sel:[0,0,0] op_sel_hi:[0,1,1] neg_lo:[0,0,1]
	ds_write_b64 v227, v[20:21] offset:1280
	v_pk_add_f32 v[22:23], v[244:245], v[248:249] op_sel:[0,1] op_sel_hi:[1,0] neg_lo:[0,1]
	v_pk_mul_f32 v[250:251], v[22:23], v[240:241] op_sel:[1,1] op_sel_hi:[1,0]
	v_pk_fma_f32 v[22:23], v[22:23], v[240:241], v[250:251] op_sel:[0,0,0] op_sel_hi:[0,1,1] neg_lo:[0,0,1]
	ds_write_b64 v227, v[22:23] offset:1408
	v_pk_add_f32 v[242:243], v[24:25], v[28:29]
	v_pk_add_f32 v[244:245], v[24:25], v[28:29] neg_lo:[0,1] neg_hi:[0,1]
	v_pk_add_f32 v[246:247], v[26:27], v[30:31]
	v_pk_add_f32 v[248:249], v[26:27], v[30:31] neg_lo:[0,1] neg_hi:[0,1]
	v_pk_add_f32 v[24:25], v[242:243], v[246:247]
	ds_write_b64 v227, v[24:25] offset:1536
	v_pk_add_f32 v[26:27], v[244:245], v[248:249] op_sel:[0,1] op_sel_hi:[1,0] neg_hi:[0,1]
	v_pk_mul_f32 v[250:251], v[26:27], v[236:237] op_sel:[1,1] op_sel_hi:[1,0]
	v_pk_fma_f32 v[26:27], v[26:27], v[236:237], v[250:251] op_sel:[0,0,0] op_sel_hi:[0,1,1] neg_lo:[0,0,1]
	ds_write_b64 v227, v[26:27] offset:1664
	v_pk_add_f32 v[28:29], v[242:243], v[246:247] neg_lo:[0,1] neg_hi:[0,1]
	v_pk_mul_f32 v[250:251], v[28:29], v[238:239] op_sel:[1,1] op_sel_hi:[1,0]
	v_pk_fma_f32 v[28:29], v[28:29], v[238:239], v[250:251] op_sel:[0,0,0] op_sel_hi:[0,1,1] neg_lo:[0,0,1]
	ds_write_b64 v227, v[28:29] offset:1792
	v_pk_add_f32 v[30:31], v[244:245], v[248:249] op_sel:[0,1] op_sel_hi:[1,0] neg_lo:[0,1]
	v_pk_mul_f32 v[250:251], v[30:31], v[240:241] op_sel:[1,1] op_sel_hi:[1,0]
	v_pk_fma_f32 v[30:31], v[30:31], v[240:241], v[250:251] op_sel:[0,0,0] op_sel_hi:[0,1,1] neg_lo:[0,0,1]
	ds_write_b64 v227, v[30:31] offset:1920
	s_waitcnt lgkmcnt(0)
	v_and_b32_e32 v226, 3, v154
	v_lshlrev_b32_e32 v224, 7, v226
	v_add_u32_e32 v224, 0x20800, v224
	v_mov_b32_e32 v225, 0x20a00
	ds_read_b64 v[238:239], v224
	ds_read_b64 v[240:241], v225
	s_waitcnt lgkmcnt(0)
	v_pk_mul_f32 v[30:31], v[238:239], v[240:241] op_sel:[1,1] op_sel_hi:[1,0]
	v_pk_fma_f32 v[16:17], v[238:239], v[240:241], v[30:31] op_sel:[0,0,0] op_sel_hi:[0,1,1] neg_lo:[0,0,1]
	v_pk_mul_f32 v[30:31], v[16:17], v[16:17] op_sel:[1,1] op_sel_hi:[1,0]
	v_pk_fma_f32 v[18:19], v[16:17], v[16:17], v[30:31] op_sel:[0,0,0] op_sel_hi:[0,1,1] neg_lo:[0,0,1]
	v_pk_mul_f32 v[30:31], v[18:19], v[16:17] op_sel:[1,1] op_sel_hi:[1,0]
	v_pk_fma_f32 v[20:21], v[18:19], v[16:17], v[30:31] op_sel:[0,0,0] op_sel_hi:[0,1,1] neg_lo:[0,0,1]
	v_lshrrev_b32_e32 v222, 2, v154
	v_lshlrev_b32_e32 v222, 4, v222
	v_add_u32_e32 v222, v222, v226
	v_lshlrev_b32_e32 v222, 3, v222
	v_add_u32_e32 v223, 0x10000, v222
	ds_read_b64 v[0:1], v222 offset:0
	ds_read_b64 v[2:3], v222 offset:32
	ds_read_b64 v[4:5], v222 offset:64
	ds_read_b64 v[6:7], v222 offset:96
	ds_read_b64 v[8:9], v222 offset:16384
	ds_read_b64 v[10:11], v222 offset:16416
	ds_read_b64 v[12:13], v222 offset:16448
	ds_read_b64 v[14:15], v222 offset:16480
	s_waitcnt lgkmcnt(4)
; HD float2 cmul(float2 a, float2 b){ return make_float2(a.x*b.x - a.y*b.y, a.x*b.y + a.y*b.x); }
; HD float2 cmulc(float2 a, float2 b){ return make_float2(a.x*b.x + a.y*b.y, a.y*b.x - a.x*b.y); }
; template<bool INV, bool NOTW>
; HD void bf4c(float2* Z, int i0, int i1, int i2, int i3, float2 w1, float2 w2, float2 w3){
;   float2 a0=Z[i0], a1=Z[i1], a2=Z[i2], a3=Z[i3];
;   if (INV && !NOTW){ a1=cmulc(a1,w1); a2=cmulc(a2,w2); a3=cmulc(a3,w3); }
;   float2 s02=make_float2(a0.x+a2.x,a0.y+a2.y), d02=make_float2(a0.x-a2.x,a0.y-a2.y);
;   float2 s13=make_float2(a1.x+a3.x,a1.y+a3.y), d13=make_float2(a1.x-a3.x,a1.y-a3.y);
;   float2 y0=make_float2(s02.x+s13.x,s02.y+s13.y), y2=make_float2(s02.x-s13.x,s02.y-s13.y);
;   float2 ym=make_float2(d02.x+d13.y,d02.y-d13.x);
;   float2 yp=make_float2(d02.x-d13.y,d02.y+d13.x);
;   float2 y1, y3;
;   if (INV){ y1=yp; y3=ym; } else if (NOTW){ y1=ym; y3=yp; } else { y1=cmul(ym,w1); y2=cmul(y2,w2); y3=cmul(yp,w3); }
;   Z[i0]=y0; Z[i1]=y1; Z[i2]=y2; Z[i3]=y3;
; template<bool INV, int LQ, bool BARRIER=true>
; HD void fft_pass(float2* Z, const float2* twA, const float2* twB, int tid){
;     ...
;     int j=tid&(q-1); int base0=((tid>>LQ)<<(LQ+2))+j;
;     float2 w1=make_float2(1.f,0.f), w2=w1, w3=w1;
;     if (LQ>0){ int k=j*tws; w1=cmul(twA[k>>6],twB[k&63]); w2=cmul(w1,w1); w3=cmul(w2,w1); }
;     _Pragma("unroll") for (int i=0;i<8;++i){ int base=base0+i*2048; bf4c<INV,(LQ==0)>(Z,base,base+q,base+2*q,base+3*q,w1,w2,w3); }
;   }
;   if (BARRIER) __syncthreads(); else asm volatile("s_waitcnt lgkmcnt(0)" ::: "memory");
	v_pk_add_f32 v[22:23], v[0:1], v[4:5]
	v_pk_add_f32 v[24:25], v[0:1], v[4:5] neg_lo:[0,1] neg_hi:[0,1]
	v_pk_add_f32 v[26:27], v[2:3], v[6:7]
	v_pk_add_f32 v[28:29], v[2:3], v[6:7] neg_lo:[0,1] neg_hi:[0,1]
	v_pk_add_f32 v[80:81], v[22:23], v[26:27]
	ds_write_b64 v222, v[80:81] offset:0
	v_pk_add_f32 v[244:245], v[24:25], v[28:29] op_sel:[0,1] op_sel_hi:[1,0] neg_hi:[0,1]
	v_pk_mul_f32 v[30:31], v[244:245], v[16:17] op_sel:[1,1] op_sel_hi:[1,0]
	v_pk_fma_f32 v[82:83], v[244:245], v[16:17], v[30:31] op_sel:[0,0,0] op_sel_hi:[0,1,1] neg_lo:[0,0,1]
	ds_write_b64 v222, v[82:83] offset:32
	v_pk_add_f32 v[242:243], v[22:23], v[26:27] neg_lo:[0,1] neg_hi:[0,1]
	v_pk_mul_f32 v[30:31], v[242:243], v[18:19] op_sel:[1,1] op_sel_hi:[1,0]
	v_pk_fma_f32 v[84:85], v[242:243], v[18:19], v[30:31] op_sel:[0,0,0] op_sel_hi:[0,1,1] neg_lo:[0,0,1]
	ds_write_b64 v222, v[84:85] offset:64
	v_pk_add_f32 v[246:247], v[24:25], v[28:29] op_sel:[0,1] op_sel_hi:[1,0] neg_lo:[0,1]
	v_pk_mul_f32 v[30:31], v[246:247], v[20:21] op_sel:[1,1] op_sel_hi:[1,0]
	v_pk_fma_f32 v[236:237], v[246:247], v[20:21], v[30:31] op_sel:[0,0,0] op_sel_hi:[0,1,1] neg_lo:[0,0,1]
	ds_write_b64 v222, v[236:237] offset:96
	ds_read_b64 v[0:1], v222 offset:32768
	ds_read_b64 v[2:3], v222 offset:32800
	ds_read_b64 v[4:5], v222 offset:32832
	ds_read_b64 v[6:7], v222 offset:32864
	s_waitcnt lgkmcnt(8)
	v_pk_add_f32 v[22:23], v[8:9], v[12:13]
	v_pk_add_f32 v[24:25], v[8:9], v[12:13] neg_lo:[0,1] neg_hi:[0,1]
	v_pk_add_f32 v[26:27], v[10:11], v[14:15]
	v_pk_add_f32 v[28:29], v[10:11], v[14:15] neg_lo:[0,1] neg_hi:[0,1]
	v_pk_add_f32 v[80:81], v[22:23], v[26:27]
	ds_write_b64 v222, v[80:81] offset:16384
	v_pk_add_f32 v[244:245], v[24:25], v[28:29] op_sel:[0,1] op_sel_hi:[1,0] neg_hi:[0,1]
	v_pk_mul_f32 v[30:31], v[244:245], v[16:17] op_sel:[1,1] op_sel_hi:[1,0]
	v_pk_fma_f32 v[82:83], v[244:245], v[16:17], v[30:31] op_sel:[0,0,0] op_sel_hi:[0,1,1] neg_lo:[0,0,1]
	ds_write_b64 v222, v[82:83] offset:16416
	v_pk_add_f32 v[242:243], v[22:23], v[26:27] neg_lo:[0,1] neg_hi:[0,1]
	v_pk_mul_f32 v[30:31], v[242:243], v[18:19] op_sel:[1,1] op_sel_hi:[1,0]
	v_pk_fma_f32 v[84:85], v[242:243], v[18:19], v[30:31] op_sel:[0,0,0] op_sel_hi:[0,1,1] neg_lo:[0,0,1]
	ds_write_b64 v222, v[84:85] offset:16448
	v_pk_add_f32 v[246:247], v[24:25], v[28:29] op_sel:[0,1] op_sel_hi:[1,0] neg_lo:[0,1]
	v_pk_mul_f32 v[30:31], v[246:247], v[20:21] op_sel:[1,1] op_sel_hi:[1,0]
	v_pk_fma_f32 v[236:237], v[246:247], v[20:21], v[30:31] op_sel:[0,0,0] op_sel_hi:[0,1,1] neg_lo:[0,0,1]
	ds_write_b64 v222, v[236:237] offset:16480
	ds_read_b64 v[8:9], v222 offset:49152
	ds_read_b64 v[10:11], v222 offset:49184
	ds_read_b64 v[12:13], v222 offset:49216
	ds_read_b64 v[14:15], v222 offset:49248
	s_waitcnt lgkmcnt(8)
	v_pk_add_f32 v[22:23], v[0:1], v[4:5]
	v_pk_add_f32 v[24:25], v[0:1], v[4:5] neg_lo:[0,1] neg_hi:[0,1]
	v_pk_add_f32 v[26:27], v[2:3], v[6:7]
	v_pk_add_f32 v[28:29], v[2:3], v[6:7] neg_lo:[0,1] neg_hi:[0,1]
	v_pk_add_f32 v[80:81], v[22:23], v[26:27]
	ds_write_b64 v222, v[80:81] offset:32768
	v_pk_add_f32 v[244:245], v[24:25], v[28:29] op_sel:[0,1] op_sel_hi:[1,0] neg_hi:[0,1]
	v_pk_mul_f32 v[30:31], v[244:245], v[16:17] op_sel:[1,1] op_sel_hi:[1,0]
	v_pk_fma_f32 v[82:83], v[244:245], v[16:17], v[30:31] op_sel:[0,0,0] op_sel_hi:[0,1,1] neg_lo:[0,0,1]
	ds_write_b64 v222, v[82:83] offset:32800
	v_pk_add_f32 v[242:243], v[22:23], v[26:27] neg_lo:[0,1] neg_hi:[0,1]
	v_pk_mul_f32 v[30:31], v[242:243], v[18:19] op_sel:[1,1] op_sel_hi:[1,0]
	v_pk_fma_f32 v[84:85], v[242:243], v[18:19], v[30:31] op_sel:[0,0,0] op_sel_hi:[0,1,1] neg_lo:[0,0,1]
	ds_write_b64 v222, v[84:85] offset:32832
	v_pk_add_f32 v[246:247], v[24:25], v[28:29] op_sel:[0,1] op_sel_hi:[1,0] neg_lo:[0,1]
	v_pk_mul_f32 v[30:31], v[246:247], v[20:21] op_sel:[1,1] op_sel_hi:[1,0]
	v_pk_fma_f32 v[236:237], v[246:247], v[20:21], v[30:31] op_sel:[0,0,0] op_sel_hi:[0,1,1] neg_lo:[0,0,1]
	ds_write_b64 v222, v[236:237] offset:32864
	ds_read_b64 v[0:1], v223 offset:0
	ds_read_b64 v[2:3], v223 offset:32
	ds_read_b64 v[4:5], v223 offset:64
	ds_read_b64 v[6:7], v223 offset:96
	s_waitcnt lgkmcnt(8)
	v_pk_add_f32 v[22:23], v[8:9], v[12:13]
	v_pk_add_f32 v[24:25], v[8:9], v[12:13] neg_lo:[0,1] neg_hi:[0,1]
	v_pk_add_f32 v[26:27], v[10:11], v[14:15]
	v_pk_add_f32 v[28:29], v[10:11], v[14:15] neg_lo:[0,1] neg_hi:[0,1]
	v_pk_add_f32 v[80:81], v[22:23], v[26:27]
	ds_write_b64 v222, v[80:81] offset:49152
	v_pk_add_f32 v[244:245], v[24:25], v[28:29] op_sel:[0,1] op_sel_hi:[1,0] neg_hi:[0,1]
	v_pk_mul_f32 v[30:31], v[244:245], v[16:17] op_sel:[1,1] op_sel_hi:[1,0]
	v_pk_fma_f32 v[82:83], v[244:245], v[16:17], v[30:31] op_sel:[0,0,0] op_sel_hi:[0,1,1] neg_lo:[0,0,1]
	ds_write_b64 v222, v[82:83] offset:49184
	v_pk_add_f32 v[242:243], v[22:23], v[26:27] neg_lo:[0,1] neg_hi:[0,1]
	v_pk_mul_f32 v[30:31], v[242:243], v[18:19] op_sel:[1,1] op_sel_hi:[1,0]
	v_pk_fma_f32 v[84:85], v[242:243], v[18:19], v[30:31] op_sel:[0,0,0] op_sel_hi:[0,1,1] neg_lo:[0,0,1]
	ds_write_b64 v222, v[84:85] offset:49216
	v_pk_add_f32 v[246:247], v[24:25], v[28:29] op_sel:[0,1] op_sel_hi:[1,0] neg_lo:[0,1]
	v_pk_mul_f32 v[30:31], v[246:247], v[20:21] op_sel:[1,1] op_sel_hi:[1,0]
	v_pk_fma_f32 v[236:237], v[246:247], v[20:21], v[30:31] op_sel:[0,0,0] op_sel_hi:[0,1,1] neg_lo:[0,0,1]
	ds_write_b64 v222, v[236:237] offset:49248
	ds_read_b64 v[8:9], v223 offset:16384
	ds_read_b64 v[10:11], v223 offset:16416
	ds_read_b64 v[12:13], v223 offset:16448
	ds_read_b64 v[14:15], v223 offset:16480
	s_waitcnt lgkmcnt(8)
; HD float2 cmul(float2 a, float2 b){ return make_float2(a.x*b.x - a.y*b.y, a.x*b.y + a.y*b.x); }
; HD float2 cmulc(float2 a, float2 b){ return make_float2(a.x*b.x + a.y*b.y, a.y*b.x - a.x*b.y); }
; template<bool INV, bool NOTW>
; HD void bf4c(float2* Z, int i0, int i1, int i2, int i3, float2 w1, float2 w2, float2 w3){
;   float2 a0=Z[i0], a1=Z[i1], a2=Z[i2], a3=Z[i3];
;   if (INV && !NOTW){ a1=cmulc(a1,w1); a2=cmulc(a2,w2); a3=cmulc(a3,w3); }
;   float2 s02=make_float2(a0.x+a2.x,a0.y+a2.y), d02=make_float2(a0.x-a2.x,a0.y-a2.y);
;   float2 s13=make_float2(a1.x+a3.x,a1.y+a3.y), d13=make_float2(a1.x-a3.x,a1.y-a3.y);
;   float2 y0=make_float2(s02.x+s13.x,s02.y+s13.y), y2=make_float2(s02.x-s13.x,s02.y-s13.y);
;   float2 ym=make_float2(d02.x+d13.y,d02.y-d13.x);
;   float2 yp=make_float2(d02.x-d13.y,d02.y+d13.x);
;   float2 y1, y3;
;   if (INV){ y1=yp; y3=ym; } else if (NOTW){ y1=ym; y3=yp; } else { y1=cmul(ym,w1); y2=cmul(y2,w2); y3=cmul(yp,w3); }
;   Z[i0]=y0; Z[i1]=y1; Z[i2]=y2; Z[i3]=y3;
; template<bool INV, int LQ, bool BARRIER=true>
; HD void fft_pass(float2* Z, const float2* twA, const float2* twB, int tid){
;     ...
;     int j=tid&(q-1); int base0=((tid>>LQ)<<(LQ+2))+j;
;     float2 w1=make_float2(1.f,0.f), w2=w1, w3=w1;
;     if (LQ>0){ int k=j*tws; w1=cmul(twA[k>>6],twB[k&63]); w2=cmul(w1,w1); w3=cmul(w2,w1); }
;     _Pragma("unroll") for (int i=0;i<8;++i){ int base=base0+i*2048; bf4c<INV,(LQ==0)>(Z,base,base+q,base+2*q,base+3*q,w1,w2,w3); }
;   }
;   if (BARRIER) __syncthreads(); else asm volatile("s_waitcnt lgkmcnt(0)" ::: "memory");
	v_pk_add_f32 v[22:23], v[0:1], v[4:5]
	v_pk_add_f32 v[24:25], v[0:1], v[4:5] neg_lo:[0,1] neg_hi:[0,1]
	v_pk_add_f32 v[26:27], v[2:3], v[6:7]
	v_pk_add_f32 v[28:29], v[2:3], v[6:7] neg_lo:[0,1] neg_hi:[0,1]
	v_pk_add_f32 v[80:81], v[22:23], v[26:27]
	ds_write_b64 v223, v[80:81] offset:0
	v_pk_add_f32 v[244:245], v[24:25], v[28:29] op_sel:[0,1] op_sel_hi:[1,0] neg_hi:[0,1]
	v_pk_mul_f32 v[30:31], v[244:245], v[16:17] op_sel:[1,1] op_sel_hi:[1,0]
	v_pk_fma_f32 v[82:83], v[244:245], v[16:17], v[30:31] op_sel:[0,0,0] op_sel_hi:[0,1,1] neg_lo:[0,0,1]
	ds_write_b64 v223, v[82:83] offset:32
	v_pk_add_f32 v[242:243], v[22:23], v[26:27] neg_lo:[0,1] neg_hi:[0,1]
	v_pk_mul_f32 v[30:31], v[242:243], v[18:19] op_sel:[1,1] op_sel_hi:[1,0]
	v_pk_fma_f32 v[84:85], v[242:243], v[18:19], v[30:31] op_sel:[0,0,0] op_sel_hi:[0,1,1] neg_lo:[0,0,1]
	ds_write_b64 v223, v[84:85] offset:64
	v_pk_add_f32 v[246:247], v[24:25], v[28:29] op_sel:[0,1] op_sel_hi:[1,0] neg_lo:[0,1]
	v_pk_mul_f32 v[30:31], v[246:247], v[20:21] op_sel:[1,1] op_sel_hi:[1,0]
	v_pk_fma_f32 v[236:237], v[246:247], v[20:21], v[30:31] op_sel:[0,0,0] op_sel_hi:[0,1,1] neg_lo:[0,0,1]
	ds_write_b64 v223, v[236:237] offset:96
	ds_read_b64 v[0:1], v223 offset:32768
	ds_read_b64 v[2:3], v223 offset:32800
	ds_read_b64 v[4:5], v223 offset:32832
	ds_read_b64 v[6:7], v223 offset:32864
	s_waitcnt lgkmcnt(8)
	v_pk_add_f32 v[22:23], v[8:9], v[12:13]
	v_pk_add_f32 v[24:25], v[8:9], v[12:13] neg_lo:[0,1] neg_hi:[0,1]
	v_pk_add_f32 v[26:27], v[10:11], v[14:15]
	v_pk_add_f32 v[28:29], v[10:11], v[14:15] neg_lo:[0,1] neg_hi:[0,1]
	v_pk_add_f32 v[80:81], v[22:23], v[26:27]
	ds_write_b64 v223, v[80:81] offset:16384
	v_pk_add_f32 v[244:245], v[24:25], v[28:29] op_sel:[0,1] op_sel_hi:[1,0] neg_hi:[0,1]
	v_pk_mul_f32 v[30:31], v[244:245], v[16:17] op_sel:[1,1] op_sel_hi:[1,0]
	v_pk_fma_f32 v[82:83], v[244:245], v[16:17], v[30:31] op_sel:[0,0,0] op_sel_hi:[0,1,1] neg_lo:[0,0,1]
	ds_write_b64 v223, v[82:83] offset:16416
	v_pk_add_f32 v[242:243], v[22:23], v[26:27] neg_lo:[0,1] neg_hi:[0,1]
	v_pk_mul_f32 v[30:31], v[242:243], v[18:19] op_sel:[1,1] op_sel_hi:[1,0]
	v_pk_fma_f32 v[84:85], v[242:243], v[18:19], v[30:31] op_sel:[0,0,0] op_sel_hi:[0,1,1] neg_lo:[0,0,1]
	ds_write_b64 v223, v[84:85] offset:16448
	v_pk_add_f32 v[246:247], v[24:25], v[28:29] op_sel:[0,1] op_sel_hi:[1,0] neg_lo:[0,1]
	v_pk_mul_f32 v[30:31], v[246:247], v[20:21] op_sel:[1,1] op_sel_hi:[1,0]
	v_pk_fma_f32 v[236:237], v[246:247], v[20:21], v[30:31] op_sel:[0,0,0] op_sel_hi:[0,1,1] neg_lo:[0,0,1]
	ds_write_b64 v223, v[236:237] offset:16480
	ds_read_b64 v[8:9], v223 offset:49152
	ds_read_b64 v[10:11], v223 offset:49184
	ds_read_b64 v[12:13], v223 offset:49216
	ds_read_b64 v[14:15], v223 offset:49248
	s_waitcnt lgkmcnt(8)
	v_pk_add_f32 v[22:23], v[0:1], v[4:5]
	v_pk_add_f32 v[24:25], v[0:1], v[4:5] neg_lo:[0,1] neg_hi:[0,1]
	v_pk_add_f32 v[26:27], v[2:3], v[6:7]
	v_pk_add_f32 v[28:29], v[2:3], v[6:7] neg_lo:[0,1] neg_hi:[0,1]
	v_pk_add_f32 v[80:81], v[22:23], v[26:27]
	ds_write_b64 v223, v[80:81] offset:32768
	v_pk_add_f32 v[244:245], v[24:25], v[28:29] op_sel:[0,1] op_sel_hi:[1,0] neg_hi:[0,1]
	v_pk_mul_f32 v[30:31], v[244:245], v[16:17] op_sel:[1,1] op_sel_hi:[1,0]
	v_pk_fma_f32 v[82:83], v[244:245], v[16:17], v[30:31] op_sel:[0,0,0] op_sel_hi:[0,1,1] neg_lo:[0,0,1]
	ds_write_b64 v223, v[82:83] offset:32800
	v_pk_add_f32 v[242:243], v[22:23], v[26:27] neg_lo:[0,1] neg_hi:[0,1]
	v_pk_mul_f32 v[30:31], v[242:243], v[18:19] op_sel:[1,1] op_sel_hi:[1,0]
	v_pk_fma_f32 v[84:85], v[242:243], v[18:19], v[30:31] op_sel:[0,0,0] op_sel_hi:[0,1,1] neg_lo:[0,0,1]
	ds_write_b64 v223, v[84:85] offset:32832
	v_pk_add_f32 v[246:247], v[24:25], v[28:29] op_sel:[0,1] op_sel_hi:[1,0] neg_lo:[0,1]
	v_pk_mul_f32 v[30:31], v[246:247], v[20:21] op_sel:[1,1] op_sel_hi:[1,0]
	v_pk_fma_f32 v[236:237], v[246:247], v[20:21], v[30:31] op_sel:[0,0,0] op_sel_hi:[0,1,1] neg_lo:[0,0,1]
	ds_write_b64 v223, v[236:237] offset:32864
	s_waitcnt lgkmcnt(4)
	v_pk_add_f32 v[22:23], v[8:9], v[12:13]
	v_pk_add_f32 v[24:25], v[8:9], v[12:13] neg_lo:[0,1] neg_hi:[0,1]
	v_pk_add_f32 v[26:27], v[10:11], v[14:15]
	v_pk_add_f32 v[28:29], v[10:11], v[14:15] neg_lo:[0,1] neg_hi:[0,1]
	v_pk_add_f32 v[80:81], v[22:23], v[26:27]
	ds_write_b64 v223, v[80:81] offset:49152
	v_pk_add_f32 v[244:245], v[24:25], v[28:29] op_sel:[0,1] op_sel_hi:[1,0] neg_hi:[0,1]
	v_pk_mul_f32 v[30:31], v[244:245], v[16:17] op_sel:[1,1] op_sel_hi:[1,0]
	v_pk_fma_f32 v[82:83], v[244:245], v[16:17], v[30:31] op_sel:[0,0,0] op_sel_hi:[0,1,1] neg_lo:[0,0,1]
	ds_write_b64 v223, v[82:83] offset:49184
	v_pk_add_f32 v[242:243], v[22:23], v[26:27] neg_lo:[0,1] neg_hi:[0,1]
	v_pk_mul_f32 v[30:31], v[242:243], v[18:19] op_sel:[1,1] op_sel_hi:[1,0]
	v_pk_fma_f32 v[84:85], v[242:243], v[18:19], v[30:31] op_sel:[0,0,0] op_sel_hi:[0,1,1] neg_lo:[0,0,1]
	ds_write_b64 v223, v[84:85] offset:49216
	v_pk_add_f32 v[246:247], v[24:25], v[28:29] op_sel:[0,1] op_sel_hi:[1,0] neg_lo:[0,1]
	v_pk_mul_f32 v[30:31], v[246:247], v[20:21] op_sel:[1,1] op_sel_hi:[1,0]
	v_pk_fma_f32 v[236:237], v[246:247], v[20:21], v[30:31] op_sel:[0,0,0] op_sel_hi:[0,1,1] neg_lo:[0,0,1]
	ds_write_b64 v223, v[236:237] offset:49248
	s_waitcnt lgkmcnt(0)
	v_add_u32_e32 v14, 0x4000, v169
	v_add_u32_e32 v15, 0x8000, v169
	v_add_u32_e32 v16, 0xc000, v169
	v_add_u32_e32 v17, 0x4000, v186
	v_add_u32_e32 v18, 0x8000, v186
	v_add_u32_e32 v19, 0xc000, v186
	s_mov_b64 s[12:13], -1
	s_and_b64 vcc, exec, s[68:69]
	s_cbranch_vccz .LBB0_1344
; HD float2 cmul(float2 a, float2 b){ return make_float2(a.x*b.x - a.y*b.y, a.x*b.y + a.y*b.x); }
; __device__ __forceinline__ void fft_mid(float2* Z, const f16x2* Hp, int tid){
;   _Pragma("unroll 4") for (int i=0;i<8;++i){ int base=(tid<<2)+i*2048;
;     u32x4 hw=*(const u32x4*)(Hp+base);
;     unsigned hw0=hw[0], hw1=hw[1], hw2=hw[2], hw3=hw[3];
;     float2 a0=Z[base], a1=Z[base+1], a2=Z[base+2], a3=Z[base+3];
;     float2 s02=make_float2(a0.x+a2.x,a0.y+a2.y), d02=make_float2(a0.x-a2.x,a0.y-a2.y);
;     float2 s13=make_float2(a1.x+a3.x,a1.y+a3.y), d13=make_float2(a1.x-a3.x,a1.y-a3.y);
;     float2 y0=make_float2(s02.x+s13.x,s02.y+s13.y), y2=make_float2(s02.x-s13.x,s02.y-s13.y);
;     float2 y1=make_float2(d02.x+d13.y,d02.y-d13.x);
;     float2 y3=make_float2(d02.x-d13.y,d02.y+d13.x);
;     f16x2 h0=__builtin_bit_cast(f16x2,hw0), h1=__builtin_bit_cast(f16x2,hw1), h2=__builtin_bit_cast(f16x2,hw2), h3=__builtin_bit_cast(f16x2,hw3);
;     float2 b0=cmul(y0,make_float2((float)h0[0],(float)h0[1])), b1=cmul(y1,make_float2((float)h1[0],(float)h1[1]));
;     float2 b2=cmul(y2,make_float2((float)h2[0],(float)h2[1])), b3=cmul(y3,make_float2((float)h3[0],(float)h3[1]));
;     float2 t02=make_float2(b0.x+b2.x,b0.y+b2.y), e02=make_float2(b0.x-b2.x,b0.y-b2.y);
;     float2 t13=make_float2(b1.x+b3.x,b1.y+b3.y), e13=make_float2(b1.x-b3.x,b1.y-b3.y);
;     Z[base]=make_float2(t02.x+t13.x,t02.y+t13.y); Z[base+2]=make_float2(t02.x-t13.x,t02.y-t13.y);
;     Z[base+1]=make_float2(e02.x-e13.y,e02.y+e13.x);
;     Z[base+3]=make_float2(e02.x+e13.y,e02.y-e13.x);
;   }
	s_cmp_lg_u32 s89, 1
	s_cselect_b64 s[50:51], -1, 0
	s_cmp_eq_u32 s89, 1
	s_cselect_b32 s69, s77, s79
	s_cselect_b32 s68, s76, s78
	v_lshlrev_b32_e32 v224, 4, v154
	v_lshlrev_b32_e32 v222, 5, v154
	v_add_u32_e32 v223, 0x10000, v222
	global_load_dwordx4 v[236:239], v224, s[68:69]
	s_add_u32 s98, s68, 0x2000
	s_addc_u32 s99, s69, 0
	global_load_dwordx4 v[240:243], v224, s[98:99]
	s_add_u32 s98, s68, 0x4000
	s_addc_u32 s99, s69, 0
	global_load_dwordx4 v[244:247], v224, s[98:99]
	s_add_u32 s98, s68, 0x6000
	s_addc_u32 s99, s69, 0
	global_load_dwordx4 v[248:251], v224, s[98:99]
	ds_read_b128 v[0:3], v222 offset:0
	ds_read_b128 v[4:7], v222 offset:16
	s_waitcnt vmcnt(3) lgkmcnt(0)
	v_add_f32_e32 v8, v0, v4
	v_sub_f32_e32 v10, v0, v4
	v_add_f32_e32 v12, v2, v6
	v_sub_f32_e32 v20, v2, v6
	v_add_f32_e32 v9, v1, v5
	v_sub_f32_e32 v11, v1, v5
	v_add_f32_e32 v13, v3, v7
	v_sub_f32_e32 v21, v3, v7
	v_add_f32_e32 v22, v8, v12
	v_add_f32_e32 v23, v9, v13
	v_sub_f32_e32 v26, v8, v12
	v_sub_f32_e32 v27, v9, v13
	v_add_f32_e32 v24, v10, v21
	v_sub_f32_e32 v25, v11, v20
	v_sub_f32_e32 v28, v10, v21
	v_add_f32_e32 v29, v11, v20
	v_cvt_f32_f16_e32 v30, v236
	v_cvt_f32_f16_sdwa v31, v236 dst_sel:DWORD dst_unused:UNUSED_PAD src0_sel:WORD_1
	s_nop 0
	v_mul_f32_e32 v0, v23, v31
	v_fma_f32 v0, v22, v30, -v0
	v_mul_f32_e32 v1, v23, v30
	v_fma_f32 v1, v22, v31, v1
	v_cvt_f32_f16_e32 v30, v237
	v_cvt_f32_f16_sdwa v31, v237 dst_sel:DWORD dst_unused:UNUSED_PAD src0_sel:WORD_1
	s_nop 0
	v_mul_f32_e32 v2, v25, v31
	v_fma_f32 v2, v24, v30, -v2
	v_mul_f32_e32 v3, v25, v30
	v_fma_f32 v3, v24, v31, v3
	v_cvt_f32_f16_e32 v30, v238
	v_cvt_f32_f16_sdwa v31, v238 dst_sel:DWORD dst_unused:UNUSED_PAD src0_sel:WORD_1
	s_nop 0
	v_mul_f32_e32 v4, v27, v31
	v_fma_f32 v4, v26, v30, -v4
	v_mul_f32_e32 v5, v27, v30
	v_fma_f32 v5, v26, v31, v5
	v_cvt_f32_f16_e32 v30, v239
	v_cvt_f32_f16_sdwa v31, v239 dst_sel:DWORD dst_unused:UNUSED_PAD src0_sel:WORD_1
	s_nop 0
	v_mul_f32_e32 v6, v29, v31
	v_fma_f32 v6, v28, v30, -v6
	v_mul_f32_e32 v7, v29, v30
	v_fma_f32 v7, v28, v31, v7
	v_add_f32_e32 v8, v0, v4
	v_sub_f32_e32 v10, v0, v4
	v_add_f32_e32 v12, v2, v6
	v_sub_f32_e32 v20, v2, v6
	v_add_f32_e32 v9, v1, v5
	v_sub_f32_e32 v11, v1, v5
	v_add_f32_e32 v13, v3, v7
	v_sub_f32_e32 v21, v3, v7
	v_add_f32_e32 v0, v8, v12
	v_add_f32_e32 v1, v9, v13
	v_sub_f32_e32 v2, v10, v21
	v_add_f32_e32 v3, v11, v20
	v_sub_f32_e32 v4, v8, v12
	v_sub_f32_e32 v5, v9, v13
	v_add_f32_e32 v6, v10, v21
	v_sub_f32_e32 v7, v11, v20
	ds_write_b128 v222, v[0:3] offset:0
	ds_write_b128 v222, v[4:7] offset:16
	ds_read_b128 v[0:3], v222 offset:16384
	ds_read_b128 v[4:7], v222 offset:16400
	s_waitcnt vmcnt(2) lgkmcnt(0)
	v_add_f32_e32 v8, v0, v4
	v_sub_f32_e32 v10, v0, v4
	v_add_f32_e32 v12, v2, v6
	v_sub_f32_e32 v20, v2, v6
	v_add_f32_e32 v9, v1, v5
	v_sub_f32_e32 v11, v1, v5
	v_add_f32_e32 v13, v3, v7
	v_sub_f32_e32 v21, v3, v7
	v_add_f32_e32 v22, v8, v12
	v_add_f32_e32 v23, v9, v13
	v_sub_f32_e32 v26, v8, v12
	v_sub_f32_e32 v27, v9, v13
	v_add_f32_e32 v24, v10, v21
	v_sub_f32_e32 v25, v11, v20
	v_sub_f32_e32 v28, v10, v21
	v_add_f32_e32 v29, v11, v20
	v_cvt_f32_f16_e32 v30, v240
	v_cvt_f32_f16_sdwa v31, v240 dst_sel:DWORD dst_unused:UNUSED_PAD src0_sel:WORD_1
	s_nop 0
	v_mul_f32_e32 v0, v23, v31
	v_fma_f32 v0, v22, v30, -v0
	v_mul_f32_e32 v1, v23, v30
	v_fma_f32 v1, v22, v31, v1
	v_cvt_f32_f16_e32 v30, v241
	v_cvt_f32_f16_sdwa v31, v241 dst_sel:DWORD dst_unused:UNUSED_PAD src0_sel:WORD_1
	s_nop 0
	v_mul_f32_e32 v2, v25, v31
	v_fma_f32 v2, v24, v30, -v2
	v_mul_f32_e32 v3, v25, v30
	v_fma_f32 v3, v24, v31, v3
	v_cvt_f32_f16_e32 v30, v242
	v_cvt_f32_f16_sdwa v31, v242 dst_sel:DWORD dst_unused:UNUSED_PAD src0_sel:WORD_1
	s_nop 0
	v_mul_f32_e32 v4, v27, v31
	v_fma_f32 v4, v26, v30, -v4
	v_mul_f32_e32 v5, v27, v30
	v_fma_f32 v5, v26, v31, v5
	v_cvt_f32_f16_e32 v30, v243
	v_cvt_f32_f16_sdwa v31, v243 dst_sel:DWORD dst_unused:UNUSED_PAD src0_sel:WORD_1
	s_nop 0
	v_mul_f32_e32 v6, v29, v31
	v_fma_f32 v6, v28, v30, -v6
	v_mul_f32_e32 v7, v29, v30
	v_fma_f32 v7, v28, v31, v7
	v_add_f32_e32 v8, v0, v4
	v_sub_f32_e32 v10, v0, v4
	v_add_f32_e32 v12, v2, v6
	v_sub_f32_e32 v20, v2, v6
	v_add_f32_e32 v9, v1, v5
	v_sub_f32_e32 v11, v1, v5
	v_add_f32_e32 v13, v3, v7
	v_sub_f32_e32 v21, v3, v7
	v_add_f32_e32 v0, v8, v12
	v_add_f32_e32 v1, v9, v13
	v_sub_f32_e32 v2, v10, v21
	v_add_f32_e32 v3, v11, v20
	v_sub_f32_e32 v4, v8, v12
	v_sub_f32_e32 v5, v9, v13
	v_add_f32_e32 v6, v10, v21
	v_sub_f32_e32 v7, v11, v20
	ds_write_b128 v222, v[0:3] offset:16384
	ds_write_b128 v222, v[4:7] offset:16400
	ds_read_b128 v[0:3], v222 offset:32768
	ds_read_b128 v[4:7], v222 offset:32784
	s_waitcnt vmcnt(1) lgkmcnt(0)
; HD float2 cmul(float2 a, float2 b){ return make_float2(a.x*b.x - a.y*b.y, a.x*b.y + a.y*b.x); }
; __device__ __forceinline__ void fft_mid(float2* Z, const f16x2* Hp, int tid){
;   _Pragma("unroll 4") for (int i=0;i<8;++i){ int base=(tid<<2)+i*2048;
;     u32x4 hw=*(const u32x4*)(Hp+base);
;     unsigned hw0=hw[0], hw1=hw[1], hw2=hw[2], hw3=hw[3];
;     float2 a0=Z[base], a1=Z[base+1], a2=Z[base+2], a3=Z[base+3];
;     float2 s02=make_float2(a0.x+a2.x,a0.y+a2.y), d02=make_float2(a0.x-a2.x,a0.y-a2.y);
;     float2 s13=make_float2(a1.x+a3.x,a1.y+a3.y), d13=make_float2(a1.x-a3.x,a1.y-a3.y);
;     float2 y0=make_float2(s02.x+s13.x,s02.y+s13.y), y2=make_float2(s02.x-s13.x,s02.y-s13.y);
;     float2 y1=make_float2(d02.x+d13.y,d02.y-d13.x);
;     float2 y3=make_float2(d02.x-d13.y,d02.y+d13.x);
;     f16x2 h0=__builtin_bit_cast(f16x2,hw0), h1=__builtin_bit_cast(f16x2,hw1), h2=__builtin_bit_cast(f16x2,hw2), h3=__builtin_bit_cast(f16x2,hw3);
;     float2 b0=cmul(y0,make_float2((float)h0[0],(float)h0[1])), b1=cmul(y1,make_float2((float)h1[0],(float)h1[1]));
;     float2 b2=cmul(y2,make_float2((float)h2[0],(float)h2[1])), b3=cmul(y3,make_float2((float)h3[0],(float)h3[1]));
;     float2 t02=make_float2(b0.x+b2.x,b0.y+b2.y), e02=make_float2(b0.x-b2.x,b0.y-b2.y);
;     float2 t13=make_float2(b1.x+b3.x,b1.y+b3.y), e13=make_float2(b1.x-b3.x,b1.y-b3.y);
;     Z[base]=make_float2(t02.x+t13.x,t02.y+t13.y); Z[base+2]=make_float2(t02.x-t13.x,t02.y-t13.y);
;     Z[base+1]=make_float2(e02.x-e13.y,e02.y+e13.x);
;     Z[base+3]=make_float2(e02.x+e13.y,e02.y-e13.x);
;   }
;   asm volatile("s_waitcnt lgkmcnt(0)" ::: "memory");
	v_add_f32_e32 v8, v0, v4
	v_sub_f32_e32 v10, v0, v4
	v_add_f32_e32 v12, v2, v6
	v_sub_f32_e32 v20, v2, v6
	v_add_f32_e32 v9, v1, v5
	v_sub_f32_e32 v11, v1, v5
	v_add_f32_e32 v13, v3, v7
	v_sub_f32_e32 v21, v3, v7
	v_add_f32_e32 v22, v8, v12
	v_add_f32_e32 v23, v9, v13
	v_sub_f32_e32 v26, v8, v12
	v_sub_f32_e32 v27, v9, v13
	v_add_f32_e32 v24, v10, v21
	v_sub_f32_e32 v25, v11, v20
	v_sub_f32_e32 v28, v10, v21
	v_add_f32_e32 v29, v11, v20
	v_cvt_f32_f16_e32 v30, v244
	v_cvt_f32_f16_sdwa v31, v244 dst_sel:DWORD dst_unused:UNUSED_PAD src0_sel:WORD_1
	s_nop 0
	v_mul_f32_e32 v0, v23, v31
	v_fma_f32 v0, v22, v30, -v0
	v_mul_f32_e32 v1, v23, v30
	v_fma_f32 v1, v22, v31, v1
	v_cvt_f32_f16_e32 v30, v245
	v_cvt_f32_f16_sdwa v31, v245 dst_sel:DWORD dst_unused:UNUSED_PAD src0_sel:WORD_1
	s_nop 0
	v_mul_f32_e32 v2, v25, v31
	v_fma_f32 v2, v24, v30, -v2
	v_mul_f32_e32 v3, v25, v30
	v_fma_f32 v3, v24, v31, v3
	v_cvt_f32_f16_e32 v30, v246
	v_cvt_f32_f16_sdwa v31, v246 dst_sel:DWORD dst_unused:UNUSED_PAD src0_sel:WORD_1
	s_nop 0
	v_mul_f32_e32 v4, v27, v31
	v_fma_f32 v4, v26, v30, -v4
	v_mul_f32_e32 v5, v27, v30
	v_fma_f32 v5, v26, v31, v5
	v_cvt_f32_f16_e32 v30, v247
	v_cvt_f32_f16_sdwa v31, v247 dst_sel:DWORD dst_unused:UNUSED_PAD src0_sel:WORD_1
	s_nop 0
	v_mul_f32_e32 v6, v29, v31
	v_fma_f32 v6, v28, v30, -v6
	v_mul_f32_e32 v7, v29, v30
	v_fma_f32 v7, v28, v31, v7
	v_add_f32_e32 v8, v0, v4
	v_sub_f32_e32 v10, v0, v4
	v_add_f32_e32 v12, v2, v6
	v_sub_f32_e32 v20, v2, v6
	v_add_f32_e32 v9, v1, v5
	v_sub_f32_e32 v11, v1, v5
	v_add_f32_e32 v13, v3, v7
	v_sub_f32_e32 v21, v3, v7
	v_add_f32_e32 v0, v8, v12
	v_add_f32_e32 v1, v9, v13
	v_sub_f32_e32 v2, v10, v21
	v_add_f32_e32 v3, v11, v20
	v_sub_f32_e32 v4, v8, v12
	v_sub_f32_e32 v5, v9, v13
	v_add_f32_e32 v6, v10, v21
	v_sub_f32_e32 v7, v11, v20
	ds_write_b128 v222, v[0:3] offset:32768
	ds_write_b128 v222, v[4:7] offset:32784
	ds_read_b128 v[0:3], v222 offset:49152
	ds_read_b128 v[4:7], v222 offset:49168
	s_waitcnt vmcnt(0) lgkmcnt(0)
	v_add_f32_e32 v8, v0, v4
	v_sub_f32_e32 v10, v0, v4
	v_add_f32_e32 v12, v2, v6
	v_sub_f32_e32 v20, v2, v6
	v_add_f32_e32 v9, v1, v5
	v_sub_f32_e32 v11, v1, v5
	v_add_f32_e32 v13, v3, v7
	v_sub_f32_e32 v21, v3, v7
	v_add_f32_e32 v22, v8, v12
	v_add_f32_e32 v23, v9, v13
	v_sub_f32_e32 v26, v8, v12
	v_sub_f32_e32 v27, v9, v13
	v_add_f32_e32 v24, v10, v21
	v_sub_f32_e32 v25, v11, v20
	v_sub_f32_e32 v28, v10, v21
	v_add_f32_e32 v29, v11, v20
	v_cvt_f32_f16_e32 v30, v248
	v_cvt_f32_f16_sdwa v31, v248 dst_sel:DWORD dst_unused:UNUSED_PAD src0_sel:WORD_1
	s_nop 0
	v_mul_f32_e32 v0, v23, v31
	v_fma_f32 v0, v22, v30, -v0
	v_mul_f32_e32 v1, v23, v30
	v_fma_f32 v1, v22, v31, v1
	v_cvt_f32_f16_e32 v30, v249
	v_cvt_f32_f16_sdwa v31, v249 dst_sel:DWORD dst_unused:UNUSED_PAD src0_sel:WORD_1
	s_nop 0
	v_mul_f32_e32 v2, v25, v31
	v_fma_f32 v2, v24, v30, -v2
	v_mul_f32_e32 v3, v25, v30
	v_fma_f32 v3, v24, v31, v3
	v_cvt_f32_f16_e32 v30, v250
	v_cvt_f32_f16_sdwa v31, v250 dst_sel:DWORD dst_unused:UNUSED_PAD src0_sel:WORD_1
	s_nop 0
	v_mul_f32_e32 v4, v27, v31
	v_fma_f32 v4, v26, v30, -v4
	v_mul_f32_e32 v5, v27, v30
	v_fma_f32 v5, v26, v31, v5
	v_cvt_f32_f16_e32 v30, v251
	v_cvt_f32_f16_sdwa v31, v251 dst_sel:DWORD dst_unused:UNUSED_PAD src0_sel:WORD_1
	s_nop 0
	v_mul_f32_e32 v6, v29, v31
	v_fma_f32 v6, v28, v30, -v6
	v_mul_f32_e32 v7, v29, v30
	v_fma_f32 v7, v28, v31, v7
	v_add_f32_e32 v8, v0, v4
	v_sub_f32_e32 v10, v0, v4
	v_add_f32_e32 v12, v2, v6
	v_sub_f32_e32 v20, v2, v6
	v_add_f32_e32 v9, v1, v5
	v_sub_f32_e32 v11, v1, v5
	v_add_f32_e32 v13, v3, v7
	v_sub_f32_e32 v21, v3, v7
	v_add_f32_e32 v0, v8, v12
	v_add_f32_e32 v1, v9, v13
	v_sub_f32_e32 v2, v10, v21
	v_add_f32_e32 v3, v11, v20
	v_sub_f32_e32 v4, v8, v12
	v_sub_f32_e32 v5, v9, v13
	v_add_f32_e32 v6, v10, v21
	v_sub_f32_e32 v7, v11, v20
	ds_write_b128 v222, v[0:3] offset:49152
	ds_write_b128 v222, v[4:7] offset:49168
	s_add_u32 s98, s68, 0x8000
	s_addc_u32 s99, s69, 0
	global_load_dwordx4 v[236:239], v224, s[98:99]
	s_add_u32 s98, s68, 0xa000
	s_addc_u32 s99, s69, 0
	global_load_dwordx4 v[240:243], v224, s[98:99]
	s_add_u32 s98, s68, 0xc000
	s_addc_u32 s99, s69, 0
	global_load_dwordx4 v[244:247], v224, s[98:99]
	s_add_u32 s98, s68, 0xe000
	s_addc_u32 s99, s69, 0
	global_load_dwordx4 v[248:251], v224, s[98:99]
	ds_read_b128 v[0:3], v223 offset:0
	ds_read_b128 v[4:7], v223 offset:16
	s_waitcnt vmcnt(3) lgkmcnt(0)
	v_add_f32_e32 v8, v0, v4
	v_sub_f32_e32 v10, v0, v4
	v_add_f32_e32 v12, v2, v6
	v_sub_f32_e32 v20, v2, v6
	v_add_f32_e32 v9, v1, v5
	v_sub_f32_e32 v11, v1, v5
	v_add_f32_e32 v13, v3, v7
	v_sub_f32_e32 v21, v3, v7
	v_add_f32_e32 v22, v8, v12
	v_add_f32_e32 v23, v9, v13
	v_sub_f32_e32 v26, v8, v12
	v_sub_f32_e32 v27, v9, v13
	v_add_f32_e32 v24, v10, v21
	v_sub_f32_e32 v25, v11, v20
	v_sub_f32_e32 v28, v10, v21
	v_add_f32_e32 v29, v11, v20
	v_cvt_f32_f16_e32 v30, v236
	v_cvt_f32_f16_sdwa v31, v236 dst_sel:DWORD dst_unused:UNUSED_PAD src0_sel:WORD_1
	s_nop 0
	v_mul_f32_e32 v0, v23, v31
	v_fma_f32 v0, v22, v30, -v0
	v_mul_f32_e32 v1, v23, v30
	v_fma_f32 v1, v22, v31, v1
	v_cvt_f32_f16_e32 v30, v237
	v_cvt_f32_f16_sdwa v31, v237 dst_sel:DWORD dst_unused:UNUSED_PAD src0_sel:WORD_1
	s_nop 0
	v_mul_f32_e32 v2, v25, v31
	v_fma_f32 v2, v24, v30, -v2
	v_mul_f32_e32 v3, v25, v30
	v_fma_f32 v3, v24, v31, v3
	v_cvt_f32_f16_e32 v30, v238
	v_cvt_f32_f16_sdwa v31, v238 dst_sel:DWORD dst_unused:UNUSED_PAD src0_sel:WORD_1
	s_nop 0
	v_mul_f32_e32 v4, v27, v31
	v_fma_f32 v4, v26, v30, -v4
	v_mul_f32_e32 v5, v27, v30
	v_fma_f32 v5, v26, v31, v5
	v_cvt_f32_f16_e32 v30, v239
	v_cvt_f32_f16_sdwa v31, v239 dst_sel:DWORD dst_unused:UNUSED_PAD src0_sel:WORD_1
	s_nop 0
	v_mul_f32_e32 v6, v29, v31
	v_fma_f32 v6, v28, v30, -v6
	v_mul_f32_e32 v7, v29, v30
	v_fma_f32 v7, v28, v31, v7
	v_add_f32_e32 v8, v0, v4
	v_sub_f32_e32 v10, v0, v4
	v_add_f32_e32 v12, v2, v6
	v_sub_f32_e32 v20, v2, v6
	v_add_f32_e32 v9, v1, v5
	v_sub_f32_e32 v11, v1, v5
	v_add_f32_e32 v13, v3, v7
	v_sub_f32_e32 v21, v3, v7
	v_add_f32_e32 v0, v8, v12
	v_add_f32_e32 v1, v9, v13
	v_sub_f32_e32 v2, v10, v21
	v_add_f32_e32 v3, v11, v20
	v_sub_f32_e32 v4, v8, v12
	v_sub_f32_e32 v5, v9, v13
	v_add_f32_e32 v6, v10, v21
	v_sub_f32_e32 v7, v11, v20
	ds_write_b128 v223, v[0:3] offset:0
	ds_write_b128 v223, v[4:7] offset:16
	ds_read_b128 v[0:3], v223 offset:16384
	ds_read_b128 v[4:7], v223 offset:16400
	s_waitcnt vmcnt(2) lgkmcnt(0)
; HD float2 cmul(float2 a, float2 b){ return make_float2(a.x*b.x - a.y*b.y, a.x*b.y + a.y*b.x); }
; __device__ __forceinline__ void fft_mid(float2* Z, const f16x2* Hp, int tid){
;   _Pragma("unroll 4") for (int i=0;i<8;++i){ int base=(tid<<2)+i*2048;
;     u32x4 hw=*(const u32x4*)(Hp+base);
;     unsigned hw0=hw[0], hw1=hw[1], hw2=hw[2], hw3=hw[3];
;     float2 a0=Z[base], a1=Z[base+1], a2=Z[base+2], a3=Z[base+3];
;     float2 s02=make_float2(a0.x+a2.x,a0.y+a2.y), d02=make_float2(a0.x-a2.x,a0.y-a2.y);
;     float2 s13=make_float2(a1.x+a3.x,a1.y+a3.y), d13=make_float2(a1.x-a3.x,a1.y-a3.y);
;     float2 y0=make_float2(s02.x+s13.x,s02.y+s13.y), y2=make_float2(s02.x-s13.x,s02.y-s13.y);
;     float2 y1=make_float2(d02.x+d13.y,d02.y-d13.x);
;     float2 y3=make_float2(d02.x-d13.y,d02.y+d13.x);
;     f16x2 h0=__builtin_bit_cast(f16x2,hw0), h1=__builtin_bit_cast(f16x2,hw1), h2=__builtin_bit_cast(f16x2,hw2), h3=__builtin_bit_cast(f16x2,hw3);
;     float2 b0=cmul(y0,make_float2((float)h0[0],(float)h0[1])), b1=cmul(y1,make_float2((float)h1[0],(float)h1[1]));
;     float2 b2=cmul(y2,make_float2((float)h2[0],(float)h2[1])), b3=cmul(y3,make_float2((float)h3[0],(float)h3[1]));
;     float2 t02=make_float2(b0.x+b2.x,b0.y+b2.y), e02=make_float2(b0.x-b2.x,b0.y-b2.y);
;     float2 t13=make_float2(b1.x+b3.x,b1.y+b3.y), e13=make_float2(b1.x-b3.x,b1.y-b3.y);
;     Z[base]=make_float2(t02.x+t13.x,t02.y+t13.y); Z[base+2]=make_float2(t02.x-t13.x,t02.y-t13.y);
;     Z[base+1]=make_float2(e02.x-e13.y,e02.y+e13.x);
;     Z[base+3]=make_float2(e02.x+e13.y,e02.y-e13.x);
;   }
;   asm volatile("s_waitcnt lgkmcnt(0)" ::: "memory");
	v_add_f32_e32 v8, v0, v4
	v_sub_f32_e32 v10, v0, v4
	v_add_f32_e32 v12, v2, v6
	v_sub_f32_e32 v20, v2, v6
	v_add_f32_e32 v9, v1, v5
	v_sub_f32_e32 v11, v1, v5
	v_add_f32_e32 v13, v3, v7
	v_sub_f32_e32 v21, v3, v7
	v_add_f32_e32 v22, v8, v12
	v_add_f32_e32 v23, v9, v13
	v_sub_f32_e32 v26, v8, v12
	v_sub_f32_e32 v27, v9, v13
	v_add_f32_e32 v24, v10, v21
	v_sub_f32_e32 v25, v11, v20
	v_sub_f32_e32 v28, v10, v21
	v_add_f32_e32 v29, v11, v20
	v_cvt_f32_f16_e32 v30, v240
	v_cvt_f32_f16_sdwa v31, v240 dst_sel:DWORD dst_unused:UNUSED_PAD src0_sel:WORD_1
	s_nop 0
	v_mul_f32_e32 v0, v23, v31
	v_fma_f32 v0, v22, v30, -v0
	v_mul_f32_e32 v1, v23, v30
	v_fma_f32 v1, v22, v31, v1
	v_cvt_f32_f16_e32 v30, v241
	v_cvt_f32_f16_sdwa v31, v241 dst_sel:DWORD dst_unused:UNUSED_PAD src0_sel:WORD_1
	s_nop 0
	v_mul_f32_e32 v2, v25, v31
	v_fma_f32 v2, v24, v30, -v2
	v_mul_f32_e32 v3, v25, v30
	v_fma_f32 v3, v24, v31, v3
	v_cvt_f32_f16_e32 v30, v242
	v_cvt_f32_f16_sdwa v31, v242 dst_sel:DWORD dst_unused:UNUSED_PAD src0_sel:WORD_1
	s_nop 0
	v_mul_f32_e32 v4, v27, v31
	v_fma_f32 v4, v26, v30, -v4
	v_mul_f32_e32 v5, v27, v30
	v_fma_f32 v5, v26, v31, v5
	v_cvt_f32_f16_e32 v30, v243
	v_cvt_f32_f16_sdwa v31, v243 dst_sel:DWORD dst_unused:UNUSED_PAD src0_sel:WORD_1
	s_nop 0
	v_mul_f32_e32 v6, v29, v31
	v_fma_f32 v6, v28, v30, -v6
	v_mul_f32_e32 v7, v29, v30
	v_fma_f32 v7, v28, v31, v7
	v_add_f32_e32 v8, v0, v4
	v_sub_f32_e32 v10, v0, v4
	v_add_f32_e32 v12, v2, v6
	v_sub_f32_e32 v20, v2, v6
	v_add_f32_e32 v9, v1, v5
	v_sub_f32_e32 v11, v1, v5
	v_add_f32_e32 v13, v3, v7
	v_sub_f32_e32 v21, v3, v7
	v_add_f32_e32 v0, v8, v12
	v_add_f32_e32 v1, v9, v13
	v_sub_f32_e32 v2, v10, v21
	v_add_f32_e32 v3, v11, v20
	v_sub_f32_e32 v4, v8, v12
	v_sub_f32_e32 v5, v9, v13
	v_add_f32_e32 v6, v10, v21
	v_sub_f32_e32 v7, v11, v20
	ds_write_b128 v223, v[0:3] offset:16384
	ds_write_b128 v223, v[4:7] offset:16400
	ds_read_b128 v[0:3], v223 offset:32768
	ds_read_b128 v[4:7], v223 offset:32784
	s_waitcnt vmcnt(1) lgkmcnt(0)
	v_add_f32_e32 v8, v0, v4
	v_sub_f32_e32 v10, v0, v4
	v_add_f32_e32 v12, v2, v6
	v_sub_f32_e32 v20, v2, v6
	v_add_f32_e32 v9, v1, v5
	v_sub_f32_e32 v11, v1, v5
	v_add_f32_e32 v13, v3, v7
	v_sub_f32_e32 v21, v3, v7
	v_add_f32_e32 v22, v8, v12
	v_add_f32_e32 v23, v9, v13
	v_sub_f32_e32 v26, v8, v12
	v_sub_f32_e32 v27, v9, v13
	v_add_f32_e32 v24, v10, v21
	v_sub_f32_e32 v25, v11, v20
	v_sub_f32_e32 v28, v10, v21
	v_add_f32_e32 v29, v11, v20
	v_cvt_f32_f16_e32 v30, v244
	v_cvt_f32_f16_sdwa v31, v244 dst_sel:DWORD dst_unused:UNUSED_PAD src0_sel:WORD_1
	s_nop 0
	v_mul_f32_e32 v0, v23, v31
	v_fma_f32 v0, v22, v30, -v0
	v_mul_f32_e32 v1, v23, v30
	v_fma_f32 v1, v22, v31, v1
	v_cvt_f32_f16_e32 v30, v245
	v_cvt_f32_f16_sdwa v31, v245 dst_sel:DWORD dst_unused:UNUSED_PAD src0_sel:WORD_1
	s_nop 0
	v_mul_f32_e32 v2, v25, v31
	v_fma_f32 v2, v24, v30, -v2
	v_mul_f32_e32 v3, v25, v30
	v_fma_f32 v3, v24, v31, v3
	v_cvt_f32_f16_e32 v30, v246
	v_cvt_f32_f16_sdwa v31, v246 dst_sel:DWORD dst_unused:UNUSED_PAD src0_sel:WORD_1
	s_nop 0
	v_mul_f32_e32 v4, v27, v31
	v_fma_f32 v4, v26, v30, -v4
	v_mul_f32_e32 v5, v27, v30
	v_fma_f32 v5, v26, v31, v5
	v_cvt_f32_f16_e32 v30, v247
	v_cvt_f32_f16_sdwa v31, v247 dst_sel:DWORD dst_unused:UNUSED_PAD src0_sel:WORD_1
	s_nop 0
	v_mul_f32_e32 v6, v29, v31
	v_fma_f32 v6, v28, v30, -v6
	v_mul_f32_e32 v7, v29, v30
	v_fma_f32 v7, v28, v31, v7
	v_add_f32_e32 v8, v0, v4
	v_sub_f32_e32 v10, v0, v4
	v_add_f32_e32 v12, v2, v6
	v_sub_f32_e32 v20, v2, v6
	v_add_f32_e32 v9, v1, v5
	v_sub_f32_e32 v11, v1, v5
	v_add_f32_e32 v13, v3, v7
	v_sub_f32_e32 v21, v3, v7
	v_add_f32_e32 v0, v8, v12
	v_add_f32_e32 v1, v9, v13
	v_sub_f32_e32 v2, v10, v21
	v_add_f32_e32 v3, v11, v20
	v_sub_f32_e32 v4, v8, v12
	v_sub_f32_e32 v5, v9, v13
	v_add_f32_e32 v6, v10, v21
	v_sub_f32_e32 v7, v11, v20
	ds_write_b128 v223, v[0:3] offset:32768
	ds_write_b128 v223, v[4:7] offset:32784
	ds_read_b128 v[0:3], v223 offset:49152
	ds_read_b128 v[4:7], v223 offset:49168
	s_waitcnt vmcnt(0) lgkmcnt(0)
	v_add_f32_e32 v8, v0, v4
	v_sub_f32_e32 v10, v0, v4
	v_add_f32_e32 v12, v2, v6
	v_sub_f32_e32 v20, v2, v6
	v_add_f32_e32 v9, v1, v5
	v_sub_f32_e32 v11, v1, v5
	v_add_f32_e32 v13, v3, v7
	v_sub_f32_e32 v21, v3, v7
	v_add_f32_e32 v22, v8, v12
	v_add_f32_e32 v23, v9, v13
	v_sub_f32_e32 v26, v8, v12
	v_sub_f32_e32 v27, v9, v13
	v_add_f32_e32 v24, v10, v21
	v_sub_f32_e32 v25, v11, v20
	v_sub_f32_e32 v28, v10, v21
	v_add_f32_e32 v29, v11, v20
	v_cvt_f32_f16_e32 v30, v248
	v_cvt_f32_f16_sdwa v31, v248 dst_sel:DWORD dst_unused:UNUSED_PAD src0_sel:WORD_1
	s_nop 0
	v_mul_f32_e32 v0, v23, v31
	v_fma_f32 v0, v22, v30, -v0
	v_mul_f32_e32 v1, v23, v30
	v_fma_f32 v1, v22, v31, v1
	v_cvt_f32_f16_e32 v30, v249
	v_cvt_f32_f16_sdwa v31, v249 dst_sel:DWORD dst_unused:UNUSED_PAD src0_sel:WORD_1
	s_nop 0
	v_mul_f32_e32 v2, v25, v31
	v_fma_f32 v2, v24, v30, -v2
	v_mul_f32_e32 v3, v25, v30
	v_fma_f32 v3, v24, v31, v3
	v_cvt_f32_f16_e32 v30, v250
	v_cvt_f32_f16_sdwa v31, v250 dst_sel:DWORD dst_unused:UNUSED_PAD src0_sel:WORD_1
	s_nop 0
	v_mul_f32_e32 v4, v27, v31
	v_fma_f32 v4, v26, v30, -v4
	v_mul_f32_e32 v5, v27, v30
	v_fma_f32 v5, v26, v31, v5
	v_cvt_f32_f16_e32 v30, v251
	v_cvt_f32_f16_sdwa v31, v251 dst_sel:DWORD dst_unused:UNUSED_PAD src0_sel:WORD_1
	s_nop 0
	v_mul_f32_e32 v6, v29, v31
	v_fma_f32 v6, v28, v30, -v6
	v_mul_f32_e32 v7, v29, v30
	v_fma_f32 v7, v28, v31, v7
	v_add_f32_e32 v8, v0, v4
	v_sub_f32_e32 v10, v0, v4
	v_add_f32_e32 v12, v2, v6
	v_sub_f32_e32 v20, v2, v6
	v_add_f32_e32 v9, v1, v5
	v_sub_f32_e32 v11, v1, v5
	v_add_f32_e32 v13, v3, v7
	v_sub_f32_e32 v21, v3, v7
	v_add_f32_e32 v0, v8, v12
	v_add_f32_e32 v1, v9, v13
	v_sub_f32_e32 v2, v10, v21
	v_add_f32_e32 v3, v11, v20
	v_sub_f32_e32 v4, v8, v12
	v_sub_f32_e32 v5, v9, v13
	v_add_f32_e32 v6, v10, v21
	v_sub_f32_e32 v7, v11, v20
	ds_write_b128 v223, v[0:3] offset:49152
	ds_write_b128 v223, v[4:7] offset:49168
	s_waitcnt lgkmcnt(0)
	s_mov_b64 s[18:19], 0x8000
	v_lshlrev_b32_e32 v232, 4, v154
	s_lshl_b32 s100, s90, 15
	v_add_u32_e32 v233, 0x2000, v232
	v_add_u32_e32 v234, 0x4000, v232
	v_add_u32_e32 v235, 0x6000, v232
	s_add_u32 s98, s70, 0x42bd000
	s_addc_u32 s99, s71, 0
	s_add_u32 s98, s98, s100
	s_addc_u32 s99, s99, 0
	s_cmp_eq_u32 s89, 1
	s_cbranch_scc1 .Lmy_pf_st1
	s_add_u32 s98, s98, 0x2000000
	s_addc_u32 s99, s99, 0
; HD float2 cmul(float2 a, float2 b){ return make_float2(a.x*b.x - a.y*b.y, a.x*b.y + a.y*b.x); }
; HD float2 cmulc(float2 a, float2 b){ return make_float2(a.x*b.x + a.y*b.y, a.y*b.x - a.x*b.y); }
; template<bool INV, bool NOTW>
; HD void bf4c(float2* Z, int i0, int i1, int i2, int i3, float2 w1, float2 w2, float2 w3){
;   float2 a0=Z[i0], a1=Z[i1], a2=Z[i2], a3=Z[i3];
;   if (INV && !NOTW){ a1=cmulc(a1,w1); a2=cmulc(a2,w2); a3=cmulc(a3,w3); }
;   float2 s02=make_float2(a0.x+a2.x,a0.y+a2.y), d02=make_float2(a0.x-a2.x,a0.y-a2.y);
;   float2 s13=make_float2(a1.x+a3.x,a1.y+a3.y), d13=make_float2(a1.x-a3.x,a1.y-a3.y);
;   float2 y0=make_float2(s02.x+s13.x,s02.y+s13.y), y2=make_float2(s02.x-s13.x,s02.y-s13.y);
;   float2 ym=make_float2(d02.x+d13.y,d02.y-d13.x);
;   float2 yp=make_float2(d02.x-d13.y,d02.y+d13.x);
;   float2 y1, y3;
;   if (INV){ y1=yp; y3=ym; } else if (NOTW){ y1=ym; y3=yp; } else { y1=cmul(ym,w1); y2=cmul(y2,w2); y3=cmul(yp,w3); }
;   Z[i0]=y0; Z[i1]=y1; Z[i2]=y2; Z[i3]=y3;
; }
; template<bool INV, int LQ, bool BARRIER=true>
; HD void fft_pass(float2* Z, const float2* twA, const float2* twB, int tid){
;     ...
;   } else {
;     int j=tid&(q-1); int base0=((tid>>LQ)<<(LQ+2))+j;
;     float2 w1=make_float2(1.f,0.f), w2=w1, w3=w1;
;     if (LQ>0){ int k=j*tws; w1=cmul(twA[k>>6],twB[k&63]); w2=cmul(w1,w1); w3=cmul(w2,w1); }
;     _Pragma("unroll") for (int i=0;i<8;++i){ int base=base0+i*2048; bf4c<INV,(LQ==0)>(Z,base,base+q,base+2*q,base+3*q,w1,w2,w3); }
;   }
;   if (BARRIER) __syncthreads(); else asm volatile("s_waitcnt lgkmcnt(0)" ::: "memory");
.Lmy_pf_st1:
	global_load_dwordx4 v[228:231], v232, s[98:99]
	global_load_dwordx4 v[228:231], v233, s[98:99]
	global_load_dwordx4 v[228:231], v234, s[98:99]
	global_load_dwordx4 v[228:231], v235, s[98:99]
	s_add_u32 s98, s98, 0x1000000
	s_addc_u32 s99, s99, 0
	global_load_dwordx4 v[228:231], v232, s[98:99]
	global_load_dwordx4 v[228:231], v233, s[98:99]
	global_load_dwordx4 v[228:231], v234, s[98:99]
	global_load_dwordx4 v[228:231], v235, s[98:99]
	s_waitcnt lgkmcnt(0)
	v_and_b32_e32 v226, 3, v154
	v_lshlrev_b32_e32 v224, 7, v226
	v_add_u32_e32 v224, 0x20800, v224
	v_mov_b32_e32 v225, 0x20a00
	ds_read_b64 v[238:239], v224
	ds_read_b64 v[240:241], v225
	s_waitcnt lgkmcnt(0)
	v_pk_mul_f32 v[30:31], v[238:239], v[240:241] op_sel:[1,1] op_sel_hi:[1,0]
	v_pk_fma_f32 v[16:17], v[238:239], v[240:241], v[30:31] op_sel:[0,0,0] op_sel_hi:[0,1,1] neg_lo:[0,0,1]
	v_pk_mul_f32 v[30:31], v[16:17], v[16:17] op_sel:[1,1] op_sel_hi:[1,0]
	v_pk_fma_f32 v[18:19], v[16:17], v[16:17], v[30:31] op_sel:[0,0,0] op_sel_hi:[0,1,1] neg_lo:[0,0,1]
	v_pk_mul_f32 v[30:31], v[18:19], v[16:17] op_sel:[1,1] op_sel_hi:[1,0]
	v_pk_fma_f32 v[20:21], v[18:19], v[16:17], v[30:31] op_sel:[0,0,0] op_sel_hi:[0,1,1] neg_lo:[0,0,1]
	v_lshrrev_b32_e32 v222, 2, v154
	v_lshlrev_b32_e32 v222, 4, v222
	v_add_u32_e32 v222, v222, v226
	v_lshlrev_b32_e32 v222, 3, v222
	v_add_u32_e32 v223, 0x10000, v222
	ds_read_b64 v[0:1], v222 offset:0
	ds_read_b64 v[2:3], v222 offset:32
	ds_read_b64 v[4:5], v222 offset:64
	ds_read_b64 v[6:7], v222 offset:96
	ds_read_b64 v[8:9], v222 offset:16384
	ds_read_b64 v[10:11], v222 offset:16416
	ds_read_b64 v[12:13], v222 offset:16448
	ds_read_b64 v[14:15], v222 offset:16480
	s_waitcnt lgkmcnt(4)
	v_pk_mul_f32 v[30:31], v[4:5], v[18:19] op_sel:[1,1] op_sel_hi:[0,1]
	v_pk_fma_f32 v[244:245], v[4:5], v[18:19], v[30:31] op_sel:[0,0,0] op_sel_hi:[1,0,1] neg_hi:[0,0,1]
	v_pk_mul_f32 v[30:31], v[2:3], v[16:17] op_sel:[1,1] op_sel_hi:[0,1]
	v_pk_fma_f32 v[242:243], v[2:3], v[16:17], v[30:31] op_sel:[0,0,0] op_sel_hi:[1,0,1] neg_hi:[0,0,1]
	v_pk_mul_f32 v[30:31], v[6:7], v[20:21] op_sel:[1,1] op_sel_hi:[0,1]
	v_pk_fma_f32 v[246:247], v[6:7], v[20:21], v[30:31] op_sel:[0,0,0] op_sel_hi:[1,0,1] neg_hi:[0,0,1]
	v_pk_add_f32 v[22:23], v[0:1], v[244:245]
	v_pk_add_f32 v[24:25], v[0:1], v[244:245] neg_lo:[0,1] neg_hi:[0,1]
	v_pk_add_f32 v[26:27], v[242:243], v[246:247]
	v_pk_add_f32 v[28:29], v[242:243], v[246:247] neg_lo:[0,1] neg_hi:[0,1]
	v_pk_add_f32 v[80:81], v[22:23], v[26:27]
	ds_write_b64 v222, v[80:81] offset:0
	v_pk_add_f32 v[82:83], v[24:25], v[28:29] op_sel:[0,1] op_sel_hi:[1,0] neg_lo:[0,1]
	ds_write_b64 v222, v[82:83] offset:32
	v_pk_add_f32 v[84:85], v[22:23], v[26:27] neg_lo:[0,1] neg_hi:[0,1]
	ds_write_b64 v222, v[84:85] offset:64
	v_pk_add_f32 v[236:237], v[24:25], v[28:29] op_sel:[0,1] op_sel_hi:[1,0] neg_hi:[0,1]
	ds_write_b64 v222, v[236:237] offset:96
	ds_read_b64 v[0:1], v222 offset:32768
	ds_read_b64 v[2:3], v222 offset:32800
	ds_read_b64 v[4:5], v222 offset:32832
	ds_read_b64 v[6:7], v222 offset:32864
	s_waitcnt lgkmcnt(8)
	v_pk_mul_f32 v[30:31], v[12:13], v[18:19] op_sel:[1,1] op_sel_hi:[0,1]
	v_pk_fma_f32 v[244:245], v[12:13], v[18:19], v[30:31] op_sel:[0,0,0] op_sel_hi:[1,0,1] neg_hi:[0,0,1]
	v_pk_mul_f32 v[30:31], v[10:11], v[16:17] op_sel:[1,1] op_sel_hi:[0,1]
	v_pk_fma_f32 v[242:243], v[10:11], v[16:17], v[30:31] op_sel:[0,0,0] op_sel_hi:[1,0,1] neg_hi:[0,0,1]
	v_pk_mul_f32 v[30:31], v[14:15], v[20:21] op_sel:[1,1] op_sel_hi:[0,1]
	v_pk_fma_f32 v[246:247], v[14:15], v[20:21], v[30:31] op_sel:[0,0,0] op_sel_hi:[1,0,1] neg_hi:[0,0,1]
	v_pk_add_f32 v[22:23], v[8:9], v[244:245]
	v_pk_add_f32 v[24:25], v[8:9], v[244:245] neg_lo:[0,1] neg_hi:[0,1]
	v_pk_add_f32 v[26:27], v[242:243], v[246:247]
	v_pk_add_f32 v[28:29], v[242:243], v[246:247] neg_lo:[0,1] neg_hi:[0,1]
	v_pk_add_f32 v[80:81], v[22:23], v[26:27]
	ds_write_b64 v222, v[80:81] offset:16384
	v_pk_add_f32 v[82:83], v[24:25], v[28:29] op_sel:[0,1] op_sel_hi:[1,0] neg_lo:[0,1]
	ds_write_b64 v222, v[82:83] offset:16416
	v_pk_add_f32 v[84:85], v[22:23], v[26:27] neg_lo:[0,1] neg_hi:[0,1]
	ds_write_b64 v222, v[84:85] offset:16448
	v_pk_add_f32 v[236:237], v[24:25], v[28:29] op_sel:[0,1] op_sel_hi:[1,0] neg_hi:[0,1]
	ds_write_b64 v222, v[236:237] offset:16480
	ds_read_b64 v[8:9], v222 offset:49152
	ds_read_b64 v[10:11], v222 offset:49184
	ds_read_b64 v[12:13], v222 offset:49216
	ds_read_b64 v[14:15], v222 offset:49248
	s_waitcnt lgkmcnt(8)
	v_pk_mul_f32 v[30:31], v[4:5], v[18:19] op_sel:[1,1] op_sel_hi:[0,1]
	v_pk_fma_f32 v[244:245], v[4:5], v[18:19], v[30:31] op_sel:[0,0,0] op_sel_hi:[1,0,1] neg_hi:[0,0,1]
	v_pk_mul_f32 v[30:31], v[2:3], v[16:17] op_sel:[1,1] op_sel_hi:[0,1]
	v_pk_fma_f32 v[242:243], v[2:3], v[16:17], v[30:31] op_sel:[0,0,0] op_sel_hi:[1,0,1] neg_hi:[0,0,1]
	v_pk_mul_f32 v[30:31], v[6:7], v[20:21] op_sel:[1,1] op_sel_hi:[0,1]
	v_pk_fma_f32 v[246:247], v[6:7], v[20:21], v[30:31] op_sel:[0,0,0] op_sel_hi:[1,0,1] neg_hi:[0,0,1]
	v_pk_add_f32 v[22:23], v[0:1], v[244:245]
	v_pk_add_f32 v[24:25], v[0:1], v[244:245] neg_lo:[0,1] neg_hi:[0,1]
	v_pk_add_f32 v[26:27], v[242:243], v[246:247]
	v_pk_add_f32 v[28:29], v[242:243], v[246:247] neg_lo:[0,1] neg_hi:[0,1]
	v_pk_add_f32 v[80:81], v[22:23], v[26:27]
	ds_write_b64 v222, v[80:81] offset:32768
	v_pk_add_f32 v[82:83], v[24:25], v[28:29] op_sel:[0,1] op_sel_hi:[1,0] neg_lo:[0,1]
	ds_write_b64 v222, v[82:83] offset:32800
	v_pk_add_f32 v[84:85], v[22:23], v[26:27] neg_lo:[0,1] neg_hi:[0,1]
	ds_write_b64 v222, v[84:85] offset:32832
	v_pk_add_f32 v[236:237], v[24:25], v[28:29] op_sel:[0,1] op_sel_hi:[1,0] neg_hi:[0,1]
	ds_write_b64 v222, v[236:237] offset:32864
	ds_read_b64 v[0:1], v223 offset:0
	ds_read_b64 v[2:3], v223 offset:32
	ds_read_b64 v[4:5], v223 offset:64
	ds_read_b64 v[6:7], v223 offset:96
	s_waitcnt lgkmcnt(8)
; HD float2 cmul(float2 a, float2 b){ return make_float2(a.x*b.x - a.y*b.y, a.x*b.y + a.y*b.x); }
; HD float2 cmulc(float2 a, float2 b){ return make_float2(a.x*b.x + a.y*b.y, a.y*b.x - a.x*b.y); }
; template<bool INV, bool NOTW>
; HD void bf4c(float2* Z, int i0, int i1, int i2, int i3, float2 w1, float2 w2, float2 w3){
;   float2 a0=Z[i0], a1=Z[i1], a2=Z[i2], a3=Z[i3];
;   if (INV && !NOTW){ a1=cmulc(a1,w1); a2=cmulc(a2,w2); a3=cmulc(a3,w3); }
;   float2 s02=make_float2(a0.x+a2.x,a0.y+a2.y), d02=make_float2(a0.x-a2.x,a0.y-a2.y);
;   float2 s13=make_float2(a1.x+a3.x,a1.y+a3.y), d13=make_float2(a1.x-a3.x,a1.y-a3.y);
;   float2 y0=make_float2(s02.x+s13.x,s02.y+s13.y), y2=make_float2(s02.x-s13.x,s02.y-s13.y);
;   float2 ym=make_float2(d02.x+d13.y,d02.y-d13.x);
;   float2 yp=make_float2(d02.x-d13.y,d02.y+d13.x);
;   float2 y1, y3;
;   if (INV){ y1=yp; y3=ym; } else if (NOTW){ y1=ym; y3=yp; } else { y1=cmul(ym,w1); y2=cmul(y2,w2); y3=cmul(yp,w3); }
;   Z[i0]=y0; Z[i1]=y1; Z[i2]=y2; Z[i3]=y3;
; }
; template<bool INV, int LQ, bool BARRIER=true>
; HD void fft_pass(float2* Z, const float2* twA, const float2* twB, int tid){
;     ...
;   } else {
;     int j=tid&(q-1); int base0=((tid>>LQ)<<(LQ+2))+j;
;     float2 w1=make_float2(1.f,0.f), w2=w1, w3=w1;
;     if (LQ>0){ int k=j*tws; w1=cmul(twA[k>>6],twB[k&63]); w2=cmul(w1,w1); w3=cmul(w2,w1); }
;     _Pragma("unroll") for (int i=0;i<8;++i){ int base=base0+i*2048; bf4c<INV,(LQ==0)>(Z,base,base+q,base+2*q,base+3*q,w1,w2,w3); }
;   }
	v_pk_mul_f32 v[30:31], v[12:13], v[18:19] op_sel:[1,1] op_sel_hi:[0,1]
	v_pk_fma_f32 v[244:245], v[12:13], v[18:19], v[30:31] op_sel:[0,0,0] op_sel_hi:[1,0,1] neg_hi:[0,0,1]
	v_pk_mul_f32 v[30:31], v[10:11], v[16:17] op_sel:[1,1] op_sel_hi:[0,1]
	v_pk_fma_f32 v[242:243], v[10:11], v[16:17], v[30:31] op_sel:[0,0,0] op_sel_hi:[1,0,1] neg_hi:[0,0,1]
	v_pk_mul_f32 v[30:31], v[14:15], v[20:21] op_sel:[1,1] op_sel_hi:[0,1]
	v_pk_fma_f32 v[246:247], v[14:15], v[20:21], v[30:31] op_sel:[0,0,0] op_sel_hi:[1,0,1] neg_hi:[0,0,1]
	v_pk_add_f32 v[22:23], v[8:9], v[244:245]
	v_pk_add_f32 v[24:25], v[8:9], v[244:245] neg_lo:[0,1] neg_hi:[0,1]
	v_pk_add_f32 v[26:27], v[242:243], v[246:247]
	v_pk_add_f32 v[28:29], v[242:243], v[246:247] neg_lo:[0,1] neg_hi:[0,1]
	v_pk_add_f32 v[80:81], v[22:23], v[26:27]
	ds_write_b64 v222, v[80:81] offset:49152
	v_pk_add_f32 v[82:83], v[24:25], v[28:29] op_sel:[0,1] op_sel_hi:[1,0] neg_lo:[0,1]
	ds_write_b64 v222, v[82:83] offset:49184
	v_pk_add_f32 v[84:85], v[22:23], v[26:27] neg_lo:[0,1] neg_hi:[0,1]
	ds_write_b64 v222, v[84:85] offset:49216
	v_pk_add_f32 v[236:237], v[24:25], v[28:29] op_sel:[0,1] op_sel_hi:[1,0] neg_hi:[0,1]
	ds_write_b64 v222, v[236:237] offset:49248
	ds_read_b64 v[8:9], v223 offset:16384
	ds_read_b64 v[10:11], v223 offset:16416
	ds_read_b64 v[12:13], v223 offset:16448
	ds_read_b64 v[14:15], v223 offset:16480
	s_waitcnt lgkmcnt(8)
	v_pk_mul_f32 v[30:31], v[4:5], v[18:19] op_sel:[1,1] op_sel_hi:[0,1]
	v_pk_fma_f32 v[244:245], v[4:5], v[18:19], v[30:31] op_sel:[0,0,0] op_sel_hi:[1,0,1] neg_hi:[0,0,1]
	v_pk_mul_f32 v[30:31], v[2:3], v[16:17] op_sel:[1,1] op_sel_hi:[0,1]
	v_pk_fma_f32 v[242:243], v[2:3], v[16:17], v[30:31] op_sel:[0,0,0] op_sel_hi:[1,0,1] neg_hi:[0,0,1]
	v_pk_mul_f32 v[30:31], v[6:7], v[20:21] op_sel:[1,1] op_sel_hi:[0,1]
	v_pk_fma_f32 v[246:247], v[6:7], v[20:21], v[30:31] op_sel:[0,0,0] op_sel_hi:[1,0,1] neg_hi:[0,0,1]
	v_pk_add_f32 v[22:23], v[0:1], v[244:245]
	v_pk_add_f32 v[24:25], v[0:1], v[244:245] neg_lo:[0,1] neg_hi:[0,1]
	v_pk_add_f32 v[26:27], v[242:243], v[246:247]
	v_pk_add_f32 v[28:29], v[242:243], v[246:247] neg_lo:[0,1] neg_hi:[0,1]
	v_pk_add_f32 v[80:81], v[22:23], v[26:27]
	ds_write_b64 v223, v[80:81] offset:0
	v_pk_add_f32 v[82:83], v[24:25], v[28:29] op_sel:[0,1] op_sel_hi:[1,0] neg_lo:[0,1]
	ds_write_b64 v223, v[82:83] offset:32
	v_pk_add_f32 v[84:85], v[22:23], v[26:27] neg_lo:[0,1] neg_hi:[0,1]
	ds_write_b64 v223, v[84:85] offset:64
	v_pk_add_f32 v[236:237], v[24:25], v[28:29] op_sel:[0,1] op_sel_hi:[1,0] neg_hi:[0,1]
	ds_write_b64 v223, v[236:237] offset:96
	ds_read_b64 v[0:1], v223 offset:32768
	ds_read_b64 v[2:3], v223 offset:32800
	ds_read_b64 v[4:5], v223 offset:32832
	ds_read_b64 v[6:7], v223 offset:32864
	s_waitcnt lgkmcnt(8)
	v_pk_mul_f32 v[30:31], v[12:13], v[18:19] op_sel:[1,1] op_sel_hi:[0,1]
	v_pk_fma_f32 v[244:245], v[12:13], v[18:19], v[30:31] op_sel:[0,0,0] op_sel_hi:[1,0,1] neg_hi:[0,0,1]
	v_pk_mul_f32 v[30:31], v[10:11], v[16:17] op_sel:[1,1] op_sel_hi:[0,1]
	v_pk_fma_f32 v[242:243], v[10:11], v[16:17], v[30:31] op_sel:[0,0,0] op_sel_hi:[1,0,1] neg_hi:[0,0,1]
	v_pk_mul_f32 v[30:31], v[14:15], v[20:21] op_sel:[1,1] op_sel_hi:[0,1]
	v_pk_fma_f32 v[246:247], v[14:15], v[20:21], v[30:31] op_sel:[0,0,0] op_sel_hi:[1,0,1] neg_hi:[0,0,1]
	v_pk_add_f32 v[22:23], v[8:9], v[244:245]
	v_pk_add_f32 v[24:25], v[8:9], v[244:245] neg_lo:[0,1] neg_hi:[0,1]
	v_pk_add_f32 v[26:27], v[242:243], v[246:247]
	v_pk_add_f32 v[28:29], v[242:243], v[246:247] neg_lo:[0,1] neg_hi:[0,1]
	v_pk_add_f32 v[80:81], v[22:23], v[26:27]
	ds_write_b64 v223, v[80:81] offset:16384
	v_pk_add_f32 v[82:83], v[24:25], v[28:29] op_sel:[0,1] op_sel_hi:[1,0] neg_lo:[0,1]
	ds_write_b64 v223, v[82:83] offset:16416
	v_pk_add_f32 v[84:85], v[22:23], v[26:27] neg_lo:[0,1] neg_hi:[0,1]
	ds_write_b64 v223, v[84:85] offset:16448
	v_pk_add_f32 v[236:237], v[24:25], v[28:29] op_sel:[0,1] op_sel_hi:[1,0] neg_hi:[0,1]
	ds_write_b64 v223, v[236:237] offset:16480
	ds_read_b64 v[8:9], v223 offset:49152
	ds_read_b64 v[10:11], v223 offset:49184
	ds_read_b64 v[12:13], v223 offset:49216
	ds_read_b64 v[14:15], v223 offset:49248
	s_waitcnt lgkmcnt(8)
	v_pk_mul_f32 v[30:31], v[4:5], v[18:19] op_sel:[1,1] op_sel_hi:[0,1]
	v_pk_fma_f32 v[244:245], v[4:5], v[18:19], v[30:31] op_sel:[0,0,0] op_sel_hi:[1,0,1] neg_hi:[0,0,1]
	v_pk_mul_f32 v[30:31], v[2:3], v[16:17] op_sel:[1,1] op_sel_hi:[0,1]
	v_pk_fma_f32 v[242:243], v[2:3], v[16:17], v[30:31] op_sel:[0,0,0] op_sel_hi:[1,0,1] neg_hi:[0,0,1]
	v_pk_mul_f32 v[30:31], v[6:7], v[20:21] op_sel:[1,1] op_sel_hi:[0,1]
	v_pk_fma_f32 v[246:247], v[6:7], v[20:21], v[30:31] op_sel:[0,0,0] op_sel_hi:[1,0,1] neg_hi:[0,0,1]
	v_pk_add_f32 v[22:23], v[0:1], v[244:245]
	v_pk_add_f32 v[24:25], v[0:1], v[244:245] neg_lo:[0,1] neg_hi:[0,1]
	v_pk_add_f32 v[26:27], v[242:243], v[246:247]
	v_pk_add_f32 v[28:29], v[242:243], v[246:247] neg_lo:[0,1] neg_hi:[0,1]
	v_pk_add_f32 v[80:81], v[22:23], v[26:27]
	ds_write_b64 v223, v[80:81] offset:32768
	v_pk_add_f32 v[82:83], v[24:25], v[28:29] op_sel:[0,1] op_sel_hi:[1,0] neg_lo:[0,1]
	ds_write_b64 v223, v[82:83] offset:32800
	v_pk_add_f32 v[84:85], v[22:23], v[26:27] neg_lo:[0,1] neg_hi:[0,1]
	ds_write_b64 v223, v[84:85] offset:32832
	v_pk_add_f32 v[236:237], v[24:25], v[28:29] op_sel:[0,1] op_sel_hi:[1,0] neg_hi:[0,1]
	ds_write_b64 v223, v[236:237] offset:32864
	s_waitcnt lgkmcnt(4)
; HD float2 cmul(float2 a, float2 b){ return make_float2(a.x*b.x - a.y*b.y, a.x*b.y + a.y*b.x); }
; template<bool INV, int LQ, bool BARRIER=true>
; HD void fft_pass(float2* Z, const float2* twA, const float2* twB, int tid){
;     ...
;     int j=tid&(q-1); int base0=((tid>>LQ)<<(LQ+2))+j;
;     float2 w1=make_float2(1.f,0.f), w2=w1, w3=w1;
;     if (LQ>0){ int k=j*tws; w1=cmul(twA[k>>6],twB[k&63]); w2=cmul(w1,w1); w3=cmul(w2,w1); }
;     _Pragma("unroll") for (int i=0;i<8;++i){ int base=base0+i*2048; bf4c<INV,(LQ==0)>(Z,base,base+q,base+2*q,base+3*q,w1,w2,w3); }
;   }
;   if (BARRIER) __syncthreads(); else asm volatile("s_waitcnt lgkmcnt(0)" ::: "memory");
; __device__ __forceinline__ void fft_inv_tail(float2* Z, const float2* twA, const float2* twB, int tid){
;   fft_pass<true,2,false>(Z,twA,twB,tid); fft_pass<true,4,false>(Z,twA,twB,tid); fft_pass<true,6>(Z,twA,twB,tid);
;   fft_pass<true,8>(Z,twA,twB,tid); fft_pass<true,10>(Z,twA,twB,tid);
	v_pk_mul_f32 v[30:31], v[12:13], v[18:19] op_sel:[1,1] op_sel_hi:[0,1]
	v_pk_fma_f32 v[244:245], v[12:13], v[18:19], v[30:31] op_sel:[0,0,0] op_sel_hi:[1,0,1] neg_hi:[0,0,1]
	v_pk_mul_f32 v[30:31], v[10:11], v[16:17] op_sel:[1,1] op_sel_hi:[0,1]
	v_pk_fma_f32 v[242:243], v[10:11], v[16:17], v[30:31] op_sel:[0,0,0] op_sel_hi:[1,0,1] neg_hi:[0,0,1]
	v_pk_mul_f32 v[30:31], v[14:15], v[20:21] op_sel:[1,1] op_sel_hi:[0,1]
	v_pk_fma_f32 v[246:247], v[14:15], v[20:21], v[30:31] op_sel:[0,0,0] op_sel_hi:[1,0,1] neg_hi:[0,0,1]
	v_pk_add_f32 v[22:23], v[8:9], v[244:245]
	v_pk_add_f32 v[24:25], v[8:9], v[244:245] neg_lo:[0,1] neg_hi:[0,1]
	v_pk_add_f32 v[26:27], v[242:243], v[246:247]
	v_pk_add_f32 v[28:29], v[242:243], v[246:247] neg_lo:[0,1] neg_hi:[0,1]
	v_pk_add_f32 v[80:81], v[22:23], v[26:27]
	ds_write_b64 v223, v[80:81] offset:49152
	v_pk_add_f32 v[82:83], v[24:25], v[28:29] op_sel:[0,1] op_sel_hi:[1,0] neg_lo:[0,1]
	ds_write_b64 v223, v[82:83] offset:49184
	v_pk_add_f32 v[84:85], v[22:23], v[26:27] neg_lo:[0,1] neg_hi:[0,1]
	ds_write_b64 v223, v[84:85] offset:49216
	v_pk_add_f32 v[236:237], v[24:25], v[28:29] op_sel:[0,1] op_sel_hi:[1,0] neg_hi:[0,1]
	ds_write_b64 v223, v[236:237] offset:49248
	s_waitcnt lgkmcnt(0)
	v_mov_b32_e32 v222, 0x3f6c835e
	v_mov_b32_e32 v223, 0x3ec3ef15
	v_mov_b32_e32 v224, 0x3f3504f3
	v_mov_b32_e32 v225, 0x3f3504f3
	v_and_b32_e32 v8, 15, v154
	v_lshlrev_b32_e32 v9, 3, v8
	v_add_u32_e32 v9, 0x20800, v9
	v_mov_b32_e32 v10, 0x20a00
	ds_read_b64 v[0:1], v9
	ds_read_b64 v[2:3], v10
	s_waitcnt lgkmcnt(0)
	v_pk_mul_f32 v[250:251], v[0:1], v[2:3] op_sel:[1,1] op_sel_hi:[1,0]
	v_pk_fma_f32 v[80:81], v[0:1], v[2:3], v[250:251] op_sel:[0,0,0] op_sel_hi:[0,1,1] neg_lo:[0,0,1]
	v_pk_mul_f32 v[250:251], v[80:81], v[80:81] op_sel:[1,1] op_sel_hi:[1,0]
	v_pk_fma_f32 v[82:83], v[80:81], v[80:81], v[250:251] op_sel:[0,0,0] op_sel_hi:[0,1,1] neg_lo:[0,0,1]
	v_pk_mul_f32 v[250:251], v[82:83], v[80:81] op_sel:[1,1] op_sel_hi:[1,0]
	v_pk_fma_f32 v[84:85], v[82:83], v[80:81], v[250:251] op_sel:[0,0,0] op_sel_hi:[0,1,1] neg_lo:[0,0,1]
	v_lshlrev_b32_e32 v9, 5, v8
	v_add_u32_e32 v9, 0x20800, v9
	v_mov_b32_e32 v10, 0x20a00
	ds_read_b64 v[0:1], v9
	ds_read_b64 v[2:3], v10
	s_waitcnt lgkmcnt(0)
	v_pk_mul_f32 v[250:251], v[0:1], v[2:3] op_sel:[1,1] op_sel_hi:[1,0]
	v_pk_fma_f32 v[236:237], v[0:1], v[2:3], v[250:251] op_sel:[0,0,0] op_sel_hi:[0,1,1] neg_lo:[0,0,1]
	v_pk_mul_f32 v[250:251], v[236:237], v[236:237] op_sel:[1,1] op_sel_hi:[1,0]
	v_pk_fma_f32 v[238:239], v[236:237], v[236:237], v[250:251] op_sel:[0,0,0] op_sel_hi:[0,1,1] neg_lo:[0,0,1]
	v_pk_mul_f32 v[250:251], v[238:239], v[236:237] op_sel:[1,1] op_sel_hi:[1,0]
	v_pk_fma_f32 v[240:241], v[238:239], v[236:237], v[250:251] op_sel:[0,0,0] op_sel_hi:[0,1,1] neg_lo:[0,0,1]
	v_lshrrev_b32_e32 v226, 6, v154
	v_bfe_u32 v227, v154, 4, 2
	v_lshl_add_u32 v226, v227, 3, v226
	v_lshlrev_b32_e32 v226, 8, v226
	v_and_b32_e32 v227, 15, v154
	v_add_u32_e32 v226, v226, v227
	v_lshlrev_b32_e32 v226, 3, v226
	v_add_u32_e32 v227, 0x10000, v226
	ds_read_b64 v[0:1], v226 offset:0
	ds_read_b64 v[2:3], v226 offset:128
	ds_read_b64 v[4:5], v226 offset:256
	ds_read_b64 v[6:7], v226 offset:384
	ds_read_b64 v[8:9], v226 offset:512
	ds_read_b64 v[10:11], v226 offset:640
	ds_read_b64 v[12:13], v226 offset:768
	ds_read_b64 v[14:15], v226 offset:896
	ds_read_b64 v[16:17], v226 offset:1024
	ds_read_b64 v[18:19], v226 offset:1152
	ds_read_b64 v[20:21], v226 offset:1280
	ds_read_b64 v[22:23], v226 offset:1408
	ds_read_b64 v[24:25], v226 offset:1536
	ds_read_b64 v[26:27], v226 offset:1664
	ds_read_b64 v[28:29], v226 offset:1792
	ds_read_b64 v[30:31], v226 offset:1920
	s_waitcnt lgkmcnt(12)
	v_pk_mul_f32 v[250:251], v[4:5], v[238:239] op_sel:[1,1] op_sel_hi:[0,1]
	v_pk_fma_f32 v[4:5], v[4:5], v[238:239], v[250:251] op_sel:[0,0,0] op_sel_hi:[1,0,1] neg_hi:[0,0,1]
	v_pk_mul_f32 v[250:251], v[2:3], v[236:237] op_sel:[1,1] op_sel_hi:[0,1]
	v_pk_fma_f32 v[2:3], v[2:3], v[236:237], v[250:251] op_sel:[0,0,0] op_sel_hi:[1,0,1] neg_hi:[0,0,1]
	v_pk_mul_f32 v[250:251], v[6:7], v[240:241] op_sel:[1,1] op_sel_hi:[0,1]
	v_pk_fma_f32 v[6:7], v[6:7], v[240:241], v[250:251] op_sel:[0,0,0] op_sel_hi:[1,0,1] neg_hi:[0,0,1]
	v_pk_add_f32 v[242:243], v[0:1], v[4:5]
	v_pk_add_f32 v[244:245], v[0:1], v[4:5] neg_lo:[0,1] neg_hi:[0,1]
	v_pk_add_f32 v[246:247], v[2:3], v[6:7]
	v_pk_add_f32 v[248:249], v[2:3], v[6:7] neg_lo:[0,1] neg_hi:[0,1]
	v_pk_add_f32 v[0:1], v[242:243], v[246:247]
	v_pk_add_f32 v[2:3], v[244:245], v[248:249] op_sel:[0,1] op_sel_hi:[1,0] neg_lo:[0,1]
	v_pk_add_f32 v[4:5], v[242:243], v[246:247] neg_lo:[0,1] neg_hi:[0,1]
	v_pk_add_f32 v[6:7], v[244:245], v[248:249] op_sel:[0,1] op_sel_hi:[1,0] neg_hi:[0,1]
	s_waitcnt lgkmcnt(8)
	v_pk_mul_f32 v[250:251], v[12:13], v[238:239] op_sel:[1,1] op_sel_hi:[0,1]
	v_pk_fma_f32 v[12:13], v[12:13], v[238:239], v[250:251] op_sel:[0,0,0] op_sel_hi:[1,0,1] neg_hi:[0,0,1]
	v_pk_mul_f32 v[250:251], v[10:11], v[236:237] op_sel:[1,1] op_sel_hi:[0,1]
	v_pk_fma_f32 v[10:11], v[10:11], v[236:237], v[250:251] op_sel:[0,0,0] op_sel_hi:[1,0,1] neg_hi:[0,0,1]
	v_pk_mul_f32 v[250:251], v[14:15], v[240:241] op_sel:[1,1] op_sel_hi:[0,1]
	v_pk_fma_f32 v[14:15], v[14:15], v[240:241], v[250:251] op_sel:[0,0,0] op_sel_hi:[1,0,1] neg_hi:[0,0,1]
	v_pk_add_f32 v[242:243], v[8:9], v[12:13]
	v_pk_add_f32 v[244:245], v[8:9], v[12:13] neg_lo:[0,1] neg_hi:[0,1]
	v_pk_add_f32 v[246:247], v[10:11], v[14:15]
	v_pk_add_f32 v[248:249], v[10:11], v[14:15] neg_lo:[0,1] neg_hi:[0,1]
	v_pk_add_f32 v[8:9], v[242:243], v[246:247]
	v_pk_add_f32 v[10:11], v[244:245], v[248:249] op_sel:[0,1] op_sel_hi:[1,0] neg_lo:[0,1]
	v_pk_add_f32 v[12:13], v[242:243], v[246:247] neg_lo:[0,1] neg_hi:[0,1]
	v_pk_add_f32 v[14:15], v[244:245], v[248:249] op_sel:[0,1] op_sel_hi:[1,0] neg_hi:[0,1]
	s_waitcnt lgkmcnt(4)
; HD float2 cmul(float2 a, float2 b){ return make_float2(a.x*b.x - a.y*b.y, a.x*b.y + a.y*b.x); }
; HD float2 cmulc(float2 a, float2 b){ return make_float2(a.x*b.x + a.y*b.y, a.y*b.x - a.x*b.y); }
; template<bool INV, bool NOTW>
; HD void bf4c(float2* Z, int i0, int i1, int i2, int i3, float2 w1, float2 w2, float2 w3){
;   float2 a0=Z[i0], a1=Z[i1], a2=Z[i2], a3=Z[i3];
;   if (INV && !NOTW){ a1=cmulc(a1,w1); a2=cmulc(a2,w2); a3=cmulc(a3,w3); }
;   float2 s02=make_float2(a0.x+a2.x,a0.y+a2.y), d02=make_float2(a0.x-a2.x,a0.y-a2.y);
;   float2 s13=make_float2(a1.x+a3.x,a1.y+a3.y), d13=make_float2(a1.x-a3.x,a1.y-a3.y);
;   float2 y0=make_float2(s02.x+s13.x,s02.y+s13.y), y2=make_float2(s02.x-s13.x,s02.y-s13.y);
;   float2 ym=make_float2(d02.x+d13.y,d02.y-d13.x);
;   float2 yp=make_float2(d02.x-d13.y,d02.y+d13.x);
;   float2 y1, y3;
;   if (INV){ y1=yp; y3=ym; } else if (NOTW){ y1=ym; y3=yp; } else { y1=cmul(ym,w1); y2=cmul(y2,w2); y3=cmul(yp,w3); }
;   Z[i0]=y0; Z[i1]=y1; Z[i2]=y2; Z[i3]=y3;
; }
; __device__ __forceinline__ void fft_inv_tail(float2* Z, const float2* twA, const float2* twB, int tid){
;   fft_pass<true,2,false>(Z,twA,twB,tid); fft_pass<true,4,false>(Z,twA,twB,tid); fft_pass<true,6>(Z,twA,twB,tid);
;   fft_pass<true,8>(Z,twA,twB,tid); fft_pass<true,10>(Z,twA,twB,tid);
	v_pk_mul_f32 v[250:251], v[20:21], v[238:239] op_sel:[1,1] op_sel_hi:[0,1]
	v_pk_fma_f32 v[20:21], v[20:21], v[238:239], v[250:251] op_sel:[0,0,0] op_sel_hi:[1,0,1] neg_hi:[0,0,1]
	v_pk_mul_f32 v[250:251], v[18:19], v[236:237] op_sel:[1,1] op_sel_hi:[0,1]
	v_pk_fma_f32 v[18:19], v[18:19], v[236:237], v[250:251] op_sel:[0,0,0] op_sel_hi:[1,0,1] neg_hi:[0,0,1]
	v_pk_mul_f32 v[250:251], v[22:23], v[240:241] op_sel:[1,1] op_sel_hi:[0,1]
	v_pk_fma_f32 v[22:23], v[22:23], v[240:241], v[250:251] op_sel:[0,0,0] op_sel_hi:[1,0,1] neg_hi:[0,0,1]
	v_pk_add_f32 v[242:243], v[16:17], v[20:21]
	v_pk_add_f32 v[244:245], v[16:17], v[20:21] neg_lo:[0,1] neg_hi:[0,1]
	v_pk_add_f32 v[246:247], v[18:19], v[22:23]
	v_pk_add_f32 v[248:249], v[18:19], v[22:23] neg_lo:[0,1] neg_hi:[0,1]
	v_pk_add_f32 v[16:17], v[242:243], v[246:247]
	v_pk_add_f32 v[18:19], v[244:245], v[248:249] op_sel:[0,1] op_sel_hi:[1,0] neg_lo:[0,1]
	v_pk_add_f32 v[20:21], v[242:243], v[246:247] neg_lo:[0,1] neg_hi:[0,1]
	v_pk_add_f32 v[22:23], v[244:245], v[248:249] op_sel:[0,1] op_sel_hi:[1,0] neg_hi:[0,1]
	s_waitcnt lgkmcnt(0)
	v_pk_mul_f32 v[250:251], v[28:29], v[238:239] op_sel:[1,1] op_sel_hi:[0,1]
	v_pk_fma_f32 v[28:29], v[28:29], v[238:239], v[250:251] op_sel:[0,0,0] op_sel_hi:[1,0,1] neg_hi:[0,0,1]
	v_pk_mul_f32 v[250:251], v[26:27], v[236:237] op_sel:[1,1] op_sel_hi:[0,1]
	v_pk_fma_f32 v[26:27], v[26:27], v[236:237], v[250:251] op_sel:[0,0,0] op_sel_hi:[1,0,1] neg_hi:[0,0,1]
	v_pk_mul_f32 v[250:251], v[30:31], v[240:241] op_sel:[1,1] op_sel_hi:[0,1]
	v_pk_fma_f32 v[30:31], v[30:31], v[240:241], v[250:251] op_sel:[0,0,0] op_sel_hi:[1,0,1] neg_hi:[0,0,1]
	v_pk_add_f32 v[242:243], v[24:25], v[28:29]
	v_pk_add_f32 v[244:245], v[24:25], v[28:29] neg_lo:[0,1] neg_hi:[0,1]
	v_pk_add_f32 v[246:247], v[26:27], v[30:31]
	v_pk_add_f32 v[248:249], v[26:27], v[30:31] neg_lo:[0,1] neg_hi:[0,1]
	v_pk_add_f32 v[24:25], v[242:243], v[246:247]
	v_pk_add_f32 v[26:27], v[244:245], v[248:249] op_sel:[0,1] op_sel_hi:[1,0] neg_lo:[0,1]
	v_pk_add_f32 v[28:29], v[242:243], v[246:247] neg_lo:[0,1] neg_hi:[0,1]
	v_pk_add_f32 v[30:31], v[244:245], v[248:249] op_sel:[0,1] op_sel_hi:[1,0] neg_hi:[0,1]
	v_pk_mul_f32 v[250:251], v[16:17], v[82:83] op_sel:[1,1] op_sel_hi:[0,1]
	v_pk_fma_f32 v[16:17], v[16:17], v[82:83], v[250:251] op_sel:[0,0,0] op_sel_hi:[1,0,1] neg_hi:[0,0,1]
	v_pk_mul_f32 v[250:251], v[8:9], v[80:81] op_sel:[1,1] op_sel_hi:[0,1]
	v_pk_fma_f32 v[8:9], v[8:9], v[80:81], v[250:251] op_sel:[0,0,0] op_sel_hi:[1,0,1] neg_hi:[0,0,1]
	v_pk_mul_f32 v[250:251], v[24:25], v[84:85] op_sel:[1,1] op_sel_hi:[0,1]
	v_pk_fma_f32 v[24:25], v[24:25], v[84:85], v[250:251] op_sel:[0,0,0] op_sel_hi:[1,0,1] neg_hi:[0,0,1]
	v_pk_add_f32 v[242:243], v[0:1], v[16:17]
	v_pk_add_f32 v[244:245], v[0:1], v[16:17] neg_lo:[0,1] neg_hi:[0,1]
	v_pk_add_f32 v[246:247], v[8:9], v[24:25]
	v_pk_add_f32 v[248:249], v[8:9], v[24:25] neg_lo:[0,1] neg_hi:[0,1]
	v_pk_add_f32 v[0:1], v[242:243], v[246:247]
	ds_write_b64 v226, v[0:1] offset:0
	v_pk_add_f32 v[8:9], v[244:245], v[248:249] op_sel:[0,1] op_sel_hi:[1,0] neg_lo:[0,1]
	ds_write_b64 v226, v[8:9] offset:512
	v_pk_add_f32 v[16:17], v[242:243], v[246:247] neg_lo:[0,1] neg_hi:[0,1]
	ds_write_b64 v226, v[16:17] offset:1024
	v_pk_add_f32 v[24:25], v[244:245], v[248:249] op_sel:[0,1] op_sel_hi:[1,0] neg_hi:[0,1]
	ds_write_b64 v226, v[24:25] offset:1536
	v_pk_mul_f32 v[250:251], v[18:19], v[224:225] op_sel:[1,1] op_sel_hi:[1,0] neg_lo:[0,0] neg_hi:[0,0]
	v_pk_fma_f32 v[18:19], v[18:19], v[224:225], v[250:251] op_sel:[0,0,0] op_sel_hi:[0,1,1] neg_lo:[0,0,1] neg_hi:[0,0,0]
	v_pk_mul_f32 v[250:251], v[18:19], v[82:83] op_sel:[1,1] op_sel_hi:[0,1]
	v_pk_fma_f32 v[18:19], v[18:19], v[82:83], v[250:251] op_sel:[0,0,0] op_sel_hi:[1,0,1] neg_hi:[0,0,1]
	v_pk_mul_f32 v[250:251], v[10:11], v[222:223] op_sel:[1,1] op_sel_hi:[1,0] neg_lo:[0,0] neg_hi:[0,0]
	v_pk_fma_f32 v[10:11], v[10:11], v[222:223], v[250:251] op_sel:[0,0,0] op_sel_hi:[0,1,1] neg_lo:[0,0,1] neg_hi:[0,0,0]
	v_pk_mul_f32 v[250:251], v[10:11], v[80:81] op_sel:[1,1] op_sel_hi:[0,1]
	v_pk_fma_f32 v[10:11], v[10:11], v[80:81], v[250:251] op_sel:[0,0,0] op_sel_hi:[1,0,1] neg_hi:[0,0,1]
	v_pk_mul_f32 v[250:251], v[26:27], v[222:223] op_sel:[1,0] op_sel_hi:[1,1] neg_lo:[0,0] neg_hi:[0,0]
	v_pk_fma_f32 v[26:27], v[26:27], v[222:223], v[250:251] op_sel:[0,1,0] op_sel_hi:[0,0,1] neg_lo:[0,0,1] neg_hi:[0,0,0]
	v_pk_mul_f32 v[250:251], v[26:27], v[84:85] op_sel:[1,1] op_sel_hi:[0,1]
	v_pk_fma_f32 v[26:27], v[26:27], v[84:85], v[250:251] op_sel:[0,0,0] op_sel_hi:[1,0,1] neg_hi:[0,0,1]
	v_pk_add_f32 v[242:243], v[2:3], v[18:19]
	v_pk_add_f32 v[244:245], v[2:3], v[18:19] neg_lo:[0,1] neg_hi:[0,1]
	v_pk_add_f32 v[246:247], v[10:11], v[26:27]
	v_pk_add_f32 v[248:249], v[10:11], v[26:27] neg_lo:[0,1] neg_hi:[0,1]
	v_pk_add_f32 v[2:3], v[242:243], v[246:247]
	ds_write_b64 v226, v[2:3] offset:128
	v_pk_add_f32 v[10:11], v[244:245], v[248:249] op_sel:[0,1] op_sel_hi:[1,0] neg_lo:[0,1]
	ds_write_b64 v226, v[10:11] offset:640
	v_pk_add_f32 v[18:19], v[242:243], v[246:247] neg_lo:[0,1] neg_hi:[0,1]
	ds_write_b64 v226, v[18:19] offset:1152
	v_pk_add_f32 v[26:27], v[244:245], v[248:249] op_sel:[0,1] op_sel_hi:[1,0] neg_hi:[0,1]
	ds_write_b64 v226, v[26:27] offset:1664
	v_pk_add_f32 v[20:21], v[20:21], 0 op_sel:[1,0] op_sel_hi:[0,0] neg_lo:[1,0]
	v_pk_mul_f32 v[250:251], v[20:21], v[82:83] op_sel:[1,1] op_sel_hi:[0,1]
	v_pk_fma_f32 v[20:21], v[20:21], v[82:83], v[250:251] op_sel:[0,0,0] op_sel_hi:[1,0,1] neg_hi:[0,0,1]
	v_pk_mul_f32 v[250:251], v[12:13], v[224:225] op_sel:[1,1] op_sel_hi:[1,0] neg_lo:[0,0] neg_hi:[0,0]
; HD float2 cmul(float2 a, float2 b){ return make_float2(a.x*b.x - a.y*b.y, a.x*b.y + a.y*b.x); }
; HD float2 cmulc(float2 a, float2 b){ return make_float2(a.x*b.x + a.y*b.y, a.y*b.x - a.x*b.y); }
; template<bool INV, bool NOTW>
; HD void bf4c(float2* Z, int i0, int i1, int i2, int i3, float2 w1, float2 w2, float2 w3){
;   float2 a0=Z[i0], a1=Z[i1], a2=Z[i2], a3=Z[i3];
;   if (INV && !NOTW){ a1=cmulc(a1,w1); a2=cmulc(a2,w2); a3=cmulc(a3,w3); }
;   float2 s02=make_float2(a0.x+a2.x,a0.y+a2.y), d02=make_float2(a0.x-a2.x,a0.y-a2.y);
;   float2 s13=make_float2(a1.x+a3.x,a1.y+a3.y), d13=make_float2(a1.x-a3.x,a1.y-a3.y);
;   float2 y0=make_float2(s02.x+s13.x,s02.y+s13.y), y2=make_float2(s02.x-s13.x,s02.y-s13.y);
;   float2 ym=make_float2(d02.x+d13.y,d02.y-d13.x);
;   float2 yp=make_float2(d02.x-d13.y,d02.y+d13.x);
;   float2 y1, y3;
;   if (INV){ y1=yp; y3=ym; } else if (NOTW){ y1=ym; y3=yp; } else { y1=cmul(ym,w1); y2=cmul(y2,w2); y3=cmul(yp,w3); }
;   Z[i0]=y0; Z[i1]=y1; Z[i2]=y2; Z[i3]=y3;
; }
; __device__ __forceinline__ void fft_inv_tail(float2* Z, const float2* twA, const float2* twB, int tid){
;   fft_pass<true,2,false>(Z,twA,twB,tid); fft_pass<true,4,false>(Z,twA,twB,tid); fft_pass<true,6>(Z,twA,twB,tid);
;   fft_pass<true,8>(Z,twA,twB,tid); fft_pass<true,10>(Z,twA,twB,tid);
	v_pk_fma_f32 v[12:13], v[12:13], v[224:225], v[250:251] op_sel:[0,0,0] op_sel_hi:[0,1,1] neg_lo:[0,0,1] neg_hi:[0,0,0]
	v_pk_mul_f32 v[250:251], v[12:13], v[80:81] op_sel:[1,1] op_sel_hi:[0,1]
	v_pk_fma_f32 v[12:13], v[12:13], v[80:81], v[250:251] op_sel:[0,0,0] op_sel_hi:[1,0,1] neg_hi:[0,0,1]
	v_pk_mul_f32 v[250:251], v[28:29], v[224:225] op_sel:[1,1] op_sel_hi:[1,0] neg_lo:[0,0] neg_hi:[0,1]
	v_pk_fma_f32 v[28:29], v[28:29], v[224:225], v[250:251] op_sel:[0,0,0] op_sel_hi:[0,1,1] neg_lo:[0,1,1] neg_hi:[0,0,0]
	v_pk_mul_f32 v[250:251], v[28:29], v[84:85] op_sel:[1,1] op_sel_hi:[0,1]
	v_pk_fma_f32 v[28:29], v[28:29], v[84:85], v[250:251] op_sel:[0,0,0] op_sel_hi:[1,0,1] neg_hi:[0,0,1]
	v_pk_add_f32 v[242:243], v[4:5], v[20:21]
	v_pk_add_f32 v[244:245], v[4:5], v[20:21] neg_lo:[0,1] neg_hi:[0,1]
	v_pk_add_f32 v[246:247], v[12:13], v[28:29]
	v_pk_add_f32 v[248:249], v[12:13], v[28:29] neg_lo:[0,1] neg_hi:[0,1]
	v_pk_add_f32 v[4:5], v[242:243], v[246:247]
	ds_write_b64 v226, v[4:5] offset:256
	v_pk_add_f32 v[12:13], v[244:245], v[248:249] op_sel:[0,1] op_sel_hi:[1,0] neg_lo:[0,1]
	ds_write_b64 v226, v[12:13] offset:768
	v_pk_add_f32 v[20:21], v[242:243], v[246:247] neg_lo:[0,1] neg_hi:[0,1]
	ds_write_b64 v226, v[20:21] offset:1280
	v_pk_add_f32 v[28:29], v[244:245], v[248:249] op_sel:[0,1] op_sel_hi:[1,0] neg_hi:[0,1]
	ds_write_b64 v226, v[28:29] offset:1792
	v_pk_mul_f32 v[250:251], v[22:23], v[224:225] op_sel:[1,1] op_sel_hi:[1,0] neg_lo:[0,0] neg_hi:[0,1]
	v_pk_fma_f32 v[22:23], v[22:23], v[224:225], v[250:251] op_sel:[0,0,0] op_sel_hi:[0,1,1] neg_lo:[0,1,1] neg_hi:[0,0,0]
	v_pk_mul_f32 v[250:251], v[22:23], v[82:83] op_sel:[1,1] op_sel_hi:[0,1]
	v_pk_fma_f32 v[22:23], v[22:23], v[82:83], v[250:251] op_sel:[0,0,0] op_sel_hi:[1,0,1] neg_hi:[0,0,1]
	v_pk_mul_f32 v[250:251], v[14:15], v[222:223] op_sel:[1,0] op_sel_hi:[1,1] neg_lo:[0,0] neg_hi:[0,0]
	v_pk_fma_f32 v[14:15], v[14:15], v[222:223], v[250:251] op_sel:[0,1,0] op_sel_hi:[0,0,1] neg_lo:[0,0,1] neg_hi:[0,0,0]
	v_pk_mul_f32 v[250:251], v[14:15], v[80:81] op_sel:[1,1] op_sel_hi:[0,1]
	v_pk_fma_f32 v[14:15], v[14:15], v[80:81], v[250:251] op_sel:[0,0,0] op_sel_hi:[1,0,1] neg_hi:[0,0,1]
	v_pk_mul_f32 v[250:251], v[30:31], v[222:223] op_sel:[1,1] op_sel_hi:[1,0] neg_lo:[0,1] neg_hi:[0,1]
	v_pk_fma_f32 v[30:31], v[30:31], v[222:223], v[250:251] op_sel:[0,0,0] op_sel_hi:[0,1,1] neg_lo:[0,1,1] neg_hi:[0,1,0]
	v_pk_mul_f32 v[250:251], v[30:31], v[84:85] op_sel:[1,1] op_sel_hi:[0,1]
	v_pk_fma_f32 v[30:31], v[30:31], v[84:85], v[250:251] op_sel:[0,0,0] op_sel_hi:[1,0,1] neg_hi:[0,0,1]
	v_pk_add_f32 v[242:243], v[6:7], v[22:23]
	v_pk_add_f32 v[244:245], v[6:7], v[22:23] neg_lo:[0,1] neg_hi:[0,1]
	v_pk_add_f32 v[246:247], v[14:15], v[30:31]
	v_pk_add_f32 v[248:249], v[14:15], v[30:31] neg_lo:[0,1] neg_hi:[0,1]
	v_pk_add_f32 v[6:7], v[242:243], v[246:247]
	ds_write_b64 v226, v[6:7] offset:384
	v_pk_add_f32 v[14:15], v[244:245], v[248:249] op_sel:[0,1] op_sel_hi:[1,0] neg_lo:[0,1]
	ds_write_b64 v226, v[14:15] offset:896
	v_pk_add_f32 v[22:23], v[242:243], v[246:247] neg_lo:[0,1] neg_hi:[0,1]
	ds_write_b64 v226, v[22:23] offset:1408
	v_pk_add_f32 v[30:31], v[244:245], v[248:249] op_sel:[0,1] op_sel_hi:[1,0] neg_hi:[0,1]
	ds_write_b64 v226, v[30:31] offset:1920
	ds_read_b64 v[0:1], v227 offset:0
	ds_read_b64 v[2:3], v227 offset:128
	ds_read_b64 v[4:5], v227 offset:256
	ds_read_b64 v[6:7], v227 offset:384
	ds_read_b64 v[8:9], v227 offset:512
	ds_read_b64 v[10:11], v227 offset:640
	ds_read_b64 v[12:13], v227 offset:768
	ds_read_b64 v[14:15], v227 offset:896
	ds_read_b64 v[16:17], v227 offset:1024
	ds_read_b64 v[18:19], v227 offset:1152
	ds_read_b64 v[20:21], v227 offset:1280
	ds_read_b64 v[22:23], v227 offset:1408
	ds_read_b64 v[24:25], v227 offset:1536
	ds_read_b64 v[26:27], v227 offset:1664
	ds_read_b64 v[28:29], v227 offset:1792
	ds_read_b64 v[30:31], v227 offset:1920
	s_waitcnt lgkmcnt(12)
	v_pk_mul_f32 v[250:251], v[4:5], v[238:239] op_sel:[1,1] op_sel_hi:[0,1]
	v_pk_fma_f32 v[4:5], v[4:5], v[238:239], v[250:251] op_sel:[0,0,0] op_sel_hi:[1,0,1] neg_hi:[0,0,1]
	v_pk_mul_f32 v[250:251], v[2:3], v[236:237] op_sel:[1,1] op_sel_hi:[0,1]
	v_pk_fma_f32 v[2:3], v[2:3], v[236:237], v[250:251] op_sel:[0,0,0] op_sel_hi:[1,0,1] neg_hi:[0,0,1]
	v_pk_mul_f32 v[250:251], v[6:7], v[240:241] op_sel:[1,1] op_sel_hi:[0,1]
	v_pk_fma_f32 v[6:7], v[6:7], v[240:241], v[250:251] op_sel:[0,0,0] op_sel_hi:[1,0,1] neg_hi:[0,0,1]
	v_pk_add_f32 v[242:243], v[0:1], v[4:5]
	v_pk_add_f32 v[244:245], v[0:1], v[4:5] neg_lo:[0,1] neg_hi:[0,1]
	v_pk_add_f32 v[246:247], v[2:3], v[6:7]
	v_pk_add_f32 v[248:249], v[2:3], v[6:7] neg_lo:[0,1] neg_hi:[0,1]
	v_pk_add_f32 v[0:1], v[242:243], v[246:247]
	v_pk_add_f32 v[2:3], v[244:245], v[248:249] op_sel:[0,1] op_sel_hi:[1,0] neg_lo:[0,1]
	v_pk_add_f32 v[4:5], v[242:243], v[246:247] neg_lo:[0,1] neg_hi:[0,1]
	v_pk_add_f32 v[6:7], v[244:245], v[248:249] op_sel:[0,1] op_sel_hi:[1,0] neg_hi:[0,1]
	s_waitcnt lgkmcnt(8)
	v_pk_mul_f32 v[250:251], v[12:13], v[238:239] op_sel:[1,1] op_sel_hi:[0,1]
	v_pk_fma_f32 v[12:13], v[12:13], v[238:239], v[250:251] op_sel:[0,0,0] op_sel_hi:[1,0,1] neg_hi:[0,0,1]
	v_pk_mul_f32 v[250:251], v[10:11], v[236:237] op_sel:[1,1] op_sel_hi:[0,1]
	v_pk_fma_f32 v[10:11], v[10:11], v[236:237], v[250:251] op_sel:[0,0,0] op_sel_hi:[1,0,1] neg_hi:[0,0,1]
	v_pk_mul_f32 v[250:251], v[14:15], v[240:241] op_sel:[1,1] op_sel_hi:[0,1]
	v_pk_fma_f32 v[14:15], v[14:15], v[240:241], v[250:251] op_sel:[0,0,0] op_sel_hi:[1,0,1] neg_hi:[0,0,1]
	v_pk_add_f32 v[242:243], v[8:9], v[12:13]
	v_pk_add_f32 v[244:245], v[8:9], v[12:13] neg_lo:[0,1] neg_hi:[0,1]
	v_pk_add_f32 v[246:247], v[10:11], v[14:15]
	v_pk_add_f32 v[248:249], v[10:11], v[14:15] neg_lo:[0,1] neg_hi:[0,1]
	v_pk_add_f32 v[8:9], v[242:243], v[246:247]
	v_pk_add_f32 v[10:11], v[244:245], v[248:249] op_sel:[0,1] op_sel_hi:[1,0] neg_lo:[0,1]
	v_pk_add_f32 v[12:13], v[242:243], v[246:247] neg_lo:[0,1] neg_hi:[0,1]
	v_pk_add_f32 v[14:15], v[244:245], v[248:249] op_sel:[0,1] op_sel_hi:[1,0] neg_hi:[0,1]
	s_waitcnt lgkmcnt(4)
; HD float2 cmul(float2 a, float2 b){ return make_float2(a.x*b.x - a.y*b.y, a.x*b.y + a.y*b.x); }
; HD float2 cmulc(float2 a, float2 b){ return make_float2(a.x*b.x + a.y*b.y, a.y*b.x - a.x*b.y); }
; template<bool INV, bool NOTW>
; HD void bf4c(float2* Z, int i0, int i1, int i2, int i3, float2 w1, float2 w2, float2 w3){
;   float2 a0=Z[i0], a1=Z[i1], a2=Z[i2], a3=Z[i3];
;   if (INV && !NOTW){ a1=cmulc(a1,w1); a2=cmulc(a2,w2); a3=cmulc(a3,w3); }
;   float2 s02=make_float2(a0.x+a2.x,a0.y+a2.y), d02=make_float2(a0.x-a2.x,a0.y-a2.y);
;   float2 s13=make_float2(a1.x+a3.x,a1.y+a3.y), d13=make_float2(a1.x-a3.x,a1.y-a3.y);
;   float2 y0=make_float2(s02.x+s13.x,s02.y+s13.y), y2=make_float2(s02.x-s13.x,s02.y-s13.y);
;   float2 ym=make_float2(d02.x+d13.y,d02.y-d13.x);
;   float2 yp=make_float2(d02.x-d13.y,d02.y+d13.x);
;   float2 y1, y3;
;   if (INV){ y1=yp; y3=ym; } else if (NOTW){ y1=ym; y3=yp; } else { y1=cmul(ym,w1); y2=cmul(y2,w2); y3=cmul(yp,w3); }
;   Z[i0]=y0; Z[i1]=y1; Z[i2]=y2; Z[i3]=y3;
; }
; __device__ __forceinline__ void fft_inv_tail(float2* Z, const float2* twA, const float2* twB, int tid){
;   fft_pass<true,2,false>(Z,twA,twB,tid); fft_pass<true,4,false>(Z,twA,twB,tid); fft_pass<true,6>(Z,twA,twB,tid);
;   fft_pass<true,8>(Z,twA,twB,tid); fft_pass<true,10>(Z,twA,twB,tid);
	v_pk_mul_f32 v[250:251], v[20:21], v[238:239] op_sel:[1,1] op_sel_hi:[0,1]
	v_pk_fma_f32 v[20:21], v[20:21], v[238:239], v[250:251] op_sel:[0,0,0] op_sel_hi:[1,0,1] neg_hi:[0,0,1]
	v_pk_mul_f32 v[250:251], v[18:19], v[236:237] op_sel:[1,1] op_sel_hi:[0,1]
	v_pk_fma_f32 v[18:19], v[18:19], v[236:237], v[250:251] op_sel:[0,0,0] op_sel_hi:[1,0,1] neg_hi:[0,0,1]
	v_pk_mul_f32 v[250:251], v[22:23], v[240:241] op_sel:[1,1] op_sel_hi:[0,1]
	v_pk_fma_f32 v[22:23], v[22:23], v[240:241], v[250:251] op_sel:[0,0,0] op_sel_hi:[1,0,1] neg_hi:[0,0,1]
	v_pk_add_f32 v[242:243], v[16:17], v[20:21]
	v_pk_add_f32 v[244:245], v[16:17], v[20:21] neg_lo:[0,1] neg_hi:[0,1]
	v_pk_add_f32 v[246:247], v[18:19], v[22:23]
	v_pk_add_f32 v[248:249], v[18:19], v[22:23] neg_lo:[0,1] neg_hi:[0,1]
	v_pk_add_f32 v[16:17], v[242:243], v[246:247]
	v_pk_add_f32 v[18:19], v[244:245], v[248:249] op_sel:[0,1] op_sel_hi:[1,0] neg_lo:[0,1]
	v_pk_add_f32 v[20:21], v[242:243], v[246:247] neg_lo:[0,1] neg_hi:[0,1]
	v_pk_add_f32 v[22:23], v[244:245], v[248:249] op_sel:[0,1] op_sel_hi:[1,0] neg_hi:[0,1]
	s_waitcnt lgkmcnt(0)
	v_pk_mul_f32 v[250:251], v[28:29], v[238:239] op_sel:[1,1] op_sel_hi:[0,1]
	v_pk_fma_f32 v[28:29], v[28:29], v[238:239], v[250:251] op_sel:[0,0,0] op_sel_hi:[1,0,1] neg_hi:[0,0,1]
	v_pk_mul_f32 v[250:251], v[26:27], v[236:237] op_sel:[1,1] op_sel_hi:[0,1]
	v_pk_fma_f32 v[26:27], v[26:27], v[236:237], v[250:251] op_sel:[0,0,0] op_sel_hi:[1,0,1] neg_hi:[0,0,1]
	v_pk_mul_f32 v[250:251], v[30:31], v[240:241] op_sel:[1,1] op_sel_hi:[0,1]
	v_pk_fma_f32 v[30:31], v[30:31], v[240:241], v[250:251] op_sel:[0,0,0] op_sel_hi:[1,0,1] neg_hi:[0,0,1]
	v_pk_add_f32 v[242:243], v[24:25], v[28:29]
	v_pk_add_f32 v[244:245], v[24:25], v[28:29] neg_lo:[0,1] neg_hi:[0,1]
	v_pk_add_f32 v[246:247], v[26:27], v[30:31]
	v_pk_add_f32 v[248:249], v[26:27], v[30:31] neg_lo:[0,1] neg_hi:[0,1]
	v_pk_add_f32 v[24:25], v[242:243], v[246:247]
	v_pk_add_f32 v[26:27], v[244:245], v[248:249] op_sel:[0,1] op_sel_hi:[1,0] neg_lo:[0,1]
	v_pk_add_f32 v[28:29], v[242:243], v[246:247] neg_lo:[0,1] neg_hi:[0,1]
	v_pk_add_f32 v[30:31], v[244:245], v[248:249] op_sel:[0,1] op_sel_hi:[1,0] neg_hi:[0,1]
	v_pk_mul_f32 v[250:251], v[16:17], v[82:83] op_sel:[1,1] op_sel_hi:[0,1]
	v_pk_fma_f32 v[16:17], v[16:17], v[82:83], v[250:251] op_sel:[0,0,0] op_sel_hi:[1,0,1] neg_hi:[0,0,1]
	v_pk_mul_f32 v[250:251], v[8:9], v[80:81] op_sel:[1,1] op_sel_hi:[0,1]
	v_pk_fma_f32 v[8:9], v[8:9], v[80:81], v[250:251] op_sel:[0,0,0] op_sel_hi:[1,0,1] neg_hi:[0,0,1]
	v_pk_mul_f32 v[250:251], v[24:25], v[84:85] op_sel:[1,1] op_sel_hi:[0,1]
	v_pk_fma_f32 v[24:25], v[24:25], v[84:85], v[250:251] op_sel:[0,0,0] op_sel_hi:[1,0,1] neg_hi:[0,0,1]
	v_pk_add_f32 v[242:243], v[0:1], v[16:17]
	v_pk_add_f32 v[244:245], v[0:1], v[16:17] neg_lo:[0,1] neg_hi:[0,1]
	v_pk_add_f32 v[246:247], v[8:9], v[24:25]
	v_pk_add_f32 v[248:249], v[8:9], v[24:25] neg_lo:[0,1] neg_hi:[0,1]
	v_pk_add_f32 v[0:1], v[242:243], v[246:247]
	ds_write_b64 v227, v[0:1] offset:0
	v_pk_add_f32 v[8:9], v[244:245], v[248:249] op_sel:[0,1] op_sel_hi:[1,0] neg_lo:[0,1]
	ds_write_b64 v227, v[8:9] offset:512
	v_pk_add_f32 v[16:17], v[242:243], v[246:247] neg_lo:[0,1] neg_hi:[0,1]
	ds_write_b64 v227, v[16:17] offset:1024
	v_pk_add_f32 v[24:25], v[244:245], v[248:249] op_sel:[0,1] op_sel_hi:[1,0] neg_hi:[0,1]
	ds_write_b64 v227, v[24:25] offset:1536
	v_pk_mul_f32 v[250:251], v[18:19], v[224:225] op_sel:[1,1] op_sel_hi:[1,0] neg_lo:[0,0] neg_hi:[0,0]
	v_pk_fma_f32 v[18:19], v[18:19], v[224:225], v[250:251] op_sel:[0,0,0] op_sel_hi:[0,1,1] neg_lo:[0,0,1] neg_hi:[0,0,0]
	v_pk_mul_f32 v[250:251], v[18:19], v[82:83] op_sel:[1,1] op_sel_hi:[0,1]
	v_pk_fma_f32 v[18:19], v[18:19], v[82:83], v[250:251] op_sel:[0,0,0] op_sel_hi:[1,0,1] neg_hi:[0,0,1]
	v_pk_mul_f32 v[250:251], v[10:11], v[222:223] op_sel:[1,1] op_sel_hi:[1,0] neg_lo:[0,0] neg_hi:[0,0]
	v_pk_fma_f32 v[10:11], v[10:11], v[222:223], v[250:251] op_sel:[0,0,0] op_sel_hi:[0,1,1] neg_lo:[0,0,1] neg_hi:[0,0,0]
	v_pk_mul_f32 v[250:251], v[10:11], v[80:81] op_sel:[1,1] op_sel_hi:[0,1]
	v_pk_fma_f32 v[10:11], v[10:11], v[80:81], v[250:251] op_sel:[0,0,0] op_sel_hi:[1,0,1] neg_hi:[0,0,1]
	v_pk_mul_f32 v[250:251], v[26:27], v[222:223] op_sel:[1,0] op_sel_hi:[1,1] neg_lo:[0,0] neg_hi:[0,0]
	v_pk_fma_f32 v[26:27], v[26:27], v[222:223], v[250:251] op_sel:[0,1,0] op_sel_hi:[0,0,1] neg_lo:[0,0,1] neg_hi:[0,0,0]
	v_pk_mul_f32 v[250:251], v[26:27], v[84:85] op_sel:[1,1] op_sel_hi:[0,1]
	v_pk_fma_f32 v[26:27], v[26:27], v[84:85], v[250:251] op_sel:[0,0,0] op_sel_hi:[1,0,1] neg_hi:[0,0,1]
	v_pk_add_f32 v[242:243], v[2:3], v[18:19]
	v_pk_add_f32 v[244:245], v[2:3], v[18:19] neg_lo:[0,1] neg_hi:[0,1]
	v_pk_add_f32 v[246:247], v[10:11], v[26:27]
	v_pk_add_f32 v[248:249], v[10:11], v[26:27] neg_lo:[0,1] neg_hi:[0,1]
	v_pk_add_f32 v[2:3], v[242:243], v[246:247]
	ds_write_b64 v227, v[2:3] offset:128
	v_pk_add_f32 v[10:11], v[244:245], v[248:249] op_sel:[0,1] op_sel_hi:[1,0] neg_lo:[0,1]
	ds_write_b64 v227, v[10:11] offset:640
	v_pk_add_f32 v[18:19], v[242:243], v[246:247] neg_lo:[0,1] neg_hi:[0,1]
	ds_write_b64 v227, v[18:19] offset:1152
	v_pk_add_f32 v[26:27], v[244:245], v[248:249] op_sel:[0,1] op_sel_hi:[1,0] neg_hi:[0,1]
	ds_write_b64 v227, v[26:27] offset:1664
	v_pk_add_f32 v[20:21], v[20:21], 0 op_sel:[1,0] op_sel_hi:[0,0] neg_lo:[1,0]
	v_pk_mul_f32 v[250:251], v[20:21], v[82:83] op_sel:[1,1] op_sel_hi:[0,1]
	v_pk_fma_f32 v[20:21], v[20:21], v[82:83], v[250:251] op_sel:[0,0,0] op_sel_hi:[1,0,1] neg_hi:[0,0,1]
	v_pk_mul_f32 v[250:251], v[12:13], v[224:225] op_sel:[1,1] op_sel_hi:[1,0] neg_lo:[0,0] neg_hi:[0,0]
; HD float2 cmul(float2 a, float2 b){ return make_float2(a.x*b.x - a.y*b.y, a.x*b.y + a.y*b.x); }
; HD float2 cmulc(float2 a, float2 b){ return make_float2(a.x*b.x + a.y*b.y, a.y*b.x - a.x*b.y); }
; template<bool INV, bool NOTW>
; HD void bf4c(float2* Z, int i0, int i1, int i2, int i3, float2 w1, float2 w2, float2 w3){
;   float2 a0=Z[i0], a1=Z[i1], a2=Z[i2], a3=Z[i3];
;   if (INV && !NOTW){ a1=cmulc(a1,w1); a2=cmulc(a2,w2); a3=cmulc(a3,w3); }
;   float2 s02=make_float2(a0.x+a2.x,a0.y+a2.y), d02=make_float2(a0.x-a2.x,a0.y-a2.y);
;   float2 s13=make_float2(a1.x+a3.x,a1.y+a3.y), d13=make_float2(a1.x-a3.x,a1.y-a3.y);
;   float2 y0=make_float2(s02.x+s13.x,s02.y+s13.y), y2=make_float2(s02.x-s13.x,s02.y-s13.y);
;   float2 ym=make_float2(d02.x+d13.y,d02.y-d13.x);
;   float2 yp=make_float2(d02.x-d13.y,d02.y+d13.x);
;   float2 y1, y3;
;   if (INV){ y1=yp; y3=ym; } else if (NOTW){ y1=ym; y3=yp; } else { y1=cmul(ym,w1); y2=cmul(y2,w2); y3=cmul(yp,w3); }
;   Z[i0]=y0; Z[i1]=y1; Z[i2]=y2; Z[i3]=y3;
; }
; __device__ __forceinline__ void fft_inv_tail(float2* Z, const float2* twA, const float2* twB, int tid){
;   fft_pass<true,2,false>(Z,twA,twB,tid); fft_pass<true,4,false>(Z,twA,twB,tid); fft_pass<true,6>(Z,twA,twB,tid);
;   fft_pass<true,8>(Z,twA,twB,tid); fft_pass<true,10>(Z,twA,twB,tid);
	v_pk_fma_f32 v[12:13], v[12:13], v[224:225], v[250:251] op_sel:[0,0,0] op_sel_hi:[0,1,1] neg_lo:[0,0,1] neg_hi:[0,0,0]
	v_pk_mul_f32 v[250:251], v[12:13], v[80:81] op_sel:[1,1] op_sel_hi:[0,1]
	v_pk_fma_f32 v[12:13], v[12:13], v[80:81], v[250:251] op_sel:[0,0,0] op_sel_hi:[1,0,1] neg_hi:[0,0,1]
	v_pk_mul_f32 v[250:251], v[28:29], v[224:225] op_sel:[1,1] op_sel_hi:[1,0] neg_lo:[0,0] neg_hi:[0,1]
	v_pk_fma_f32 v[28:29], v[28:29], v[224:225], v[250:251] op_sel:[0,0,0] op_sel_hi:[0,1,1] neg_lo:[0,1,1] neg_hi:[0,0,0]
	v_pk_mul_f32 v[250:251], v[28:29], v[84:85] op_sel:[1,1] op_sel_hi:[0,1]
	v_pk_fma_f32 v[28:29], v[28:29], v[84:85], v[250:251] op_sel:[0,0,0] op_sel_hi:[1,0,1] neg_hi:[0,0,1]
	v_pk_add_f32 v[242:243], v[4:5], v[20:21]
	v_pk_add_f32 v[244:245], v[4:5], v[20:21] neg_lo:[0,1] neg_hi:[0,1]
	v_pk_add_f32 v[246:247], v[12:13], v[28:29]
	v_pk_add_f32 v[248:249], v[12:13], v[28:29] neg_lo:[0,1] neg_hi:[0,1]
	v_pk_add_f32 v[4:5], v[242:243], v[246:247]
	ds_write_b64 v227, v[4:5] offset:256
	v_pk_add_f32 v[12:13], v[244:245], v[248:249] op_sel:[0,1] op_sel_hi:[1,0] neg_lo:[0,1]
	ds_write_b64 v227, v[12:13] offset:768
	v_pk_add_f32 v[20:21], v[242:243], v[246:247] neg_lo:[0,1] neg_hi:[0,1]
	ds_write_b64 v227, v[20:21] offset:1280
	v_pk_add_f32 v[28:29], v[244:245], v[248:249] op_sel:[0,1] op_sel_hi:[1,0] neg_hi:[0,1]
	ds_write_b64 v227, v[28:29] offset:1792
	v_pk_mul_f32 v[250:251], v[22:23], v[224:225] op_sel:[1,1] op_sel_hi:[1,0] neg_lo:[0,0] neg_hi:[0,1]
	v_pk_fma_f32 v[22:23], v[22:23], v[224:225], v[250:251] op_sel:[0,0,0] op_sel_hi:[0,1,1] neg_lo:[0,1,1] neg_hi:[0,0,0]
	v_pk_mul_f32 v[250:251], v[22:23], v[82:83] op_sel:[1,1] op_sel_hi:[0,1]
	v_pk_fma_f32 v[22:23], v[22:23], v[82:83], v[250:251] op_sel:[0,0,0] op_sel_hi:[1,0,1] neg_hi:[0,0,1]
	v_pk_mul_f32 v[250:251], v[14:15], v[222:223] op_sel:[1,0] op_sel_hi:[1,1] neg_lo:[0,0] neg_hi:[0,0]
	v_pk_fma_f32 v[14:15], v[14:15], v[222:223], v[250:251] op_sel:[0,1,0] op_sel_hi:[0,0,1] neg_lo:[0,0,1] neg_hi:[0,0,0]
	v_pk_mul_f32 v[250:251], v[14:15], v[80:81] op_sel:[1,1] op_sel_hi:[0,1]
	v_pk_fma_f32 v[14:15], v[14:15], v[80:81], v[250:251] op_sel:[0,0,0] op_sel_hi:[1,0,1] neg_hi:[0,0,1]
	v_pk_mul_f32 v[250:251], v[30:31], v[222:223] op_sel:[1,1] op_sel_hi:[1,0] neg_lo:[0,1] neg_hi:[0,1]
	v_pk_fma_f32 v[30:31], v[30:31], v[222:223], v[250:251] op_sel:[0,0,0] op_sel_hi:[0,1,1] neg_lo:[0,1,1] neg_hi:[0,1,0]
	v_pk_mul_f32 v[250:251], v[30:31], v[84:85] op_sel:[1,1] op_sel_hi:[0,1]
	v_pk_fma_f32 v[30:31], v[30:31], v[84:85], v[250:251] op_sel:[0,0,0] op_sel_hi:[1,0,1] neg_hi:[0,0,1]
	v_pk_add_f32 v[242:243], v[6:7], v[22:23]
	v_pk_add_f32 v[244:245], v[6:7], v[22:23] neg_lo:[0,1] neg_hi:[0,1]
	v_pk_add_f32 v[246:247], v[14:15], v[30:31]
	v_pk_add_f32 v[248:249], v[14:15], v[30:31] neg_lo:[0,1] neg_hi:[0,1]
	v_pk_add_f32 v[6:7], v[242:243], v[246:247]
	ds_write_b64 v227, v[6:7] offset:384
	v_pk_add_f32 v[14:15], v[244:245], v[248:249] op_sel:[0,1] op_sel_hi:[1,0] neg_lo:[0,1]
	ds_write_b64 v227, v[14:15] offset:896
	v_pk_add_f32 v[22:23], v[242:243], v[246:247] neg_lo:[0,1] neg_hi:[0,1]
	ds_write_b64 v227, v[22:23] offset:1408
	v_pk_add_f32 v[30:31], v[244:245], v[248:249] op_sel:[0,1] op_sel_hi:[1,0] neg_hi:[0,1]
	ds_write_b64 v227, v[30:31] offset:1920
	s_waitcnt lgkmcnt(0)
	s_barrier
	v_and_b32_e32 v8, 255, v154
	v_lshrrev_b32_e32 v9, 4, v8
	v_lshlrev_b32_e32 v9, 3, v9
	v_add_u32_e32 v9, 0x20800, v9
	v_and_b32_e32 v10, 15, v8
	v_lshlrev_b32_e32 v10, 5, v10
	v_add_u32_e32 v10, 0x20a00, v10
	ds_read_b64 v[0:1], v9
	ds_read_b64 v[2:3], v10
	s_waitcnt lgkmcnt(0)
	v_pk_mul_f32 v[250:251], v[0:1], v[2:3] op_sel:[1,1] op_sel_hi:[1,0]
	v_pk_fma_f32 v[80:81], v[0:1], v[2:3], v[250:251] op_sel:[0,0,0] op_sel_hi:[0,1,1] neg_lo:[0,0,1]
	v_pk_mul_f32 v[250:251], v[80:81], v[80:81] op_sel:[1,1] op_sel_hi:[1,0]
	v_pk_fma_f32 v[82:83], v[80:81], v[80:81], v[250:251] op_sel:[0,0,0] op_sel_hi:[0,1,1] neg_lo:[0,0,1]
	v_pk_mul_f32 v[250:251], v[82:83], v[80:81] op_sel:[1,1] op_sel_hi:[1,0]
	v_pk_fma_f32 v[84:85], v[82:83], v[80:81], v[250:251] op_sel:[0,0,0] op_sel_hi:[0,1,1] neg_lo:[0,0,1]
	v_lshrrev_b32_e32 v9, 2, v8
	v_lshlrev_b32_e32 v9, 3, v9
	v_add_u32_e32 v9, 0x20800, v9
	v_and_b32_e32 v10, 3, v8
	v_lshlrev_b32_e32 v10, 7, v10
	v_add_u32_e32 v10, 0x20a00, v10
	ds_read_b64 v[0:1], v9
	ds_read_b64 v[2:3], v10
	s_waitcnt lgkmcnt(0)
	v_pk_mul_f32 v[250:251], v[0:1], v[2:3] op_sel:[1,1] op_sel_hi:[1,0]
	v_pk_fma_f32 v[236:237], v[0:1], v[2:3], v[250:251] op_sel:[0,0,0] op_sel_hi:[0,1,1] neg_lo:[0,0,1]
	v_pk_mul_f32 v[250:251], v[236:237], v[236:237] op_sel:[1,1] op_sel_hi:[1,0]
	v_pk_fma_f32 v[238:239], v[236:237], v[236:237], v[250:251] op_sel:[0,0,0] op_sel_hi:[0,1,1] neg_lo:[0,0,1]
	v_pk_mul_f32 v[250:251], v[238:239], v[236:237] op_sel:[1,1] op_sel_hi:[1,0]
	v_pk_fma_f32 v[240:241], v[238:239], v[236:237], v[250:251] op_sel:[0,0,0] op_sel_hi:[0,1,1] neg_lo:[0,0,1]
	v_lshrrev_b32_e32 v226, 8, v154
	v_lshlrev_b32_e32 v226, 12, v226
	v_and_b32_e32 v227, 255, v154
	v_add_u32_e32 v226, v226, v227
	v_lshlrev_b32_e32 v226, 3, v226
	v_add_u32_e32 v227, 0x10000, v226
	ds_read_b64 v[0:1], v226 offset:0
	ds_read_b64 v[2:3], v226 offset:2048
	ds_read_b64 v[4:5], v226 offset:4096
	ds_read_b64 v[6:7], v226 offset:6144
	ds_read_b64 v[8:9], v226 offset:8192
	ds_read_b64 v[10:11], v226 offset:10240
	ds_read_b64 v[12:13], v226 offset:12288
	ds_read_b64 v[14:15], v226 offset:14336
	ds_read_b64 v[16:17], v226 offset:16384
	ds_read_b64 v[18:19], v226 offset:18432
	ds_read_b64 v[20:21], v226 offset:20480
	ds_read_b64 v[22:23], v226 offset:22528
	ds_read_b64 v[24:25], v226 offset:24576
	ds_read_b64 v[26:27], v226 offset:26624
	ds_read_b64 v[28:29], v226 offset:28672
	ds_read_b64 v[30:31], v226 offset:30720
	s_waitcnt lgkmcnt(12)
; HD float2 cmul(float2 a, float2 b){ return make_float2(a.x*b.x - a.y*b.y, a.x*b.y + a.y*b.x); }
; HD float2 cmulc(float2 a, float2 b){ return make_float2(a.x*b.x + a.y*b.y, a.y*b.x - a.x*b.y); }
; template<bool INV, bool NOTW>
; HD void bf4c(float2* Z, int i0, int i1, int i2, int i3, float2 w1, float2 w2, float2 w3){
;   float2 a0=Z[i0], a1=Z[i1], a2=Z[i2], a3=Z[i3];
;   if (INV && !NOTW){ a1=cmulc(a1,w1); a2=cmulc(a2,w2); a3=cmulc(a3,w3); }
;   float2 s02=make_float2(a0.x+a2.x,a0.y+a2.y), d02=make_float2(a0.x-a2.x,a0.y-a2.y);
;   float2 s13=make_float2(a1.x+a3.x,a1.y+a3.y), d13=make_float2(a1.x-a3.x,a1.y-a3.y);
;   float2 y0=make_float2(s02.x+s13.x,s02.y+s13.y), y2=make_float2(s02.x-s13.x,s02.y-s13.y);
;   float2 ym=make_float2(d02.x+d13.y,d02.y-d13.x);
;   float2 yp=make_float2(d02.x-d13.y,d02.y+d13.x);
;   float2 y1, y3;
;   if (INV){ y1=yp; y3=ym; } else if (NOTW){ y1=ym; y3=yp; } else { y1=cmul(ym,w1); y2=cmul(y2,w2); y3=cmul(yp,w3); }
;   Z[i0]=y0; Z[i1]=y1; Z[i2]=y2; Z[i3]=y3;
; }
; template<bool INV, int LQ, bool BARRIER=true>
; HD void fft_pass(float2* Z, const float2* twA, const float2* twB, int tid){
;     ...
;   } else {
;     int j=tid&(q-1); int base0=((tid>>LQ)<<(LQ+2))+j;
;     float2 w1=make_float2(1.f,0.f), w2=w1, w3=w1;
;     if (LQ>0){ int k=j*tws; w1=cmul(twA[k>>6],twB[k&63]); w2=cmul(w1,w1); w3=cmul(w2,w1); }
;     _Pragma("unroll") for (int i=0;i<8;++i){ int base=base0+i*2048; bf4c<INV,(LQ==0)>(Z,base,base+q,base+2*q,base+3*q,w1,w2,w3); }
;   }
; __device__ __forceinline__ void fft_inv_tail(float2* Z, const float2* twA, const float2* twB, int tid){
;     ...
;   fft_pass<true,8>(Z,twA,twB,tid); fft_pass<true,10>(Z,twA,twB,tid);
	v_pk_mul_f32 v[250:251], v[4:5], v[238:239] op_sel:[1,1] op_sel_hi:[0,1]
	v_pk_fma_f32 v[4:5], v[4:5], v[238:239], v[250:251] op_sel:[0,0,0] op_sel_hi:[1,0,1] neg_hi:[0,0,1]
	v_pk_mul_f32 v[250:251], v[2:3], v[236:237] op_sel:[1,1] op_sel_hi:[0,1]
	v_pk_fma_f32 v[2:3], v[2:3], v[236:237], v[250:251] op_sel:[0,0,0] op_sel_hi:[1,0,1] neg_hi:[0,0,1]
	v_pk_mul_f32 v[250:251], v[6:7], v[240:241] op_sel:[1,1] op_sel_hi:[0,1]
	v_pk_fma_f32 v[6:7], v[6:7], v[240:241], v[250:251] op_sel:[0,0,0] op_sel_hi:[1,0,1] neg_hi:[0,0,1]
	v_pk_add_f32 v[242:243], v[0:1], v[4:5]
	v_pk_add_f32 v[244:245], v[0:1], v[4:5] neg_lo:[0,1] neg_hi:[0,1]
	v_pk_add_f32 v[246:247], v[2:3], v[6:7]
	v_pk_add_f32 v[248:249], v[2:3], v[6:7] neg_lo:[0,1] neg_hi:[0,1]
	v_pk_add_f32 v[0:1], v[242:243], v[246:247]
	v_pk_add_f32 v[2:3], v[244:245], v[248:249] op_sel:[0,1] op_sel_hi:[1,0] neg_lo:[0,1]
	v_pk_add_f32 v[4:5], v[242:243], v[246:247] neg_lo:[0,1] neg_hi:[0,1]
	v_pk_add_f32 v[6:7], v[244:245], v[248:249] op_sel:[0,1] op_sel_hi:[1,0] neg_hi:[0,1]
	s_waitcnt lgkmcnt(8)
	v_pk_mul_f32 v[250:251], v[12:13], v[238:239] op_sel:[1,1] op_sel_hi:[0,1]
	v_pk_fma_f32 v[12:13], v[12:13], v[238:239], v[250:251] op_sel:[0,0,0] op_sel_hi:[1,0,1] neg_hi:[0,0,1]
	v_pk_mul_f32 v[250:251], v[10:11], v[236:237] op_sel:[1,1] op_sel_hi:[0,1]
	v_pk_fma_f32 v[10:11], v[10:11], v[236:237], v[250:251] op_sel:[0,0,0] op_sel_hi:[1,0,1] neg_hi:[0,0,1]
	v_pk_mul_f32 v[250:251], v[14:15], v[240:241] op_sel:[1,1] op_sel_hi:[0,1]
	v_pk_fma_f32 v[14:15], v[14:15], v[240:241], v[250:251] op_sel:[0,0,0] op_sel_hi:[1,0,1] neg_hi:[0,0,1]
	v_pk_add_f32 v[242:243], v[8:9], v[12:13]
	v_pk_add_f32 v[244:245], v[8:9], v[12:13] neg_lo:[0,1] neg_hi:[0,1]
	v_pk_add_f32 v[246:247], v[10:11], v[14:15]
	v_pk_add_f32 v[248:249], v[10:11], v[14:15] neg_lo:[0,1] neg_hi:[0,1]
	v_pk_add_f32 v[8:9], v[242:243], v[246:247]
	v_pk_add_f32 v[10:11], v[244:245], v[248:249] op_sel:[0,1] op_sel_hi:[1,0] neg_lo:[0,1]
	v_pk_add_f32 v[12:13], v[242:243], v[246:247] neg_lo:[0,1] neg_hi:[0,1]
	v_pk_add_f32 v[14:15], v[244:245], v[248:249] op_sel:[0,1] op_sel_hi:[1,0] neg_hi:[0,1]
	s_waitcnt lgkmcnt(4)
	v_pk_mul_f32 v[250:251], v[20:21], v[238:239] op_sel:[1,1] op_sel_hi:[0,1]
	v_pk_fma_f32 v[20:21], v[20:21], v[238:239], v[250:251] op_sel:[0,0,0] op_sel_hi:[1,0,1] neg_hi:[0,0,1]
	v_pk_mul_f32 v[250:251], v[18:19], v[236:237] op_sel:[1,1] op_sel_hi:[0,1]
	v_pk_fma_f32 v[18:19], v[18:19], v[236:237], v[250:251] op_sel:[0,0,0] op_sel_hi:[1,0,1] neg_hi:[0,0,1]
	v_pk_mul_f32 v[250:251], v[22:23], v[240:241] op_sel:[1,1] op_sel_hi:[0,1]
	v_pk_fma_f32 v[22:23], v[22:23], v[240:241], v[250:251] op_sel:[0,0,0] op_sel_hi:[1,0,1] neg_hi:[0,0,1]
	v_pk_add_f32 v[242:243], v[16:17], v[20:21]
	v_pk_add_f32 v[244:245], v[16:17], v[20:21] neg_lo:[0,1] neg_hi:[0,1]
	v_pk_add_f32 v[246:247], v[18:19], v[22:23]
	v_pk_add_f32 v[248:249], v[18:19], v[22:23] neg_lo:[0,1] neg_hi:[0,1]
	v_pk_add_f32 v[16:17], v[242:243], v[246:247]
	v_pk_add_f32 v[18:19], v[244:245], v[248:249] op_sel:[0,1] op_sel_hi:[1,0] neg_lo:[0,1]
	v_pk_add_f32 v[20:21], v[242:243], v[246:247] neg_lo:[0,1] neg_hi:[0,1]
	v_pk_add_f32 v[22:23], v[244:245], v[248:249] op_sel:[0,1] op_sel_hi:[1,0] neg_hi:[0,1]
	s_waitcnt lgkmcnt(0)
	v_pk_mul_f32 v[250:251], v[28:29], v[238:239] op_sel:[1,1] op_sel_hi:[0,1]
	v_pk_fma_f32 v[28:29], v[28:29], v[238:239], v[250:251] op_sel:[0,0,0] op_sel_hi:[1,0,1] neg_hi:[0,0,1]
	v_pk_mul_f32 v[250:251], v[26:27], v[236:237] op_sel:[1,1] op_sel_hi:[0,1]
	v_pk_fma_f32 v[26:27], v[26:27], v[236:237], v[250:251] op_sel:[0,0,0] op_sel_hi:[1,0,1] neg_hi:[0,0,1]
	v_pk_mul_f32 v[250:251], v[30:31], v[240:241] op_sel:[1,1] op_sel_hi:[0,1]
	v_pk_fma_f32 v[30:31], v[30:31], v[240:241], v[250:251] op_sel:[0,0,0] op_sel_hi:[1,0,1] neg_hi:[0,0,1]
	v_pk_add_f32 v[242:243], v[24:25], v[28:29]
	v_pk_add_f32 v[244:245], v[24:25], v[28:29] neg_lo:[0,1] neg_hi:[0,1]
	v_pk_add_f32 v[246:247], v[26:27], v[30:31]
	v_pk_add_f32 v[248:249], v[26:27], v[30:31] neg_lo:[0,1] neg_hi:[0,1]
	v_pk_add_f32 v[24:25], v[242:243], v[246:247]
	v_pk_add_f32 v[26:27], v[244:245], v[248:249] op_sel:[0,1] op_sel_hi:[1,0] neg_lo:[0,1]
	v_pk_add_f32 v[28:29], v[242:243], v[246:247] neg_lo:[0,1] neg_hi:[0,1]
	v_pk_add_f32 v[30:31], v[244:245], v[248:249] op_sel:[0,1] op_sel_hi:[1,0] neg_hi:[0,1]
	v_pk_mul_f32 v[250:251], v[16:17], v[82:83] op_sel:[1,1] op_sel_hi:[0,1]
	v_pk_fma_f32 v[16:17], v[16:17], v[82:83], v[250:251] op_sel:[0,0,0] op_sel_hi:[1,0,1] neg_hi:[0,0,1]
	v_pk_mul_f32 v[250:251], v[8:9], v[80:81] op_sel:[1,1] op_sel_hi:[0,1]
	v_pk_fma_f32 v[8:9], v[8:9], v[80:81], v[250:251] op_sel:[0,0,0] op_sel_hi:[1,0,1] neg_hi:[0,0,1]
	v_pk_mul_f32 v[250:251], v[24:25], v[84:85] op_sel:[1,1] op_sel_hi:[0,1]
	v_pk_fma_f32 v[24:25], v[24:25], v[84:85], v[250:251] op_sel:[0,0,0] op_sel_hi:[1,0,1] neg_hi:[0,0,1]
	v_pk_add_f32 v[242:243], v[0:1], v[16:17]
	v_pk_add_f32 v[244:245], v[0:1], v[16:17] neg_lo:[0,1] neg_hi:[0,1]
	v_pk_add_f32 v[246:247], v[8:9], v[24:25]
	v_pk_add_f32 v[248:249], v[8:9], v[24:25] neg_lo:[0,1] neg_hi:[0,1]
	v_pk_add_f32 v[0:1], v[242:243], v[246:247]
	ds_write_b64 v226, v[0:1] offset:0
	v_pk_add_f32 v[8:9], v[244:245], v[248:249] op_sel:[0,1] op_sel_hi:[1,0] neg_lo:[0,1]
	ds_write_b64 v226, v[8:9] offset:8192
	v_pk_add_f32 v[16:17], v[242:243], v[246:247] neg_lo:[0,1] neg_hi:[0,1]
	ds_write_b64 v226, v[16:17] offset:16384
	v_pk_add_f32 v[24:25], v[244:245], v[248:249] op_sel:[0,1] op_sel_hi:[1,0] neg_hi:[0,1]
	ds_write_b64 v226, v[24:25] offset:24576
	v_pk_mul_f32 v[250:251], v[18:19], v[224:225] op_sel:[1,1] op_sel_hi:[1,0] neg_lo:[0,0] neg_hi:[0,0]
; HD float2 cmul(float2 a, float2 b){ return make_float2(a.x*b.x - a.y*b.y, a.x*b.y + a.y*b.x); }
; HD float2 cmulc(float2 a, float2 b){ return make_float2(a.x*b.x + a.y*b.y, a.y*b.x - a.x*b.y); }
; template<bool INV, bool NOTW>
; HD void bf4c(float2* Z, int i0, int i1, int i2, int i3, float2 w1, float2 w2, float2 w3){
;   float2 a0=Z[i0], a1=Z[i1], a2=Z[i2], a3=Z[i3];
;   if (INV && !NOTW){ a1=cmulc(a1,w1); a2=cmulc(a2,w2); a3=cmulc(a3,w3); }
;   float2 s02=make_float2(a0.x+a2.x,a0.y+a2.y), d02=make_float2(a0.x-a2.x,a0.y-a2.y);
;   float2 s13=make_float2(a1.x+a3.x,a1.y+a3.y), d13=make_float2(a1.x-a3.x,a1.y-a3.y);
;   float2 y0=make_float2(s02.x+s13.x,s02.y+s13.y), y2=make_float2(s02.x-s13.x,s02.y-s13.y);
;   float2 ym=make_float2(d02.x+d13.y,d02.y-d13.x);
;   float2 yp=make_float2(d02.x-d13.y,d02.y+d13.x);
;   float2 y1, y3;
;   if (INV){ y1=yp; y3=ym; } else if (NOTW){ y1=ym; y3=yp; } else { y1=cmul(ym,w1); y2=cmul(y2,w2); y3=cmul(yp,w3); }
;   Z[i0]=y0; Z[i1]=y1; Z[i2]=y2; Z[i3]=y3;
; }
; __device__ __forceinline__ void fft_inv_tail(float2* Z, const float2* twA, const float2* twB, int tid){
;     ...
;   fft_pass<true,8>(Z,twA,twB,tid); fft_pass<true,10>(Z,twA,twB,tid);
	v_pk_fma_f32 v[18:19], v[18:19], v[224:225], v[250:251] op_sel:[0,0,0] op_sel_hi:[0,1,1] neg_lo:[0,0,1] neg_hi:[0,0,0]
	v_pk_mul_f32 v[250:251], v[18:19], v[82:83] op_sel:[1,1] op_sel_hi:[0,1]
	v_pk_fma_f32 v[18:19], v[18:19], v[82:83], v[250:251] op_sel:[0,0,0] op_sel_hi:[1,0,1] neg_hi:[0,0,1]
	v_pk_mul_f32 v[250:251], v[10:11], v[222:223] op_sel:[1,1] op_sel_hi:[1,0] neg_lo:[0,0] neg_hi:[0,0]
	v_pk_fma_f32 v[10:11], v[10:11], v[222:223], v[250:251] op_sel:[0,0,0] op_sel_hi:[0,1,1] neg_lo:[0,0,1] neg_hi:[0,0,0]
	v_pk_mul_f32 v[250:251], v[10:11], v[80:81] op_sel:[1,1] op_sel_hi:[0,1]
	v_pk_fma_f32 v[10:11], v[10:11], v[80:81], v[250:251] op_sel:[0,0,0] op_sel_hi:[1,0,1] neg_hi:[0,0,1]
	v_pk_mul_f32 v[250:251], v[26:27], v[222:223] op_sel:[1,0] op_sel_hi:[1,1] neg_lo:[0,0] neg_hi:[0,0]
	v_pk_fma_f32 v[26:27], v[26:27], v[222:223], v[250:251] op_sel:[0,1,0] op_sel_hi:[0,0,1] neg_lo:[0,0,1] neg_hi:[0,0,0]
	v_pk_mul_f32 v[250:251], v[26:27], v[84:85] op_sel:[1,1] op_sel_hi:[0,1]
	v_pk_fma_f32 v[26:27], v[26:27], v[84:85], v[250:251] op_sel:[0,0,0] op_sel_hi:[1,0,1] neg_hi:[0,0,1]
	v_pk_add_f32 v[242:243], v[2:3], v[18:19]
	v_pk_add_f32 v[244:245], v[2:3], v[18:19] neg_lo:[0,1] neg_hi:[0,1]
	v_pk_add_f32 v[246:247], v[10:11], v[26:27]
	v_pk_add_f32 v[248:249], v[10:11], v[26:27] neg_lo:[0,1] neg_hi:[0,1]
	v_pk_add_f32 v[2:3], v[242:243], v[246:247]
	ds_write_b64 v226, v[2:3] offset:2048
	v_pk_add_f32 v[10:11], v[244:245], v[248:249] op_sel:[0,1] op_sel_hi:[1,0] neg_lo:[0,1]
	ds_write_b64 v226, v[10:11] offset:10240
	v_pk_add_f32 v[18:19], v[242:243], v[246:247] neg_lo:[0,1] neg_hi:[0,1]
	ds_write_b64 v226, v[18:19] offset:18432
	v_pk_add_f32 v[26:27], v[244:245], v[248:249] op_sel:[0,1] op_sel_hi:[1,0] neg_hi:[0,1]
	ds_write_b64 v226, v[26:27] offset:26624
	v_pk_add_f32 v[20:21], v[20:21], 0 op_sel:[1,0] op_sel_hi:[0,0] neg_lo:[1,0]
	v_pk_mul_f32 v[250:251], v[20:21], v[82:83] op_sel:[1,1] op_sel_hi:[0,1]
	v_pk_fma_f32 v[20:21], v[20:21], v[82:83], v[250:251] op_sel:[0,0,0] op_sel_hi:[1,0,1] neg_hi:[0,0,1]
	v_pk_mul_f32 v[250:251], v[12:13], v[224:225] op_sel:[1,1] op_sel_hi:[1,0] neg_lo:[0,0] neg_hi:[0,0]
	v_pk_fma_f32 v[12:13], v[12:13], v[224:225], v[250:251] op_sel:[0,0,0] op_sel_hi:[0,1,1] neg_lo:[0,0,1] neg_hi:[0,0,0]
	v_pk_mul_f32 v[250:251], v[12:13], v[80:81] op_sel:[1,1] op_sel_hi:[0,1]
	v_pk_fma_f32 v[12:13], v[12:13], v[80:81], v[250:251] op_sel:[0,0,0] op_sel_hi:[1,0,1] neg_hi:[0,0,1]
	v_pk_mul_f32 v[250:251], v[28:29], v[224:225] op_sel:[1,1] op_sel_hi:[1,0] neg_lo:[0,0] neg_hi:[0,1]
	v_pk_fma_f32 v[28:29], v[28:29], v[224:225], v[250:251] op_sel:[0,0,0] op_sel_hi:[0,1,1] neg_lo:[0,1,1] neg_hi:[0,0,0]
	v_pk_mul_f32 v[250:251], v[28:29], v[84:85] op_sel:[1,1] op_sel_hi:[0,1]
	v_pk_fma_f32 v[28:29], v[28:29], v[84:85], v[250:251] op_sel:[0,0,0] op_sel_hi:[1,0,1] neg_hi:[0,0,1]
	v_pk_add_f32 v[242:243], v[4:5], v[20:21]
	v_pk_add_f32 v[244:245], v[4:5], v[20:21] neg_lo:[0,1] neg_hi:[0,1]
	v_pk_add_f32 v[246:247], v[12:13], v[28:29]
	v_pk_add_f32 v[248:249], v[12:13], v[28:29] neg_lo:[0,1] neg_hi:[0,1]
	v_pk_add_f32 v[4:5], v[242:243], v[246:247]
	ds_write_b64 v226, v[4:5] offset:4096
	v_pk_add_f32 v[12:13], v[244:245], v[248:249] op_sel:[0,1] op_sel_hi:[1,0] neg_lo:[0,1]
	ds_write_b64 v226, v[12:13] offset:12288
	v_pk_add_f32 v[20:21], v[242:243], v[246:247] neg_lo:[0,1] neg_hi:[0,1]
	ds_write_b64 v226, v[20:21] offset:20480
	v_pk_add_f32 v[28:29], v[244:245], v[248:249] op_sel:[0,1] op_sel_hi:[1,0] neg_hi:[0,1]
	ds_write_b64 v226, v[28:29] offset:28672
	v_pk_mul_f32 v[250:251], v[22:23], v[224:225] op_sel:[1,1] op_sel_hi:[1,0] neg_lo:[0,0] neg_hi:[0,1]
	v_pk_fma_f32 v[22:23], v[22:23], v[224:225], v[250:251] op_sel:[0,0,0] op_sel_hi:[0,1,1] neg_lo:[0,1,1] neg_hi:[0,0,0]
	v_pk_mul_f32 v[250:251], v[22:23], v[82:83] op_sel:[1,1] op_sel_hi:[0,1]
	v_pk_fma_f32 v[22:23], v[22:23], v[82:83], v[250:251] op_sel:[0,0,0] op_sel_hi:[1,0,1] neg_hi:[0,0,1]
	v_pk_mul_f32 v[250:251], v[14:15], v[222:223] op_sel:[1,0] op_sel_hi:[1,1] neg_lo:[0,0] neg_hi:[0,0]
	v_pk_fma_f32 v[14:15], v[14:15], v[222:223], v[250:251] op_sel:[0,1,0] op_sel_hi:[0,0,1] neg_lo:[0,0,1] neg_hi:[0,0,0]
	v_pk_mul_f32 v[250:251], v[14:15], v[80:81] op_sel:[1,1] op_sel_hi:[0,1]
	v_pk_fma_f32 v[14:15], v[14:15], v[80:81], v[250:251] op_sel:[0,0,0] op_sel_hi:[1,0,1] neg_hi:[0,0,1]
	v_pk_mul_f32 v[250:251], v[30:31], v[222:223] op_sel:[1,1] op_sel_hi:[1,0] neg_lo:[0,1] neg_hi:[0,1]
	v_pk_fma_f32 v[30:31], v[30:31], v[222:223], v[250:251] op_sel:[0,0,0] op_sel_hi:[0,1,1] neg_lo:[0,1,1] neg_hi:[0,1,0]
	v_pk_mul_f32 v[250:251], v[30:31], v[84:85] op_sel:[1,1] op_sel_hi:[0,1]
	v_pk_fma_f32 v[30:31], v[30:31], v[84:85], v[250:251] op_sel:[0,0,0] op_sel_hi:[1,0,1] neg_hi:[0,0,1]
	v_pk_add_f32 v[242:243], v[6:7], v[22:23]
	v_pk_add_f32 v[244:245], v[6:7], v[22:23] neg_lo:[0,1] neg_hi:[0,1]
	v_pk_add_f32 v[246:247], v[14:15], v[30:31]
	v_pk_add_f32 v[248:249], v[14:15], v[30:31] neg_lo:[0,1] neg_hi:[0,1]
	v_pk_add_f32 v[6:7], v[242:243], v[246:247]
	ds_write_b64 v226, v[6:7] offset:6144
	v_pk_add_f32 v[14:15], v[244:245], v[248:249] op_sel:[0,1] op_sel_hi:[1,0] neg_lo:[0,1]
	ds_write_b64 v226, v[14:15] offset:14336
	v_pk_add_f32 v[22:23], v[242:243], v[246:247] neg_lo:[0,1] neg_hi:[0,1]
	ds_write_b64 v226, v[22:23] offset:22528
	v_pk_add_f32 v[30:31], v[244:245], v[248:249] op_sel:[0,1] op_sel_hi:[1,0] neg_hi:[0,1]
	ds_write_b64 v226, v[30:31] offset:30720
	ds_read_b64 v[0:1], v227 offset:0
	ds_read_b64 v[2:3], v227 offset:2048
	ds_read_b64 v[4:5], v227 offset:4096
	ds_read_b64 v[6:7], v227 offset:6144
	ds_read_b64 v[8:9], v227 offset:8192
	ds_read_b64 v[10:11], v227 offset:10240
	ds_read_b64 v[12:13], v227 offset:12288
	ds_read_b64 v[14:15], v227 offset:14336
	ds_read_b64 v[16:17], v227 offset:16384
	ds_read_b64 v[18:19], v227 offset:18432
	ds_read_b64 v[20:21], v227 offset:20480
	ds_read_b64 v[22:23], v227 offset:22528
	ds_read_b64 v[24:25], v227 offset:24576
	ds_read_b64 v[26:27], v227 offset:26624
	ds_read_b64 v[28:29], v227 offset:28672
	ds_read_b64 v[30:31], v227 offset:30720
	s_waitcnt lgkmcnt(12)
; HD float2 cmul(float2 a, float2 b){ return make_float2(a.x*b.x - a.y*b.y, a.x*b.y + a.y*b.x); }
; HD float2 cmulc(float2 a, float2 b){ return make_float2(a.x*b.x + a.y*b.y, a.y*b.x - a.x*b.y); }
; template<bool INV, bool NOTW>
; HD void bf4c(float2* Z, int i0, int i1, int i2, int i3, float2 w1, float2 w2, float2 w3){
;   float2 a0=Z[i0], a1=Z[i1], a2=Z[i2], a3=Z[i3];
;   if (INV && !NOTW){ a1=cmulc(a1,w1); a2=cmulc(a2,w2); a3=cmulc(a3,w3); }
;   float2 s02=make_float2(a0.x+a2.x,a0.y+a2.y), d02=make_float2(a0.x-a2.x,a0.y-a2.y);
;   float2 s13=make_float2(a1.x+a3.x,a1.y+a3.y), d13=make_float2(a1.x-a3.x,a1.y-a3.y);
;   float2 y0=make_float2(s02.x+s13.x,s02.y+s13.y), y2=make_float2(s02.x-s13.x,s02.y-s13.y);
;   float2 ym=make_float2(d02.x+d13.y,d02.y-d13.x);
;   float2 yp=make_float2(d02.x-d13.y,d02.y+d13.x);
;   float2 y1, y3;
;   if (INV){ y1=yp; y3=ym; } else if (NOTW){ y1=ym; y3=yp; } else { y1=cmul(ym,w1); y2=cmul(y2,w2); y3=cmul(yp,w3); }
;   Z[i0]=y0; Z[i1]=y1; Z[i2]=y2; Z[i3]=y3;
; }
; __device__ __forceinline__ void fft_inv_tail(float2* Z, const float2* twA, const float2* twB, int tid){
;     ...
;   fft_pass<true,8>(Z,twA,twB,tid); fft_pass<true,10>(Z,twA,twB,tid);
	v_pk_mul_f32 v[250:251], v[4:5], v[238:239] op_sel:[1,1] op_sel_hi:[0,1]
	v_pk_fma_f32 v[4:5], v[4:5], v[238:239], v[250:251] op_sel:[0,0,0] op_sel_hi:[1,0,1] neg_hi:[0,0,1]
	v_pk_mul_f32 v[250:251], v[2:3], v[236:237] op_sel:[1,1] op_sel_hi:[0,1]
	v_pk_fma_f32 v[2:3], v[2:3], v[236:237], v[250:251] op_sel:[0,0,0] op_sel_hi:[1,0,1] neg_hi:[0,0,1]
	v_pk_mul_f32 v[250:251], v[6:7], v[240:241] op_sel:[1,1] op_sel_hi:[0,1]
	v_pk_fma_f32 v[6:7], v[6:7], v[240:241], v[250:251] op_sel:[0,0,0] op_sel_hi:[1,0,1] neg_hi:[0,0,1]
	v_pk_add_f32 v[242:243], v[0:1], v[4:5]
	v_pk_add_f32 v[244:245], v[0:1], v[4:5] neg_lo:[0,1] neg_hi:[0,1]
	v_pk_add_f32 v[246:247], v[2:3], v[6:7]
	v_pk_add_f32 v[248:249], v[2:3], v[6:7] neg_lo:[0,1] neg_hi:[0,1]
	v_pk_add_f32 v[0:1], v[242:243], v[246:247]
	v_pk_add_f32 v[2:3], v[244:245], v[248:249] op_sel:[0,1] op_sel_hi:[1,0] neg_lo:[0,1]
	v_pk_add_f32 v[4:5], v[242:243], v[246:247] neg_lo:[0,1] neg_hi:[0,1]
	v_pk_add_f32 v[6:7], v[244:245], v[248:249] op_sel:[0,1] op_sel_hi:[1,0] neg_hi:[0,1]
	s_waitcnt lgkmcnt(8)
	v_pk_mul_f32 v[250:251], v[12:13], v[238:239] op_sel:[1,1] op_sel_hi:[0,1]
	v_pk_fma_f32 v[12:13], v[12:13], v[238:239], v[250:251] op_sel:[0,0,0] op_sel_hi:[1,0,1] neg_hi:[0,0,1]
	v_pk_mul_f32 v[250:251], v[10:11], v[236:237] op_sel:[1,1] op_sel_hi:[0,1]
	v_pk_fma_f32 v[10:11], v[10:11], v[236:237], v[250:251] op_sel:[0,0,0] op_sel_hi:[1,0,1] neg_hi:[0,0,1]
	v_pk_mul_f32 v[250:251], v[14:15], v[240:241] op_sel:[1,1] op_sel_hi:[0,1]
	v_pk_fma_f32 v[14:15], v[14:15], v[240:241], v[250:251] op_sel:[0,0,0] op_sel_hi:[1,0,1] neg_hi:[0,0,1]
	v_pk_add_f32 v[242:243], v[8:9], v[12:13]
	v_pk_add_f32 v[244:245], v[8:9], v[12:13] neg_lo:[0,1] neg_hi:[0,1]
	v_pk_add_f32 v[246:247], v[10:11], v[14:15]
	v_pk_add_f32 v[248:249], v[10:11], v[14:15] neg_lo:[0,1] neg_hi:[0,1]
	v_pk_add_f32 v[8:9], v[242:243], v[246:247]
	v_pk_add_f32 v[10:11], v[244:245], v[248:249] op_sel:[0,1] op_sel_hi:[1,0] neg_lo:[0,1]
	v_pk_add_f32 v[12:13], v[242:243], v[246:247] neg_lo:[0,1] neg_hi:[0,1]
	v_pk_add_f32 v[14:15], v[244:245], v[248:249] op_sel:[0,1] op_sel_hi:[1,0] neg_hi:[0,1]
	s_waitcnt lgkmcnt(4)
	v_pk_mul_f32 v[250:251], v[20:21], v[238:239] op_sel:[1,1] op_sel_hi:[0,1]
	v_pk_fma_f32 v[20:21], v[20:21], v[238:239], v[250:251] op_sel:[0,0,0] op_sel_hi:[1,0,1] neg_hi:[0,0,1]
	v_pk_mul_f32 v[250:251], v[18:19], v[236:237] op_sel:[1,1] op_sel_hi:[0,1]
	v_pk_fma_f32 v[18:19], v[18:19], v[236:237], v[250:251] op_sel:[0,0,0] op_sel_hi:[1,0,1] neg_hi:[0,0,1]
	v_pk_mul_f32 v[250:251], v[22:23], v[240:241] op_sel:[1,1] op_sel_hi:[0,1]
	v_pk_fma_f32 v[22:23], v[22:23], v[240:241], v[250:251] op_sel:[0,0,0] op_sel_hi:[1,0,1] neg_hi:[0,0,1]
	v_pk_add_f32 v[242:243], v[16:17], v[20:21]
	v_pk_add_f32 v[244:245], v[16:17], v[20:21] neg_lo:[0,1] neg_hi:[0,1]
	v_pk_add_f32 v[246:247], v[18:19], v[22:23]
	v_pk_add_f32 v[248:249], v[18:19], v[22:23] neg_lo:[0,1] neg_hi:[0,1]
	v_pk_add_f32 v[16:17], v[242:243], v[246:247]
	v_pk_add_f32 v[18:19], v[244:245], v[248:249] op_sel:[0,1] op_sel_hi:[1,0] neg_lo:[0,1]
	v_pk_add_f32 v[20:21], v[242:243], v[246:247] neg_lo:[0,1] neg_hi:[0,1]
	v_pk_add_f32 v[22:23], v[244:245], v[248:249] op_sel:[0,1] op_sel_hi:[1,0] neg_hi:[0,1]
	s_waitcnt lgkmcnt(0)
	v_pk_mul_f32 v[250:251], v[28:29], v[238:239] op_sel:[1,1] op_sel_hi:[0,1]
	v_pk_fma_f32 v[28:29], v[28:29], v[238:239], v[250:251] op_sel:[0,0,0] op_sel_hi:[1,0,1] neg_hi:[0,0,1]
	v_pk_mul_f32 v[250:251], v[26:27], v[236:237] op_sel:[1,1] op_sel_hi:[0,1]
	v_pk_fma_f32 v[26:27], v[26:27], v[236:237], v[250:251] op_sel:[0,0,0] op_sel_hi:[1,0,1] neg_hi:[0,0,1]
	v_pk_mul_f32 v[250:251], v[30:31], v[240:241] op_sel:[1,1] op_sel_hi:[0,1]
	v_pk_fma_f32 v[30:31], v[30:31], v[240:241], v[250:251] op_sel:[0,0,0] op_sel_hi:[1,0,1] neg_hi:[0,0,1]
	v_pk_add_f32 v[242:243], v[24:25], v[28:29]
	v_pk_add_f32 v[244:245], v[24:25], v[28:29] neg_lo:[0,1] neg_hi:[0,1]
	v_pk_add_f32 v[246:247], v[26:27], v[30:31]
	v_pk_add_f32 v[248:249], v[26:27], v[30:31] neg_lo:[0,1] neg_hi:[0,1]
	v_pk_add_f32 v[24:25], v[242:243], v[246:247]
	v_pk_add_f32 v[26:27], v[244:245], v[248:249] op_sel:[0,1] op_sel_hi:[1,0] neg_lo:[0,1]
	v_pk_add_f32 v[28:29], v[242:243], v[246:247] neg_lo:[0,1] neg_hi:[0,1]
	v_pk_add_f32 v[30:31], v[244:245], v[248:249] op_sel:[0,1] op_sel_hi:[1,0] neg_hi:[0,1]
	v_pk_mul_f32 v[250:251], v[16:17], v[82:83] op_sel:[1,1] op_sel_hi:[0,1]
	v_pk_fma_f32 v[16:17], v[16:17], v[82:83], v[250:251] op_sel:[0,0,0] op_sel_hi:[1,0,1] neg_hi:[0,0,1]
	v_pk_mul_f32 v[250:251], v[8:9], v[80:81] op_sel:[1,1] op_sel_hi:[0,1]
	v_pk_fma_f32 v[8:9], v[8:9], v[80:81], v[250:251] op_sel:[0,0,0] op_sel_hi:[1,0,1] neg_hi:[0,0,1]
	v_pk_mul_f32 v[250:251], v[24:25], v[84:85] op_sel:[1,1] op_sel_hi:[0,1]
	v_pk_fma_f32 v[24:25], v[24:25], v[84:85], v[250:251] op_sel:[0,0,0] op_sel_hi:[1,0,1] neg_hi:[0,0,1]
	v_pk_add_f32 v[242:243], v[0:1], v[16:17]
	v_pk_add_f32 v[244:245], v[0:1], v[16:17] neg_lo:[0,1] neg_hi:[0,1]
	v_pk_add_f32 v[246:247], v[8:9], v[24:25]
	v_pk_add_f32 v[248:249], v[8:9], v[24:25] neg_lo:[0,1] neg_hi:[0,1]
	v_pk_add_f32 v[0:1], v[242:243], v[246:247]
	ds_write_b64 v227, v[0:1] offset:0
	v_pk_add_f32 v[8:9], v[244:245], v[248:249] op_sel:[0,1] op_sel_hi:[1,0] neg_lo:[0,1]
	ds_write_b64 v227, v[8:9] offset:8192
	v_pk_add_f32 v[16:17], v[242:243], v[246:247] neg_lo:[0,1] neg_hi:[0,1]
	ds_write_b64 v227, v[16:17] offset:16384
	v_pk_add_f32 v[24:25], v[244:245], v[248:249] op_sel:[0,1] op_sel_hi:[1,0] neg_hi:[0,1]
	ds_write_b64 v227, v[24:25] offset:24576
	v_pk_mul_f32 v[250:251], v[18:19], v[224:225] op_sel:[1,1] op_sel_hi:[1,0] neg_lo:[0,0] neg_hi:[0,0]
; HD float2 cmul(float2 a, float2 b){ return make_float2(a.x*b.x - a.y*b.y, a.x*b.y + a.y*b.x); }
; HD float2 cmulc(float2 a, float2 b){ return make_float2(a.x*b.x + a.y*b.y, a.y*b.x - a.x*b.y); }
; template<bool INV, bool NOTW>
; HD void bf4c(float2* Z, int i0, int i1, int i2, int i3, float2 w1, float2 w2, float2 w3){
;   float2 a0=Z[i0], a1=Z[i1], a2=Z[i2], a3=Z[i3];
;   if (INV && !NOTW){ a1=cmulc(a1,w1); a2=cmulc(a2,w2); a3=cmulc(a3,w3); }
;   float2 s02=make_float2(a0.x+a2.x,a0.y+a2.y), d02=make_float2(a0.x-a2.x,a0.y-a2.y);
;   float2 s13=make_float2(a1.x+a3.x,a1.y+a3.y), d13=make_float2(a1.x-a3.x,a1.y-a3.y);
;   float2 y0=make_float2(s02.x+s13.x,s02.y+s13.y), y2=make_float2(s02.x-s13.x,s02.y-s13.y);
;   float2 ym=make_float2(d02.x+d13.y,d02.y-d13.x);
;   float2 yp=make_float2(d02.x-d13.y,d02.y+d13.x);
;   float2 y1, y3;
;   if (INV){ y1=yp; y3=ym; } else if (NOTW){ y1=ym; y3=yp; } else { y1=cmul(ym,w1); y2=cmul(y2,w2); y3=cmul(yp,w3); }
;   Z[i0]=y0; Z[i1]=y1; Z[i2]=y2; Z[i3]=y3;
; }
; __device__ __forceinline__ void fft_inv_tail(float2* Z, const float2* twA, const float2* twB, int tid){
;     ...
;   fft_pass<true,8>(Z,twA,twB,tid); fft_pass<true,10>(Z,twA,twB,tid);
; __device__ __forceinline__ void phase_hyena(KP kp_, int hf){ asm volatile("" : "+s"(kp_)); const Params p=load_params(kp_);
;     ...
;         if (st==1){ int tq=tid; asm volatile("" : "+v"(tq));
;           _Pragma("unroll 4") for (int i=0;i<8;++i){ int tb=tq+512*i; float2 xr[2]; inv12_half(Z,twA,twB,tb,xr[0],xr[1]);
;             _Pragma("unroll") for (int hh=0;hh<2;++hh){ int t=tb+hh*4096;
;               float u0=hconv3(rv,t,wv0,wv1,wv2,bv_), u1=hconv3(rv+8192,t,wv0,wv1,wv2,bv_);
;               float x0=hconv3(r1,t,wa0,wa1,wa2,ba_), x1=hconv3(r1+8192,t,wa0,wa1,wa2,ba_);
;               float2 y=xr[hh]; y.x*=(1.f/16384.f); y.y*=(1.f/16384.f);
;               Zs[t]=make_float2(x0*(y.x+u0*bias0), x1*(y.y+u1*bias0)); } }
	v_pk_fma_f32 v[18:19], v[18:19], v[224:225], v[250:251] op_sel:[0,0,0] op_sel_hi:[0,1,1] neg_lo:[0,0,1] neg_hi:[0,0,0]
	v_pk_mul_f32 v[250:251], v[18:19], v[82:83] op_sel:[1,1] op_sel_hi:[0,1]
	v_pk_fma_f32 v[18:19], v[18:19], v[82:83], v[250:251] op_sel:[0,0,0] op_sel_hi:[1,0,1] neg_hi:[0,0,1]
	v_pk_mul_f32 v[250:251], v[10:11], v[222:223] op_sel:[1,1] op_sel_hi:[1,0] neg_lo:[0,0] neg_hi:[0,0]
	v_pk_fma_f32 v[10:11], v[10:11], v[222:223], v[250:251] op_sel:[0,0,0] op_sel_hi:[0,1,1] neg_lo:[0,0,1] neg_hi:[0,0,0]
	v_pk_mul_f32 v[250:251], v[10:11], v[80:81] op_sel:[1,1] op_sel_hi:[0,1]
	v_pk_fma_f32 v[10:11], v[10:11], v[80:81], v[250:251] op_sel:[0,0,0] op_sel_hi:[1,0,1] neg_hi:[0,0,1]
	v_pk_mul_f32 v[250:251], v[26:27], v[222:223] op_sel:[1,0] op_sel_hi:[1,1] neg_lo:[0,0] neg_hi:[0,0]
	v_pk_fma_f32 v[26:27], v[26:27], v[222:223], v[250:251] op_sel:[0,1,0] op_sel_hi:[0,0,1] neg_lo:[0,0,1] neg_hi:[0,0,0]
	v_pk_mul_f32 v[250:251], v[26:27], v[84:85] op_sel:[1,1] op_sel_hi:[0,1]
	v_pk_fma_f32 v[26:27], v[26:27], v[84:85], v[250:251] op_sel:[0,0,0] op_sel_hi:[1,0,1] neg_hi:[0,0,1]
	v_pk_add_f32 v[242:243], v[2:3], v[18:19]
	v_pk_add_f32 v[244:245], v[2:3], v[18:19] neg_lo:[0,1] neg_hi:[0,1]
	v_pk_add_f32 v[246:247], v[10:11], v[26:27]
	v_pk_add_f32 v[248:249], v[10:11], v[26:27] neg_lo:[0,1] neg_hi:[0,1]
	v_pk_add_f32 v[2:3], v[242:243], v[246:247]
	ds_write_b64 v227, v[2:3] offset:2048
	v_pk_add_f32 v[10:11], v[244:245], v[248:249] op_sel:[0,1] op_sel_hi:[1,0] neg_lo:[0,1]
	ds_write_b64 v227, v[10:11] offset:10240
	v_pk_add_f32 v[18:19], v[242:243], v[246:247] neg_lo:[0,1] neg_hi:[0,1]
	ds_write_b64 v227, v[18:19] offset:18432
	v_pk_add_f32 v[26:27], v[244:245], v[248:249] op_sel:[0,1] op_sel_hi:[1,0] neg_hi:[0,1]
	ds_write_b64 v227, v[26:27] offset:26624
	v_pk_add_f32 v[20:21], v[20:21], 0 op_sel:[1,0] op_sel_hi:[0,0] neg_lo:[1,0]
	v_pk_mul_f32 v[250:251], v[20:21], v[82:83] op_sel:[1,1] op_sel_hi:[0,1]
	v_pk_fma_f32 v[20:21], v[20:21], v[82:83], v[250:251] op_sel:[0,0,0] op_sel_hi:[1,0,1] neg_hi:[0,0,1]
	v_pk_mul_f32 v[250:251], v[12:13], v[224:225] op_sel:[1,1] op_sel_hi:[1,0] neg_lo:[0,0] neg_hi:[0,0]
	v_pk_fma_f32 v[12:13], v[12:13], v[224:225], v[250:251] op_sel:[0,0,0] op_sel_hi:[0,1,1] neg_lo:[0,0,1] neg_hi:[0,0,0]
	v_pk_mul_f32 v[250:251], v[12:13], v[80:81] op_sel:[1,1] op_sel_hi:[0,1]
	v_pk_fma_f32 v[12:13], v[12:13], v[80:81], v[250:251] op_sel:[0,0,0] op_sel_hi:[1,0,1] neg_hi:[0,0,1]
	v_pk_mul_f32 v[250:251], v[28:29], v[224:225] op_sel:[1,1] op_sel_hi:[1,0] neg_lo:[0,0] neg_hi:[0,1]
	v_pk_fma_f32 v[28:29], v[28:29], v[224:225], v[250:251] op_sel:[0,0,0] op_sel_hi:[0,1,1] neg_lo:[0,1,1] neg_hi:[0,0,0]
	v_pk_mul_f32 v[250:251], v[28:29], v[84:85] op_sel:[1,1] op_sel_hi:[0,1]
	v_pk_fma_f32 v[28:29], v[28:29], v[84:85], v[250:251] op_sel:[0,0,0] op_sel_hi:[1,0,1] neg_hi:[0,0,1]
	v_pk_add_f32 v[242:243], v[4:5], v[20:21]
	v_pk_add_f32 v[244:245], v[4:5], v[20:21] neg_lo:[0,1] neg_hi:[0,1]
	v_pk_add_f32 v[246:247], v[12:13], v[28:29]
	v_pk_add_f32 v[248:249], v[12:13], v[28:29] neg_lo:[0,1] neg_hi:[0,1]
	v_pk_add_f32 v[4:5], v[242:243], v[246:247]
	ds_write_b64 v227, v[4:5] offset:4096
	v_pk_add_f32 v[12:13], v[244:245], v[248:249] op_sel:[0,1] op_sel_hi:[1,0] neg_lo:[0,1]
	ds_write_b64 v227, v[12:13] offset:12288
	v_pk_add_f32 v[20:21], v[242:243], v[246:247] neg_lo:[0,1] neg_hi:[0,1]
	ds_write_b64 v227, v[20:21] offset:20480
	v_pk_add_f32 v[28:29], v[244:245], v[248:249] op_sel:[0,1] op_sel_hi:[1,0] neg_hi:[0,1]
	ds_write_b64 v227, v[28:29] offset:28672
	v_pk_mul_f32 v[250:251], v[22:23], v[224:225] op_sel:[1,1] op_sel_hi:[1,0] neg_lo:[0,0] neg_hi:[0,1]
	v_pk_fma_f32 v[22:23], v[22:23], v[224:225], v[250:251] op_sel:[0,0,0] op_sel_hi:[0,1,1] neg_lo:[0,1,1] neg_hi:[0,0,0]
	v_pk_mul_f32 v[250:251], v[22:23], v[82:83] op_sel:[1,1] op_sel_hi:[0,1]
	v_pk_fma_f32 v[22:23], v[22:23], v[82:83], v[250:251] op_sel:[0,0,0] op_sel_hi:[1,0,1] neg_hi:[0,0,1]
	v_pk_mul_f32 v[250:251], v[14:15], v[222:223] op_sel:[1,0] op_sel_hi:[1,1] neg_lo:[0,0] neg_hi:[0,0]
	v_pk_fma_f32 v[14:15], v[14:15], v[222:223], v[250:251] op_sel:[0,1,0] op_sel_hi:[0,0,1] neg_lo:[0,0,1] neg_hi:[0,0,0]
	v_pk_mul_f32 v[250:251], v[14:15], v[80:81] op_sel:[1,1] op_sel_hi:[0,1]
	v_pk_fma_f32 v[14:15], v[14:15], v[80:81], v[250:251] op_sel:[0,0,0] op_sel_hi:[1,0,1] neg_hi:[0,0,1]
	v_pk_mul_f32 v[250:251], v[30:31], v[222:223] op_sel:[1,1] op_sel_hi:[1,0] neg_lo:[0,1] neg_hi:[0,1]
	v_pk_fma_f32 v[30:31], v[30:31], v[222:223], v[250:251] op_sel:[0,0,0] op_sel_hi:[0,1,1] neg_lo:[0,1,1] neg_hi:[0,1,0]
	v_pk_mul_f32 v[250:251], v[30:31], v[84:85] op_sel:[1,1] op_sel_hi:[0,1]
	v_pk_fma_f32 v[30:31], v[30:31], v[84:85], v[250:251] op_sel:[0,0,0] op_sel_hi:[1,0,1] neg_hi:[0,0,1]
	v_pk_add_f32 v[242:243], v[6:7], v[22:23]
	v_pk_add_f32 v[244:245], v[6:7], v[22:23] neg_lo:[0,1] neg_hi:[0,1]
	v_pk_add_f32 v[246:247], v[14:15], v[30:31]
	v_pk_add_f32 v[248:249], v[14:15], v[30:31] neg_lo:[0,1] neg_hi:[0,1]
	v_pk_add_f32 v[6:7], v[242:243], v[246:247]
	ds_write_b64 v227, v[6:7] offset:6144
	v_pk_add_f32 v[14:15], v[244:245], v[248:249] op_sel:[0,1] op_sel_hi:[1,0] neg_lo:[0,1]
	ds_write_b64 v227, v[14:15] offset:14336
	v_pk_add_f32 v[22:23], v[242:243], v[246:247] neg_lo:[0,1] neg_hi:[0,1]
	ds_write_b64 v227, v[22:23] offset:22528
	v_pk_add_f32 v[30:31], v[244:245], v[248:249] op_sel:[0,1] op_sel_hi:[1,0] neg_hi:[0,1]
	ds_write_b64 v227, v[30:31] offset:30720
	s_waitcnt lgkmcnt(0)
	s_barrier
	s_mov_b64 s[12:13], -1
	s_and_b64 vcc, exec, s[50:51]
	s_cbranch_vccz .LBB0_1340
	v_mov_b32_e32 v0, v86
	s_mov_b64 s[50:51], 0
	v_and_b32_e32 v1, 63, v0
	v_lshl_add_u32 v30, v1, 3, s91
	v_ashrrev_i32_e32 v1, 31, v0
	v_lshlrev_b64 v[6:7], 1, v[0:1]
	v_lshl_add_u64 v[2:3], v[76:77], 0, v[6:7]
	v_lshl_add_u64 v[4:5], s[14:15], 0, v[6:7]
	v_lshl_add_u64 v[6:7], s[54:55], 0, v[6:7]
	v_lshl_add_u32 v31, v0, 3, 0
